# pool mixer: all weight-fragment/scale loads and the window-tap loads of later k-steps issued up front into fresh registers with counted vmcnt waits (was load-wait-mfma serial)
# speedup vs baseline: 1.0096x; 1.0096x over previous
.LBB0_584:
	s_cmp_gt_i32 s16, 1
	s_cbranch_scc0 .LBB0_588
	s_cmp_eq_u32 s16, 2
	s_mov_b64 s[4:5], -1
	s_cbranch_scc0 .LBB0_587
	v_mov_b32_e32 v0, v209
	s_lshl_b32 s6, s56, 1
	v_readfirstlane_b32 s0, v0
	s_ashr_i32 s0, s0, 2
	v_and_b32_e32 v53, 15, v0
	v_bfi_b32 v32, -16, s0, v0
	v_bfe_u32 v51, v0, 4, 2
	v_subrev_u32_e32 v0, s6, v32
	v_add_u32_e32 v48, s59, v0
	s_mov_b32 s0, 0x38e38e39
	v_mul_hi_i32 v0, v48, s0
	v_lshrrev_b32_e32 v2, 31, v0
	v_ashrrev_i32_e32 v0, 13, v0
	v_add_u32_e32 v0, v0, v2
	v_mul_i32_i24_e32 v0, 0x9000, v0
	v_sub_u32_e32 v0, v48, v0
	s_mov_b32 s0, 0x8000
	v_cmp_gt_i32_e32 vcc, s0, v0
	v_lshlrev_b32_e32 v46, 4, v51
	v_mov_b32_e32 v47, v1
	v_cndmask_b32_e32 v2, v220, v221, vcc
	v_and_b32_e32 v56, v2, v0
	v_cndmask_b32_e32 v55, v217, v210, vcc
	v_add_u32_e32 v2, -4, v56
	v_add_u32_e32 v3, 4, v56
	v_max_i32_e32 v0, 0, v2
	v_min_u32_e32 v3, v3, v55
	v_sub_u32_e32 v0, v3, v0
	v_cvt_f32_i32_e32 v0, v0
	v_add_u32_e32 v10, -2, v56
	v_add_u32_e32 v14, -1, v56
	v_cmp_lt_u32_e64 s[4:5], v14, v55
	v_div_scale_f32 v3, s[0:1], v0, v0, 1.0
	v_rcp_f32_e32 v4, v3
	v_readlane_b32 s0, v253, 62
	v_readlane_b32 s1, v253, 63
	v_cndmask_b32_e64 v14, v56, v14, s[4:5]
	v_fma_f32 v5, -v3, v4, 1.0
	v_fmac_f32_e32 v4, v5, v4
	v_div_scale_f32 v5, vcc, 1.0, v0, 1.0
	v_mul_f32_e32 v6, v5, v4
	v_fma_f32 v7, -v3, v6, v5
	v_fmac_f32_e32 v6, v7, v4
	v_fma_f32 v3, -v3, v6, v5
	v_div_fmas_f32 v3, v3, v4, v6
	v_cmp_lt_u32_e32 vcc, v2, v55
	v_add_u32_e32 v6, -3, v56
	v_lshl_add_u64 v[30:31], s[0:1], 0, v[46:47]
	v_cndmask_b32_e64 v52, 0, 1.0, vcc
	v_cndmask_b32_e32 v2, v56, v2, vcc
	v_cmp_lt_u32_e32 vcc, v6, v55
	v_add_u32_e32 v2, v32, v2
	v_cmp_lt_u32_e64 s[0:1], v10, v55
	v_cndmask_b32_e32 v6, v56, v6, vcc
	v_subrev_u32_e32 v2, s6, v2
	v_add_u32_e32 v6, v32, v6
	v_cndmask_b32_e64 v10, v56, v10, s[0:1]
	v_sub_u32_e32 v2, v2, v56
	v_subrev_u32_e32 v6, s6, v6
	v_add_u32_e32 v10, v32, v10
	v_add_u32_e32 v22, 1, v56
	v_add_u32_e32 v2, s59, v2
	v_sub_u32_e32 v6, v6, v56
	v_subrev_u32_e32 v10, s6, v10
	v_add_u32_e32 v14, v32, v14
	v_cmp_lt_u32_e64 s[8:9], v22, v55
	v_add_u32_e32 v26, 2, v56
	v_div_fixup_f32 v50, v3, v0, 1.0
	v_ashrrev_i32_e32 v3, 31, v2
	v_add_u32_e32 v6, s59, v6
	v_sub_u32_e32 v10, v10, v56
	v_subrev_u32_e32 v14, s6, v14
	v_cndmask_b32_e64 v22, v56, v22, s[8:9]
	v_cmp_lt_u32_e64 s[10:11], v26, v55
	v_add_u32_e32 v33, 3, v56
	v_lshlrev_b64 v[2:3], 10, v[2:3]
	v_ashrrev_i32_e32 v7, 31, v6
	v_add_u32_e32 v10, s59, v10
	v_sub_u32_e32 v14, v14, v56
	v_add_u32_e32 v22, v32, v22
	v_cndmask_b32_e64 v26, v56, v26, s[10:11]
	v_cmp_lt_u32_e64 s[12:13], v33, v55
	v_lshl_add_u64 v[74:75], v[30:31], 0, v[2:3]
	v_lshlrev_b64 v[6:7], 10, v[6:7]
	v_ashrrev_i32_e32 v11, 31, v10
	v_add_u32_e32 v14, s59, v14
	v_subrev_u32_e32 v22, s6, v22
	v_add_u32_e32 v26, v32, v26
	v_cndmask_b32_e64 v33, v56, v33, s[12:13]
	global_load_dwordx4 v[2:5], v[74:75], off offset:512
	v_lshl_add_u64 v[72:73], v[30:31], 0, v[6:7]
	v_lshlrev_b64 v[10:11], 10, v[10:11]
	v_ashrrev_i32_e32 v15, 31, v14
	v_sub_u32_e32 v22, v22, v56
	v_subrev_u32_e32 v26, s6, v26
	v_add_u32_e32 v32, v32, v33
	v_ashrrev_i32_e32 v49, 31, v48
	global_load_dwordx4 v[6:9], v[72:73], off offset:512
	v_lshl_add_u64 v[70:71], v[30:31], 0, v[10:11]
	v_lshlrev_b64 v[14:15], 10, v[14:15]
	v_add_u32_e32 v22, s59, v22
	v_sub_u32_e32 v26, v26, v56
	v_subrev_u32_e32 v32, s6, v32
	v_lshlrev_b64 v[18:19], 10, v[48:49]
	global_load_dwordx4 v[10:13], v[70:71], off offset:512
	v_lshl_add_u64 v[68:69], v[30:31], 0, v[14:15]
	v_ashrrev_i32_e32 v23, 31, v22
	v_add_u32_e32 v26, s59, v26
	v_sub_u32_e32 v32, v32, v56
	global_load_dwordx4 v[14:17], v[68:69], off offset:512
	v_lshl_add_u64 v[38:39], v[30:31], 0, v[18:19]
	v_lshlrev_b64 v[22:23], 10, v[22:23]
	v_ashrrev_i32_e32 v27, 31, v26
	v_add_u32_e32 v32, s59, v32
	global_load_dwordx4 v[18:21], v[38:39], off offset:512
	v_lshl_add_u64 v[40:41], v[30:31], 0, v[22:23]
	v_lshlrev_b64 v[26:27], 10, v[26:27]
	v_ashrrev_i32_e32 v33, 31, v32
	global_load_dwordx4 v[22:25], v[40:41], off offset:512
	v_lshl_add_u64 v[42:43], v[30:31], 0, v[26:27]
	v_lshlrev_b64 v[32:33], 10, v[32:33]
	global_load_dwordx4 v[26:29], v[42:43], off offset:512
	v_lshl_add_u64 v[44:45], v[30:31], 0, v[32:33]
	global_load_dwordx4 v[30:33], v[44:45], off offset:512
	global_load_dwordx4 v[92:95], v[74:75], off offset:576
	global_load_dwordx4 v[96:99], v[72:73], off offset:576
	global_load_dwordx4 v[100:103], v[70:71], off offset:576
	global_load_dwordx4 v[104:107], v[68:69], off offset:576
	global_load_dwordx4 v[108:111], v[38:39], off offset:576
	global_load_dwordx4 v[112:115], v[40:41], off offset:576
	global_load_dwordx4 v[116:119], v[42:43], off offset:576
	global_load_dwordx4 v[120:123], v[44:45], off offset:576
	global_load_dwordx4 v[124:127], v[74:75], off offset:640
	global_load_dwordx4 v[128:131], v[72:73], off offset:640
	global_load_dwordx4 v[132:135], v[70:71], off offset:640
	global_load_dwordx4 v[136:139], v[68:69], off offset:640
	global_load_dwordx4 v[140:143], v[38:39], off offset:640
	global_load_dwordx4 v[144:147], v[40:41], off offset:640
	global_load_dwordx4 v[148:151], v[42:43], off offset:640
	global_load_dwordx4 v[152:155], v[44:45], off offset:640
	global_load_dwordx4 v[156:159], v[74:75], off offset:704
	global_load_dwordx4 v[160:163], v[72:73], off offset:704
	global_load_dwordx4 v[164:167], v[70:71], off offset:704
	global_load_dwordx4 v[168:171], v[68:69], off offset:704
	global_load_dwordx4 v[172:175], v[38:39], off offset:704
	global_load_dwordx4 v[176:179], v[40:41], off offset:704
	global_load_dwordx4 v[180:183], v[42:43], off offset:704
	global_load_dwordx4 v[184:187], v[44:45], off offset:704
	v_cndmask_b32_e64 v54, 0, 1.0, vcc
	v_cndmask_b32_e64 v58, 0, 1.0, s[0:1]
	v_cndmask_b32_e64 v66, 0, 1.0, s[4:5]
	v_cmp_lt_u32_e32 vcc, v56, v55
	v_cndmask_b32_e64 v62, 0, 1.0, s[8:9]
	v_cndmask_b32_e64 v60, 0, 1.0, s[10:11]
	v_cndmask_b32_e64 v64, 0, 1.0, vcc
	v_cndmask_b32_e64 v56, 0, 1.0, s[12:13]
	s_mov_b64 s[0:1], 0x400
	v_lshlrev_b32_e32 v0, 3, v51
	s_mov_b64 s[4:5], 0
	s_waitcnt vmcnt(31)
	v_lshlrev_b32_e32 v34, 16, v2
	v_and_b32_e32 v35, 0xffff0000, v2
	v_lshlrev_b32_e32 v36, 16, v3
	v_and_b32_e32 v37, 0xffff0000, v3
	v_pk_fma_f32 v[34:35], v[52:53], v[34:35], 0 op_sel_hi:[0, 1, 0]
	v_lshlrev_b32_e32 v76, 16, v4
	v_and_b32_e32 v77, 0xffff0000, v4
	v_lshlrev_b32_e32 v78, 16, v5
	s_waitcnt vmcnt(30)
	v_lshlrev_b32_e32 v2, 16, v6
	v_and_b32_e32 v3, 0xffff0000, v6
	v_pk_fma_f32 v[2:3], v[54:55], v[2:3], v[34:35] op_sel_hi:[0, 1, 1]
	v_and_b32_e32 v79, 0xffff0000, v5
	v_lshlrev_b32_e32 v4, 16, v7
	v_and_b32_e32 v5, 0xffff0000, v7
	v_lshlrev_b32_e32 v6, 16, v8
	s_waitcnt vmcnt(29)
	v_lshlrev_b32_e32 v80, 16, v10
	v_and_b32_e32 v81, 0xffff0000, v10
	v_pk_fma_f32 v[2:3], v[58:59], v[80:81], v[2:3] op_sel_hi:[0, 1, 1]
	v_lshlrev_b32_e32 v10, 16, v11
	v_and_b32_e32 v11, 0xffff0000, v11
	s_waitcnt vmcnt(28)
	v_lshlrev_b32_e32 v34, 16, v14
	v_and_b32_e32 v35, 0xffff0000, v14
	v_pk_fma_f32 v[2:3], v[66:67], v[34:35], v[2:3] op_sel_hi:[0, 1, 1]
	v_and_b32_e32 v7, 0xffff0000, v8
	v_lshlrev_b32_e32 v82, 16, v12
	s_waitcnt vmcnt(27)
	v_lshlrev_b32_e32 v34, 16, v18
	v_and_b32_e32 v35, 0xffff0000, v18
	v_pk_fma_f32 v[2:3], v[64:65], v[34:35], v[2:3] op_sel_hi:[0, 1, 1]
	v_and_b32_e32 v83, 0xffff0000, v12
	s_waitcnt vmcnt(26)
	v_lshlrev_b32_e32 v80, 16, v22
	v_and_b32_e32 v81, 0xffff0000, v22
	v_pk_fma_f32 v[2:3], v[62:63], v[80:81], v[2:3] op_sel_hi:[0, 1, 1]
	s_waitcnt vmcnt(25)
	v_lshlrev_b32_e32 v80, 16, v26
	v_and_b32_e32 v81, 0xffff0000, v26
	v_pk_fma_f32 v[2:3], v[60:61], v[80:81], v[2:3] op_sel_hi:[0, 1, 1]
	s_waitcnt vmcnt(24)
	v_lshlrev_b32_e32 v80, 16, v30
	v_and_b32_e32 v81, 0xffff0000, v30
	v_pk_fma_f32 v[2:3], v[56:57], v[80:81], v[2:3] op_sel_hi:[0, 1, 1]
	v_pk_fma_f32 v[2:3], v[50:51], v[2:3], v[34:35] op_sel_hi:[0, 1, 1] neg_lo:[0, 0, 1] neg_hi:[0, 0, 1]
	v_pk_fma_f32 v[34:35], v[52:53], v[36:37], 0 op_sel_hi:[0, 1, 0]
	v_pk_fma_f32 v[4:5], v[54:55], v[4:5], v[34:35] op_sel_hi:[0, 1, 1]
	v_pk_fma_f32 v[4:5], v[58:59], v[10:11], v[4:5] op_sel_hi:[0, 1, 1]
	v_lshlrev_b32_e32 v10, 16, v15
	v_and_b32_e32 v11, 0xffff0000, v15
	v_pk_fma_f32 v[4:5], v[66:67], v[10:11], v[4:5] op_sel_hi:[0, 1, 1]
	v_lshlrev_b32_e32 v10, 16, v19
	v_and_b32_e32 v11, 0xffff0000, v19
	v_pk_fma_f32 v[4:5], v[64:65], v[10:11], v[4:5] op_sel_hi:[0, 1, 1]
	v_lshlrev_b32_e32 v14, 16, v23
	v_and_b32_e32 v15, 0xffff0000, v23
	v_pk_fma_f32 v[4:5], v[62:63], v[14:15], v[4:5] op_sel_hi:[0, 1, 1]
	v_lshlrev_b32_e32 v14, 16, v27
	v_and_b32_e32 v15, 0xffff0000, v27
	v_pk_fma_f32 v[4:5], v[60:61], v[14:15], v[4:5] op_sel_hi:[0, 1, 1]
	v_lshlrev_b32_e32 v14, 16, v31
	v_and_b32_e32 v15, 0xffff0000, v31
	v_pk_fma_f32 v[4:5], v[56:57], v[14:15], v[4:5] op_sel_hi:[0, 1, 1]
	v_pk_fma_f32 v[4:5], v[50:51], v[4:5], v[10:11] op_sel_hi:[0, 1, 1] neg_lo:[0, 0, 1] neg_hi:[0, 0, 1]
	v_cvt_pk_bf16_f32 v2, v2, v3
	v_cvt_pk_bf16_f32 v3, v4, v5
	v_pk_fma_f32 v[4:5], v[52:53], v[76:77], 0 op_sel_hi:[0, 1, 0]
	v_pk_fma_f32 v[4:5], v[54:55], v[6:7], v[4:5] op_sel_hi:[0, 1, 1]
	v_pk_fma_f32 v[4:5], v[58:59], v[82:83], v[4:5] op_sel_hi:[0, 1, 1]
	v_lshlrev_b32_e32 v6, 16, v16
	v_and_b32_e32 v7, 0xffff0000, v16
	v_pk_fma_f32 v[4:5], v[66:67], v[6:7], v[4:5] op_sel_hi:[0, 1, 1]
	v_lshlrev_b32_e32 v6, 16, v20
	v_and_b32_e32 v7, 0xffff0000, v20
	v_pk_fma_f32 v[4:5], v[64:65], v[6:7], v[4:5] op_sel_hi:[0, 1, 1]
	v_lshlrev_b32_e32 v10, 16, v24
	v_and_b32_e32 v11, 0xffff0000, v24
	v_pk_fma_f32 v[4:5], v[62:63], v[10:11], v[4:5] op_sel_hi:[0, 1, 1]
	v_lshlrev_b32_e32 v10, 16, v28
	v_and_b32_e32 v11, 0xffff0000, v28
	v_pk_fma_f32 v[4:5], v[60:61], v[10:11], v[4:5] op_sel_hi:[0, 1, 1]
	v_lshlrev_b32_e32 v10, 16, v32
	v_and_b32_e32 v11, 0xffff0000, v32
	v_pk_fma_f32 v[4:5], v[56:57], v[10:11], v[4:5] op_sel_hi:[0, 1, 1]
	v_lshlrev_b32_e32 v8, 16, v9
	v_and_b32_e32 v9, 0xffff0000, v9
	v_pk_fma_f32 v[4:5], v[50:51], v[4:5], v[6:7] op_sel_hi:[0, 1, 1] neg_lo:[0, 0, 1] neg_hi:[0, 0, 1]
	v_pk_fma_f32 v[6:7], v[52:53], v[78:79], 0 op_sel_hi:[0, 1, 0]
	v_lshlrev_b32_e32 v12, 16, v13
	v_and_b32_e32 v13, 0xffff0000, v13
	v_pk_fma_f32 v[6:7], v[54:55], v[8:9], v[6:7] op_sel_hi:[0, 1, 1]
	v_pk_fma_f32 v[6:7], v[58:59], v[12:13], v[6:7] op_sel_hi:[0, 1, 1]
	v_lshlrev_b32_e32 v8, 16, v17
	v_and_b32_e32 v9, 0xffff0000, v17
	v_pk_fma_f32 v[6:7], v[66:67], v[8:9], v[6:7] op_sel_hi:[0, 1, 1]
	v_lshlrev_b32_e32 v8, 16, v21
	v_and_b32_e32 v9, 0xffff0000, v21
	v_pk_fma_f32 v[6:7], v[64:65], v[8:9], v[6:7] op_sel_hi:[0, 1, 1]
	v_lshlrev_b32_e32 v10, 16, v25
	v_and_b32_e32 v11, 0xffff0000, v25
	v_pk_fma_f32 v[6:7], v[62:63], v[10:11], v[6:7] op_sel_hi:[0, 1, 1]
	v_lshlrev_b32_e32 v10, 16, v29
	v_and_b32_e32 v11, 0xffff0000, v29
	v_pk_fma_f32 v[6:7], v[60:61], v[10:11], v[6:7] op_sel_hi:[0, 1, 1]
	v_lshlrev_b32_e32 v10, 16, v33
	v_and_b32_e32 v11, 0xffff0000, v33
	v_pk_fma_f32 v[6:7], v[56:57], v[10:11], v[6:7] op_sel_hi:[0, 1, 1]
	v_pk_fma_f32 v[6:7], v[50:51], v[6:7], v[8:9] op_sel_hi:[0, 1, 1] neg_lo:[0, 0, 1] neg_hi:[0, 0, 1]
	v_cvt_pk_bf16_f32 v4, v4, v5
	v_cvt_pk_bf16_f32 v5, v6, v7
	s_nop 0
	s_nop 0
	s_nop 0
	s_nop 0
	s_nop 0
	s_nop 0
	s_nop 0
	s_nop 0
	s_waitcnt vmcnt(23)
	v_lshlrev_b32_e32 v76, 16, v92
	v_and_b32_e32 v77, 0xffff0000, v92
	v_lshlrev_b32_e32 v78, 16, v93
	v_and_b32_e32 v79, 0xffff0000, v93
	s_waitcnt vmcnt(22)
	v_lshlrev_b32_e32 v6, 16, v96
	v_and_b32_e32 v7, 0xffff0000, v96
	v_pk_fma_f32 v[76:77], v[52:53], v[76:77], 0 op_sel_hi:[0, 1, 0]
	s_waitcnt vmcnt(21)
	v_lshlrev_b32_e32 v84, 16, v100
	v_and_b32_e32 v85, 0xffff0000, v100
	v_pk_fma_f32 v[6:7], v[54:55], v[6:7], v[76:77] op_sel_hi:[0, 1, 1]
	v_pk_fma_f32 v[6:7], v[58:59], v[84:85], v[6:7] op_sel_hi:[0, 1, 1]
	s_waitcnt vmcnt(20)
	v_lshlrev_b32_e32 v76, 16, v104
	v_and_b32_e32 v77, 0xffff0000, v104
	v_pk_fma_f32 v[6:7], v[66:67], v[76:77], v[6:7] op_sel_hi:[0, 1, 1]
	s_waitcnt vmcnt(19)
	v_lshlrev_b32_e32 v76, 16, v108
	v_and_b32_e32 v77, 0xffff0000, v108
	v_pk_fma_f32 v[6:7], v[64:65], v[76:77], v[6:7] op_sel_hi:[0, 1, 1]
	s_waitcnt vmcnt(18)
	v_lshlrev_b32_e32 v84, 16, v112
	v_and_b32_e32 v85, 0xffff0000, v112
	v_pk_fma_f32 v[6:7], v[62:63], v[84:85], v[6:7] op_sel_hi:[0, 1, 1]
	s_waitcnt vmcnt(17)
	v_lshlrev_b32_e32 v84, 16, v116
	v_and_b32_e32 v85, 0xffff0000, v116
	v_pk_fma_f32 v[6:7], v[60:61], v[84:85], v[6:7] op_sel_hi:[0, 1, 1]
	s_waitcnt vmcnt(16)
	v_lshlrev_b32_e32 v84, 16, v120
	v_and_b32_e32 v85, 0xffff0000, v120
	v_pk_fma_f32 v[6:7], v[56:57], v[84:85], v[6:7] op_sel_hi:[0, 1, 1]
	v_lshlrev_b32_e32 v80, 16, v94
	v_and_b32_e32 v81, 0xffff0000, v94
	v_lshlrev_b32_e32 v82, 16, v95
	v_and_b32_e32 v83, 0xffff0000, v95
	v_lshlrev_b32_e32 v8, 16, v97
	v_and_b32_e32 v9, 0xffff0000, v97
	v_pk_fma_f32 v[6:7], v[50:51], v[6:7], v[76:77] op_sel_hi:[0, 1, 1] neg_lo:[0, 0, 1] neg_hi:[0, 0, 1]
	v_pk_fma_f32 v[76:77], v[52:53], v[78:79], 0 op_sel_hi:[0, 1, 0]
	v_lshlrev_b32_e32 v22, 16, v101
	v_and_b32_e32 v23, 0xffff0000, v101
	v_pk_fma_f32 v[8:9], v[54:55], v[8:9], v[76:77] op_sel_hi:[0, 1, 1]
	v_pk_fma_f32 v[8:9], v[58:59], v[22:23], v[8:9] op_sel_hi:[0, 1, 1]
	v_lshlrev_b32_e32 v14, 16, v105
	v_and_b32_e32 v15, 0xffff0000, v105
	v_pk_fma_f32 v[8:9], v[66:67], v[14:15], v[8:9] op_sel_hi:[0, 1, 1]
	v_lshlrev_b32_e32 v14, 16, v109
	v_and_b32_e32 v15, 0xffff0000, v109
	v_pk_fma_f32 v[8:9], v[64:65], v[14:15], v[8:9] op_sel_hi:[0, 1, 1]
	v_lshlrev_b32_e32 v18, 16, v113
	v_and_b32_e32 v19, 0xffff0000, v113
	v_pk_fma_f32 v[8:9], v[62:63], v[18:19], v[8:9] op_sel_hi:[0, 1, 1]
	v_lshlrev_b32_e32 v18, 16, v117
	v_and_b32_e32 v19, 0xffff0000, v117
	v_pk_fma_f32 v[8:9], v[60:61], v[18:19], v[8:9] op_sel_hi:[0, 1, 1]
	v_lshlrev_b32_e32 v18, 16, v121
	v_and_b32_e32 v19, 0xffff0000, v121
	v_pk_fma_f32 v[8:9], v[56:57], v[18:19], v[8:9] op_sel_hi:[0, 1, 1]
	v_pk_fma_f32 v[8:9], v[50:51], v[8:9], v[14:15] op_sel_hi:[0, 1, 1] neg_lo:[0, 0, 1] neg_hi:[0, 0, 1]
	v_lshlrev_b32_e32 v10, 16, v98
	v_and_b32_e32 v11, 0xffff0000, v98
	v_cvt_pk_bf16_f32 v6, v6, v7
	v_cvt_pk_bf16_f32 v7, v8, v9
	v_pk_fma_f32 v[8:9], v[52:53], v[80:81], 0 op_sel_hi:[0, 1, 0]
	v_lshlrev_b32_e32 v86, 16, v102
	v_and_b32_e32 v87, 0xffff0000, v102
	v_pk_fma_f32 v[8:9], v[54:55], v[10:11], v[8:9] op_sel_hi:[0, 1, 1]
	v_pk_fma_f32 v[8:9], v[58:59], v[86:87], v[8:9] op_sel_hi:[0, 1, 1]
	v_lshlrev_b32_e32 v10, 16, v106
	v_and_b32_e32 v11, 0xffff0000, v106
	v_pk_fma_f32 v[8:9], v[66:67], v[10:11], v[8:9] op_sel_hi:[0, 1, 1]
	v_lshlrev_b32_e32 v10, 16, v110
	v_and_b32_e32 v11, 0xffff0000, v110
	v_pk_fma_f32 v[8:9], v[64:65], v[10:11], v[8:9] op_sel_hi:[0, 1, 1]
	v_lshlrev_b32_e32 v14, 16, v114
	v_and_b32_e32 v15, 0xffff0000, v114
	v_pk_fma_f32 v[8:9], v[62:63], v[14:15], v[8:9] op_sel_hi:[0, 1, 1]
	v_lshlrev_b32_e32 v14, 16, v118
	v_and_b32_e32 v15, 0xffff0000, v118
	v_pk_fma_f32 v[8:9], v[60:61], v[14:15], v[8:9] op_sel_hi:[0, 1, 1]
	v_lshlrev_b32_e32 v14, 16, v122
	v_and_b32_e32 v15, 0xffff0000, v122
	v_pk_fma_f32 v[8:9], v[56:57], v[14:15], v[8:9] op_sel_hi:[0, 1, 1]
	v_lshlrev_b32_e32 v12, 16, v99
	v_and_b32_e32 v13, 0xffff0000, v99
	v_pk_fma_f32 v[8:9], v[50:51], v[8:9], v[10:11] op_sel_hi:[0, 1, 1] neg_lo:[0, 0, 1] neg_hi:[0, 0, 1]
	v_pk_fma_f32 v[10:11], v[52:53], v[82:83], 0 op_sel_hi:[0, 1, 0]
	v_lshlrev_b32_e32 v24, 16, v103
	v_and_b32_e32 v25, 0xffff0000, v103
	v_pk_fma_f32 v[10:11], v[54:55], v[12:13], v[10:11] op_sel_hi:[0, 1, 1]
	v_pk_fma_f32 v[10:11], v[58:59], v[24:25], v[10:11] op_sel_hi:[0, 1, 1]
	v_lshlrev_b32_e32 v12, 16, v107
	v_and_b32_e32 v13, 0xffff0000, v107
	v_pk_fma_f32 v[10:11], v[66:67], v[12:13], v[10:11] op_sel_hi:[0, 1, 1]
	v_lshlrev_b32_e32 v12, 16, v111
	v_and_b32_e32 v13, 0xffff0000, v111
	v_pk_fma_f32 v[10:11], v[64:65], v[12:13], v[10:11] op_sel_hi:[0, 1, 1]
	v_lshlrev_b32_e32 v14, 16, v115
	v_and_b32_e32 v15, 0xffff0000, v115
	v_pk_fma_f32 v[10:11], v[62:63], v[14:15], v[10:11] op_sel_hi:[0, 1, 1]
	v_lshlrev_b32_e32 v14, 16, v119
	v_and_b32_e32 v15, 0xffff0000, v119
	v_pk_fma_f32 v[10:11], v[60:61], v[14:15], v[10:11] op_sel_hi:[0, 1, 1]
	v_lshlrev_b32_e32 v14, 16, v123
	v_and_b32_e32 v15, 0xffff0000, v123
	v_pk_fma_f32 v[10:11], v[56:57], v[14:15], v[10:11] op_sel_hi:[0, 1, 1]
	v_pk_fma_f32 v[10:11], v[50:51], v[10:11], v[12:13] op_sel_hi:[0, 1, 1] neg_lo:[0, 0, 1] neg_hi:[0, 0, 1]
	v_cvt_pk_bf16_f32 v8, v8, v9
	v_cvt_pk_bf16_f32 v9, v10, v11
	s_nop 0
	s_nop 0
	s_nop 0
	s_nop 0
	s_nop 0
	s_nop 0
	s_nop 0
	s_nop 0
	s_waitcnt vmcnt(15)
	v_lshlrev_b32_e32 v80, 16, v124
	v_and_b32_e32 v81, 0xffff0000, v124
	v_lshlrev_b32_e32 v82, 16, v125
	v_and_b32_e32 v83, 0xffff0000, v125
	s_waitcnt vmcnt(14)
	v_lshlrev_b32_e32 v10, 16, v128
	v_and_b32_e32 v11, 0xffff0000, v128
	v_pk_fma_f32 v[80:81], v[52:53], v[80:81], 0 op_sel_hi:[0, 1, 0]
	s_waitcnt vmcnt(13)
	v_lshlrev_b32_e32 v88, 16, v132
	v_and_b32_e32 v89, 0xffff0000, v132
	v_pk_fma_f32 v[10:11], v[54:55], v[10:11], v[80:81] op_sel_hi:[0, 1, 1]
	v_pk_fma_f32 v[10:11], v[58:59], v[88:89], v[10:11] op_sel_hi:[0, 1, 1]
	s_waitcnt vmcnt(12)
	v_lshlrev_b32_e32 v80, 16, v136
	v_and_b32_e32 v81, 0xffff0000, v136
	v_pk_fma_f32 v[10:11], v[66:67], v[80:81], v[10:11] op_sel_hi:[0, 1, 1]
	s_waitcnt vmcnt(11)
	v_lshlrev_b32_e32 v80, 16, v140
	v_and_b32_e32 v81, 0xffff0000, v140
	v_pk_fma_f32 v[10:11], v[64:65], v[80:81], v[10:11] op_sel_hi:[0, 1, 1]
	s_waitcnt vmcnt(10)
	v_lshlrev_b32_e32 v88, 16, v144
	v_and_b32_e32 v89, 0xffff0000, v144
	v_pk_fma_f32 v[10:11], v[62:63], v[88:89], v[10:11] op_sel_hi:[0, 1, 1]
	s_waitcnt vmcnt(9)
	v_lshlrev_b32_e32 v88, 16, v148
	v_and_b32_e32 v89, 0xffff0000, v148
	v_pk_fma_f32 v[10:11], v[60:61], v[88:89], v[10:11] op_sel_hi:[0, 1, 1]
	s_waitcnt vmcnt(8)
	v_lshlrev_b32_e32 v88, 16, v152
	v_and_b32_e32 v89, 0xffff0000, v152
	v_pk_fma_f32 v[10:11], v[56:57], v[88:89], v[10:11] op_sel_hi:[0, 1, 1]
	v_lshlrev_b32_e32 v84, 16, v126
	v_and_b32_e32 v85, 0xffff0000, v126
	v_lshlrev_b32_e32 v86, 16, v127
	v_and_b32_e32 v87, 0xffff0000, v127
	v_lshlrev_b32_e32 v12, 16, v129
	v_and_b32_e32 v13, 0xffff0000, v129
	v_pk_fma_f32 v[10:11], v[50:51], v[10:11], v[80:81] op_sel_hi:[0, 1, 1] neg_lo:[0, 0, 1] neg_hi:[0, 0, 1]
	v_pk_fma_f32 v[80:81], v[52:53], v[82:83], 0 op_sel_hi:[0, 1, 0]
	v_lshlrev_b32_e32 v18, 16, v133
	v_and_b32_e32 v19, 0xffff0000, v133
	v_pk_fma_f32 v[12:13], v[54:55], v[12:13], v[80:81] op_sel_hi:[0, 1, 1]
	v_pk_fma_f32 v[12:13], v[58:59], v[18:19], v[12:13] op_sel_hi:[0, 1, 1]
	v_lshlrev_b32_e32 v18, 16, v137
	v_and_b32_e32 v19, 0xffff0000, v137
	v_pk_fma_f32 v[12:13], v[66:67], v[18:19], v[12:13] op_sel_hi:[0, 1, 1]
	v_lshlrev_b32_e32 v18, 16, v141
	v_and_b32_e32 v19, 0xffff0000, v141
	v_pk_fma_f32 v[12:13], v[64:65], v[18:19], v[12:13] op_sel_hi:[0, 1, 1]
	v_lshlrev_b32_e32 v22, 16, v145
	v_and_b32_e32 v23, 0xffff0000, v145
	v_pk_fma_f32 v[12:13], v[62:63], v[22:23], v[12:13] op_sel_hi:[0, 1, 1]
	v_lshlrev_b32_e32 v22, 16, v149
	v_and_b32_e32 v23, 0xffff0000, v149
	v_pk_fma_f32 v[12:13], v[60:61], v[22:23], v[12:13] op_sel_hi:[0, 1, 1]
	v_lshlrev_b32_e32 v22, 16, v153
	v_and_b32_e32 v23, 0xffff0000, v153
	v_pk_fma_f32 v[12:13], v[56:57], v[22:23], v[12:13] op_sel_hi:[0, 1, 1]
	v_pk_fma_f32 v[12:13], v[50:51], v[12:13], v[18:19] op_sel_hi:[0, 1, 1] neg_lo:[0, 0, 1] neg_hi:[0, 0, 1]
	v_lshlrev_b32_e32 v14, 16, v130
	v_and_b32_e32 v15, 0xffff0000, v130
	v_cvt_pk_bf16_f32 v10, v10, v11
	v_cvt_pk_bf16_f32 v11, v12, v13
	v_pk_fma_f32 v[12:13], v[52:53], v[84:85], 0 op_sel_hi:[0, 1, 0]
	v_lshlrev_b32_e32 v90, 16, v134
	v_and_b32_e32 v91, 0xffff0000, v134
	v_pk_fma_f32 v[12:13], v[54:55], v[14:15], v[12:13] op_sel_hi:[0, 1, 1]
	v_pk_fma_f32 v[12:13], v[58:59], v[90:91], v[12:13] op_sel_hi:[0, 1, 1]
	v_lshlrev_b32_e32 v14, 16, v138
	v_and_b32_e32 v15, 0xffff0000, v138
	v_pk_fma_f32 v[12:13], v[66:67], v[14:15], v[12:13] op_sel_hi:[0, 1, 1]
	v_lshlrev_b32_e32 v14, 16, v142
	v_and_b32_e32 v15, 0xffff0000, v142
	v_pk_fma_f32 v[12:13], v[64:65], v[14:15], v[12:13] op_sel_hi:[0, 1, 1]
	v_lshlrev_b32_e32 v18, 16, v146
	v_and_b32_e32 v19, 0xffff0000, v146
	v_pk_fma_f32 v[12:13], v[62:63], v[18:19], v[12:13] op_sel_hi:[0, 1, 1]
	v_lshlrev_b32_e32 v18, 16, v150
	v_and_b32_e32 v19, 0xffff0000, v150
	v_pk_fma_f32 v[12:13], v[60:61], v[18:19], v[12:13] op_sel_hi:[0, 1, 1]
	v_lshlrev_b32_e32 v18, 16, v154
	v_and_b32_e32 v19, 0xffff0000, v154
	v_pk_fma_f32 v[12:13], v[56:57], v[18:19], v[12:13] op_sel_hi:[0, 1, 1]
	v_lshlrev_b32_e32 v16, 16, v131
	v_and_b32_e32 v17, 0xffff0000, v131
	v_pk_fma_f32 v[12:13], v[50:51], v[12:13], v[14:15] op_sel_hi:[0, 1, 1] neg_lo:[0, 0, 1] neg_hi:[0, 0, 1]
	v_pk_fma_f32 v[14:15], v[52:53], v[86:87], 0 op_sel_hi:[0, 1, 0]
	v_lshlrev_b32_e32 v20, 16, v135
	v_and_b32_e32 v21, 0xffff0000, v135
	v_pk_fma_f32 v[14:15], v[54:55], v[16:17], v[14:15] op_sel_hi:[0, 1, 1]
	v_pk_fma_f32 v[14:15], v[58:59], v[20:21], v[14:15] op_sel_hi:[0, 1, 1]
	v_lshlrev_b32_e32 v16, 16, v139
	v_and_b32_e32 v17, 0xffff0000, v139
	v_pk_fma_f32 v[14:15], v[66:67], v[16:17], v[14:15] op_sel_hi:[0, 1, 1]
	v_lshlrev_b32_e32 v16, 16, v143
	v_and_b32_e32 v17, 0xffff0000, v143
	v_pk_fma_f32 v[14:15], v[64:65], v[16:17], v[14:15] op_sel_hi:[0, 1, 1]
	v_lshlrev_b32_e32 v18, 16, v147
	v_and_b32_e32 v19, 0xffff0000, v147
	v_pk_fma_f32 v[14:15], v[62:63], v[18:19], v[14:15] op_sel_hi:[0, 1, 1]
	v_lshlrev_b32_e32 v18, 16, v151
	v_and_b32_e32 v19, 0xffff0000, v151
	v_pk_fma_f32 v[14:15], v[60:61], v[18:19], v[14:15] op_sel_hi:[0, 1, 1]
	v_lshlrev_b32_e32 v18, 16, v155
	v_and_b32_e32 v19, 0xffff0000, v155
	v_pk_fma_f32 v[14:15], v[56:57], v[18:19], v[14:15] op_sel_hi:[0, 1, 1]
	v_pk_fma_f32 v[14:15], v[50:51], v[14:15], v[16:17] op_sel_hi:[0, 1, 1] neg_lo:[0, 0, 1] neg_hi:[0, 0, 1]
	v_cvt_pk_bf16_f32 v12, v12, v13
	v_cvt_pk_bf16_f32 v13, v14, v15
	s_nop 0
	s_nop 0
	s_nop 0
	s_nop 0
	s_nop 0
	s_nop 0
	s_nop 0
	s_nop 0
	s_nop 0
	s_nop 0
	s_waitcnt vmcnt(7)
	v_lshlrev_b32_e32 v68, 16, v156
	v_and_b32_e32 v69, 0xffff0000, v156
	v_lshlrev_b32_e32 v70, 16, v157
	v_and_b32_e32 v71, 0xffff0000, v157
	s_waitcnt vmcnt(6)
	v_lshlrev_b32_e32 v14, 16, v160
	v_and_b32_e32 v15, 0xffff0000, v160
	v_pk_fma_f32 v[68:69], v[52:53], v[68:69], 0 op_sel_hi:[0, 1, 0]
	s_waitcnt vmcnt(5)
	v_lshlrev_b32_e32 v76, 16, v164
	v_and_b32_e32 v77, 0xffff0000, v164
	v_pk_fma_f32 v[14:15], v[54:55], v[14:15], v[68:69] op_sel_hi:[0, 1, 1]
	v_pk_fma_f32 v[14:15], v[58:59], v[76:77], v[14:15] op_sel_hi:[0, 1, 1]
	s_waitcnt vmcnt(4)
	v_lshlrev_b32_e32 v68, 16, v168
	v_and_b32_e32 v69, 0xffff0000, v168
	v_pk_fma_f32 v[14:15], v[66:67], v[68:69], v[14:15] op_sel_hi:[0, 1, 1]
	s_waitcnt vmcnt(3)
	v_lshlrev_b32_e32 v68, 16, v172
	v_and_b32_e32 v69, 0xffff0000, v172
	v_pk_fma_f32 v[14:15], v[64:65], v[68:69], v[14:15] op_sel_hi:[0, 1, 1]
	s_waitcnt vmcnt(2)
	v_lshlrev_b32_e32 v76, 16, v176
	v_and_b32_e32 v77, 0xffff0000, v176
	v_pk_fma_f32 v[14:15], v[62:63], v[76:77], v[14:15] op_sel_hi:[0, 1, 1]
	s_waitcnt vmcnt(1)
	v_lshlrev_b32_e32 v76, 16, v180
	v_and_b32_e32 v77, 0xffff0000, v180
	v_pk_fma_f32 v[14:15], v[60:61], v[76:77], v[14:15] op_sel_hi:[0, 1, 1]
	s_waitcnt vmcnt(0)
	v_lshlrev_b32_e32 v76, 16, v184
	v_and_b32_e32 v77, 0xffff0000, v184
	v_pk_fma_f32 v[14:15], v[56:57], v[76:77], v[14:15] op_sel_hi:[0, 1, 1]
	v_lshlrev_b32_e32 v72, 16, v158
	v_and_b32_e32 v73, 0xffff0000, v158
	v_lshlrev_b32_e32 v74, 16, v159
	v_and_b32_e32 v75, 0xffff0000, v159
	v_lshlrev_b32_e32 v16, 16, v161
	v_and_b32_e32 v17, 0xffff0000, v161
	v_pk_fma_f32 v[14:15], v[50:51], v[14:15], v[68:69] op_sel_hi:[0, 1, 1] neg_lo:[0, 0, 1] neg_hi:[0, 0, 1]
	v_pk_fma_f32 v[68:69], v[52:53], v[70:71], 0 op_sel_hi:[0, 1, 0]
	v_lshlrev_b32_e32 v30, 16, v165
	v_and_b32_e32 v31, 0xffff0000, v165
	v_pk_fma_f32 v[16:17], v[54:55], v[16:17], v[68:69] op_sel_hi:[0, 1, 1]
	v_pk_fma_f32 v[16:17], v[58:59], v[30:31], v[16:17] op_sel_hi:[0, 1, 1]
	v_lshlrev_b32_e32 v22, 16, v169
	v_and_b32_e32 v23, 0xffff0000, v169
	v_pk_fma_f32 v[16:17], v[66:67], v[22:23], v[16:17] op_sel_hi:[0, 1, 1]
	v_lshlrev_b32_e32 v22, 16, v173
	v_and_b32_e32 v23, 0xffff0000, v173
	v_pk_fma_f32 v[16:17], v[64:65], v[22:23], v[16:17] op_sel_hi:[0, 1, 1]
	v_lshlrev_b32_e32 v26, 16, v177
	v_and_b32_e32 v27, 0xffff0000, v177
	v_pk_fma_f32 v[16:17], v[62:63], v[26:27], v[16:17] op_sel_hi:[0, 1, 1]
	v_lshlrev_b32_e32 v26, 16, v181
	v_and_b32_e32 v27, 0xffff0000, v181
	v_pk_fma_f32 v[16:17], v[60:61], v[26:27], v[16:17] op_sel_hi:[0, 1, 1]
	v_lshlrev_b32_e32 v26, 16, v185
	v_and_b32_e32 v27, 0xffff0000, v185
	v_pk_fma_f32 v[16:17], v[56:57], v[26:27], v[16:17] op_sel_hi:[0, 1, 1]
	v_pk_fma_f32 v[16:17], v[50:51], v[16:17], v[22:23] op_sel_hi:[0, 1, 1] neg_lo:[0, 0, 1] neg_hi:[0, 0, 1]
	v_lshlrev_b32_e32 v18, 16, v162
	v_and_b32_e32 v19, 0xffff0000, v162
	v_cvt_pk_bf16_f32 v14, v14, v15
	v_cvt_pk_bf16_f32 v15, v16, v17
	v_pk_fma_f32 v[16:17], v[52:53], v[72:73], 0 op_sel_hi:[0, 1, 0]
	v_lshlrev_b32_e32 v78, 16, v166
	v_and_b32_e32 v79, 0xffff0000, v166
	v_pk_fma_f32 v[16:17], v[54:55], v[18:19], v[16:17] op_sel_hi:[0, 1, 1]
	v_pk_fma_f32 v[16:17], v[58:59], v[78:79], v[16:17] op_sel_hi:[0, 1, 1]
	v_lshlrev_b32_e32 v18, 16, v170
	v_and_b32_e32 v19, 0xffff0000, v170
	v_pk_fma_f32 v[16:17], v[66:67], v[18:19], v[16:17] op_sel_hi:[0, 1, 1]
	v_lshlrev_b32_e32 v18, 16, v174
	v_and_b32_e32 v19, 0xffff0000, v174
	v_pk_fma_f32 v[16:17], v[64:65], v[18:19], v[16:17] op_sel_hi:[0, 1, 1]
	v_lshlrev_b32_e32 v22, 16, v178
	v_and_b32_e32 v23, 0xffff0000, v178
	v_pk_fma_f32 v[16:17], v[62:63], v[22:23], v[16:17] op_sel_hi:[0, 1, 1]
	v_lshlrev_b32_e32 v22, 16, v182
	v_and_b32_e32 v23, 0xffff0000, v182
	v_pk_fma_f32 v[16:17], v[60:61], v[22:23], v[16:17] op_sel_hi:[0, 1, 1]
	v_lshlrev_b32_e32 v22, 16, v186
	v_and_b32_e32 v23, 0xffff0000, v186
	v_pk_fma_f32 v[16:17], v[56:57], v[22:23], v[16:17] op_sel_hi:[0, 1, 1]
	v_lshlrev_b32_e32 v20, 16, v163
	v_and_b32_e32 v21, 0xffff0000, v163
	v_pk_fma_f32 v[16:17], v[50:51], v[16:17], v[18:19] op_sel_hi:[0, 1, 1] neg_lo:[0, 0, 1] neg_hi:[0, 0, 1]
	v_pk_fma_f32 v[18:19], v[52:53], v[74:75], 0 op_sel_hi:[0, 1, 0]
	v_lshlrev_b32_e32 v32, 16, v167
	v_and_b32_e32 v33, 0xffff0000, v167
	v_pk_fma_f32 v[18:19], v[54:55], v[20:21], v[18:19] op_sel_hi:[0, 1, 1]
	v_pk_fma_f32 v[18:19], v[58:59], v[32:33], v[18:19] op_sel_hi:[0, 1, 1]
	v_lshlrev_b32_e32 v20, 16, v171
	v_and_b32_e32 v21, 0xffff0000, v171
	v_pk_fma_f32 v[18:19], v[66:67], v[20:21], v[18:19] op_sel_hi:[0, 1, 1]
	v_lshlrev_b32_e32 v20, 16, v175
	v_and_b32_e32 v21, 0xffff0000, v175
	v_pk_fma_f32 v[18:19], v[64:65], v[20:21], v[18:19] op_sel_hi:[0, 1, 1]
	v_lshlrev_b32_e32 v22, 16, v179
	v_and_b32_e32 v23, 0xffff0000, v179
	v_pk_fma_f32 v[18:19], v[62:63], v[22:23], v[18:19] op_sel_hi:[0, 1, 1]
	v_lshlrev_b32_e32 v22, 16, v183
	v_and_b32_e32 v23, 0xffff0000, v183
	v_pk_fma_f32 v[18:19], v[60:61], v[22:23], v[18:19] op_sel_hi:[0, 1, 1]
	v_lshlrev_b32_e32 v22, 16, v187
	v_and_b32_e32 v23, 0xffff0000, v187
	v_pk_fma_f32 v[18:19], v[56:57], v[22:23], v[18:19] op_sel_hi:[0, 1, 1]
	v_pk_fma_f32 v[18:19], v[50:51], v[18:19], v[20:21] op_sel_hi:[0, 1, 1] neg_lo:[0, 0, 1] neg_hi:[0, 0, 1]
	v_lshlrev_b64 v[20:21], 11, v[48:49]
	v_cvt_pk_bf16_f32 v16, v16, v17
	v_cvt_pk_bf16_f32 v17, v18, v19
	v_lshl_add_u64 v[18:19], s[34:35], 0, v[46:47]
	v_lshl_add_u64 v[30:31], s[84:85], 0, v[20:21]
	v_lshlrev_b32_e32 v20, 8, v53
	v_mov_b32_e32 v21, v1
	v_lshl_add_u64 v[28:29], v[18:19], 0, v[20:21]
	v_add_co_u32_e32 v56, vcc, 0x1000, v28
	s_nop 1
	v_addc_co_u32_e32 v57, vcc, 0, v29, vcc
	v_add_co_u32_e32 v58, vcc, 0x3000, v28
	s_nop 1
	v_addc_co_u32_e32 v59, vcc, 0, v29, vcc
	v_add_co_u32_e32 v60, vcc, 0x5000, v28
	s_nop 1
	v_addc_co_u32_e32 v61, vcc, 0, v29, vcc
	v_add_co_u32_e32 v62, vcc, 0x7000, v28
	s_nop 1
	v_addc_co_u32_e32 v63, vcc, 0, v29, vcc
	global_load_dwordx4 v[84:87], v[56:57], off offset:-4096
	global_load_dwordx4 v[88:91], v[56:57], off offset:-4032
	global_load_dwordx4 v[92:95], v[56:57], off offset:-3968
	global_load_dwordx4 v[96:99], v[56:57], off offset:-3904
	global_load_dwordx4 v[100:103], v46, s[30:31] offset:1024
	global_load_dwordx4 v[104:107], v[56:57], off
	global_load_dwordx4 v[108:111], v[56:57], off offset:64
	global_load_dwordx4 v[112:115], v[56:57], off offset:128
	global_load_dwordx4 v[116:119], v[56:57], off offset:192
	global_load_dwordx4 v[120:123], v46, s[30:31] offset:1088
	global_load_dwordx4 v[124:127], v[58:59], off offset:-4096
	global_load_dwordx4 v[128:131], v[58:59], off offset:-4032
	global_load_dwordx4 v[132:135], v[58:59], off offset:-3968
	global_load_dwordx4 v[136:139], v[58:59], off offset:-3904
	global_load_dwordx4 v[140:143], v46, s[30:31] offset:1152
	global_load_dwordx4 v[144:147], v[58:59], off
	global_load_dwordx4 v[148:151], v[58:59], off offset:64
	global_load_dwordx4 v[152:155], v[58:59], off offset:128
	global_load_dwordx4 v[156:159], v[58:59], off offset:192
	global_load_dwordx4 v[160:163], v46, s[30:31] offset:1216
	global_load_dwordx4 v[164:167], v[60:61], off offset:-4096
	global_load_dwordx4 v[168:171], v[60:61], off offset:-4032
	global_load_dwordx4 v[172:175], v[60:61], off offset:-3968
	global_load_dwordx4 v[176:179], v[60:61], off offset:-3904
	global_load_dwordx4 v[180:183], v46, s[30:31] offset:1280
	global_load_dwordx4 v[184:187], v[60:61], off
	global_load_dwordx4 v[188:191], v[60:61], off offset:64
	global_load_dwordx4 v[192:195], v[60:61], off offset:128
	global_load_dwordx4 v[196:199], v[60:61], off offset:192
	global_load_dwordx4 v[200:203], v46, s[30:31] offset:1344
	global_load_dwordx4 v[204:207], v[62:63], off offset:-4096
	global_load_dwordx4 v[222:225], v[62:63], off offset:-4032
	global_load_dwordx4 v[226:229], v[62:63], off offset:-3968
	global_load_dwordx4 v[230:233], v[62:63], off offset:-3904
	global_load_dwordx4 v[234:237], v46, s[30:31] offset:1408
	global_load_dwordx4 v[238:241], v[62:63], off
	global_load_dwordx4 v[242:245], v[62:63], off offset:64
	global_load_dwordx4 v[246:249], v[62:63], off offset:128
	global_load_dwordx4 v[52:55], v[62:63], off offset:192
	s_nop 0
	s_nop 0
	s_waitcnt vmcnt(38)
	v_mfma_f32_16x16x32_bf16 v[18:21], v[84:87], v[2:5], 0
	v_lshl_add_u64 v[26:27], v[30:31], 0, s[0:1]
	s_movk_i32 s0, 0x1000
	s_waitcnt vmcnt(37)
	v_mfma_f32_16x16x32_bf16 v[18:21], v[88:91], v[6:9], v[18:21]
	s_nop 0
	s_waitcnt vmcnt(36)
	v_mfma_f32_16x16x32_bf16 v[18:21], v[92:95], v[10:13], v[18:21]
	s_nop 0
	s_waitcnt vmcnt(35)
	v_mfma_f32_16x16x32_bf16 v[18:21], v[96:99], v[14:17], v[18:21]
	s_nop 0
	s_waitcnt vmcnt(34)
	s_nop 5
	v_pk_mul_f32 v[20:21], v[20:21], v[102:103]
	v_add_co_u32_e32 v24, vcc, s0, v28
	v_pk_mul_f32 v[18:19], v[18:19], v[100:101]
	s_nop 0
	v_addc_co_u32_e32 v25, vcc, 0, v29, vcc
	s_movk_i32 s0, 0x2000
	v_cvt_pk_bf16_f32 v22, v18, v19
	v_cvt_pk_bf16_f32 v23, v20, v21
	v_lshl_add_u64 v[18:19], v[30:31], 0, v[0:1]
	v_add_co_u32_e32 v34, vcc, s0, v28
	global_store_dwordx2 v[18:19], v[22:23], off offset:1536
	s_nop 0
	v_addc_co_u32_e32 v35, vcc, 0, v29, vcc
	s_nop 0
	s_nop 0
	s_waitcnt vmcnt(34)
	v_mfma_f32_16x16x32_bf16 v[20:23], v[104:107], v[2:5], 0
	s_movk_i32 s0, 0x3000
	v_mov_b32_e32 v0, 0x170
	v_lshl_or_b32 v0, v51, 2, v0
	s_waitcnt vmcnt(33)
	v_mfma_f32_16x16x32_bf16 v[20:23], v[108:111], v[6:9], v[20:23]
	s_nop 0
	s_waitcnt vmcnt(32)
	v_mfma_f32_16x16x32_bf16 v[20:23], v[112:115], v[10:13], v[20:23]
	s_nop 0
	v_add_co_u32_e32 v24, vcc, s0, v28
	s_waitcnt vmcnt(31)
	v_mfma_f32_16x16x32_bf16 v[20:23], v[116:119], v[14:17], v[20:23]
	s_nop 0
	v_addc_co_u32_e32 v25, vcc, 0, v29, vcc
	s_movk_i32 s0, 0x4000
	s_waitcnt vmcnt(30)
	s_nop 3
	v_pk_mul_f32 v[22:23], v[22:23], v[122:123]
	v_pk_mul_f32 v[20:21], v[20:21], v[120:121]
	s_nop 0
	v_cvt_pk_bf16_f32 v20, v20, v21
	v_cvt_pk_bf16_f32 v21, v22, v23
	global_store_dwordx2 v[18:19], v[20:21], off offset:1568
	s_nop 0
	s_nop 0
	s_nop 0
	s_waitcnt vmcnt(30)
	v_mfma_f32_16x16x32_bf16 v[20:23], v[124:127], v[2:5], 0
	s_waitcnt vmcnt(29)
	v_mfma_f32_16x16x32_bf16 v[20:23], v[128:131], v[6:9], v[20:23]
	s_nop 0
	s_waitcnt vmcnt(28)
	v_mfma_f32_16x16x32_bf16 v[20:23], v[132:135], v[10:13], v[20:23]
	s_nop 0
	v_add_co_u32_e32 v34, vcc, s0, v28
	s_waitcnt vmcnt(27)
	v_mfma_f32_16x16x32_bf16 v[20:23], v[136:139], v[14:17], v[20:23]
	s_nop 0
	v_addc_co_u32_e32 v35, vcc, 0, v29, vcc
	s_movk_i32 s0, 0x5000
	s_waitcnt vmcnt(26)
	s_nop 3
	v_pk_mul_f32 v[22:23], v[22:23], v[142:143]
	v_pk_mul_f32 v[20:21], v[20:21], v[140:141]
	s_nop 0
	v_cvt_pk_bf16_f32 v20, v20, v21
	v_cvt_pk_bf16_f32 v21, v22, v23
	global_store_dwordx2 v[18:19], v[20:21], off offset:1600
	s_nop 0
	s_nop 0
	s_nop 0
	s_waitcnt vmcnt(26)
	v_mfma_f32_16x16x32_bf16 v[20:23], v[144:147], v[2:5], 0
	s_waitcnt vmcnt(25)
	v_mfma_f32_16x16x32_bf16 v[20:23], v[148:151], v[6:9], v[20:23]
	s_nop 0
	s_waitcnt vmcnt(24)
	v_mfma_f32_16x16x32_bf16 v[20:23], v[152:155], v[10:13], v[20:23]
	s_nop 0
	v_add_co_u32_e32 v24, vcc, s0, v28
	s_waitcnt vmcnt(23)
	v_mfma_f32_16x16x32_bf16 v[20:23], v[156:159], v[14:17], v[20:23]
	s_nop 0
	v_addc_co_u32_e32 v25, vcc, 0, v29, vcc
	s_movk_i32 s0, 0x6000
	s_waitcnt vmcnt(22)
	s_nop 3
	v_pk_mul_f32 v[22:23], v[22:23], v[162:163]
	v_pk_mul_f32 v[20:21], v[20:21], v[160:161]
	s_nop 0
	v_cvt_pk_bf16_f32 v20, v20, v21
	v_cvt_pk_bf16_f32 v21, v22, v23
	global_store_dwordx2 v[18:19], v[20:21], off offset:1632
	s_nop 0
	s_nop 0
	s_nop 0
	s_waitcnt vmcnt(22)
	v_mfma_f32_16x16x32_bf16 v[20:23], v[164:167], v[2:5], 0
	s_waitcnt vmcnt(21)
	v_mfma_f32_16x16x32_bf16 v[20:23], v[168:171], v[6:9], v[20:23]
	s_nop 0
	s_waitcnt vmcnt(20)
	v_mfma_f32_16x16x32_bf16 v[20:23], v[172:175], v[10:13], v[20:23]
	s_nop 0
	v_add_co_u32_e32 v34, vcc, s0, v28
	s_waitcnt vmcnt(19)
	v_mfma_f32_16x16x32_bf16 v[20:23], v[176:179], v[14:17], v[20:23]
	s_nop 0
	v_addc_co_u32_e32 v35, vcc, 0, v29, vcc
	s_waitcnt vmcnt(18)
	s_nop 4
	v_pk_mul_f32 v[22:23], v[22:23], v[182:183]
	v_pk_mul_f32 v[20:21], v[20:21], v[180:181]
	s_nop 0
	v_cvt_pk_bf16_f32 v20, v20, v21
	v_cvt_pk_bf16_f32 v21, v22, v23
	global_store_dwordx2 v[18:19], v[20:21], off offset:1664
	s_nop 0
	s_nop 0
	s_nop 0
	s_waitcnt vmcnt(18)
	v_mfma_f32_16x16x32_bf16 v[20:23], v[184:187], v[2:5], 0
	s_waitcnt vmcnt(17)
	v_mfma_f32_16x16x32_bf16 v[20:23], v[188:191], v[6:9], v[20:23]
	s_nop 0
	s_waitcnt vmcnt(16)
	v_mfma_f32_16x16x32_bf16 v[20:23], v[192:195], v[10:13], v[20:23]
	s_nop 0
	s_waitcnt vmcnt(15)
	v_mfma_f32_16x16x32_bf16 v[20:23], v[196:199], v[14:17], v[20:23]
	s_nop 0
	s_waitcnt vmcnt(14)
	s_nop 5
	v_pk_mul_f32 v[22:23], v[22:23], v[202:203]
	v_pk_mul_f32 v[20:21], v[20:21], v[200:201]
	s_nop 0
	v_cvt_pk_bf16_f32 v20, v20, v21
	v_cvt_pk_bf16_f32 v21, v22, v23
	global_store_dwordx2 v[18:19], v[20:21], off offset:1696
	s_nop 0
	s_nop 0
	s_nop 0
	s_waitcnt vmcnt(14)
	v_mfma_f32_16x16x32_bf16 v[20:23], v[204:207], v[2:5], 0
	s_waitcnt vmcnt(13)
	v_mfma_f32_16x16x32_bf16 v[20:23], v[222:225], v[6:9], v[20:23]
	s_nop 0
	s_waitcnt vmcnt(12)
	v_mfma_f32_16x16x32_bf16 v[20:23], v[226:229], v[10:13], v[20:23]
	s_nop 0
	s_waitcnt vmcnt(11)
	v_mfma_f32_16x16x32_bf16 v[20:23], v[230:233], v[14:17], v[20:23]
	s_nop 0
	s_waitcnt vmcnt(10)
	s_nop 5
	v_pk_mul_f32 v[22:23], v[22:23], v[236:237]
	v_pk_mul_f32 v[20:21], v[20:21], v[234:235]
	s_nop 0
	v_cvt_pk_bf16_f32 v20, v20, v21
	v_cvt_pk_bf16_f32 v21, v22, v23
	v_add_co_u32_e32 v22, vcc, 0x7000, v28
	global_store_dwordx2 v[18:19], v[20:21], off offset:1728
	s_nop 0
	v_addc_co_u32_e32 v23, vcc, 0, v29, vcc
	s_nop 0
	s_waitcnt vmcnt(10)
	v_mfma_f32_16x16x32_bf16 v[2:5], v[238:241], v[2:5], 0
	s_nop 0
	s_waitcnt vmcnt(9)
	v_mfma_f32_16x16x32_bf16 v[2:5], v[242:245], v[6:9], v[2:5]
	s_nop 0
	s_waitcnt vmcnt(8)
	v_mfma_f32_16x16x32_bf16 v[2:5], v[246:249], v[10:13], v[2:5]
	s_nop 0
	s_waitcnt vmcnt(7)
	v_mfma_f32_16x16x32_bf16 v[2:5], v[52:55], v[14:17], v[2:5]

.LBB0_588:
	s_and_b64 vcc, exec, s[0:1]
	s_cbranch_vccz .LBB0_590
	v_mov_b32_e32 v0, v209
	v_mov_b32_e32 v29, v1
	v_readfirstlane_b32 s0, v0
	s_ashr_i32 s0, s0, 2
	v_and_b32_e32 v21, 15, v0
	v_bfi_b32 v23, -16, s0, v0
	v_bfe_u32 v36, v0, 4, 2
	v_subrev_u32_e32 v0, s56, v23
	v_add_u32_e32 v18, s59, v0
	s_mov_b32 s0, 0x38e38e39
	v_mul_hi_i32 v0, v18, s0
	v_lshrrev_b32_e32 v2, 31, v0
	v_ashrrev_i32_e32 v0, 13, v0
	v_add_u32_e32 v0, v0, v2
	v_mul_i32_i24_e32 v0, 0x9000, v0
	v_sub_u32_e32 v0, v18, v0
	s_mov_b32 s0, 0x8000
	v_cmp_gt_i32_e32 vcc, s0, v0
	v_lshlrev_b32_e32 v28, 4, v36
	v_ashrrev_i32_e32 v19, 31, v18
	v_cndmask_b32_e32 v2, v220, v221, vcc
	v_and_b32_e32 v37, v2, v0
	v_cndmask_b32_e32 v31, v217, v210, vcc
	v_add_u32_e32 v2, -2, v37
	v_add_u32_e32 v3, 2, v37
	v_max_i32_e32 v0, 0, v2
	v_min_u32_e32 v3, v3, v31
	v_sub_u32_e32 v0, v3, v0
	v_cvt_f32_i32_e32 v0, v0
	v_add_u32_e32 v26, 1, v37
	v_lshlrev_b64 v[10:11], 10, v[18:19]
	v_lshlrev_b64 v[18:19], 11, v[18:19]
	v_div_scale_f32 v3, s[0:1], v0, v0, 1.0
	v_rcp_f32_e32 v4, v3
	v_readlane_b32 s0, v253, 62
	v_readlane_b32 s1, v253, 63
	v_fma_f32 v5, -v3, v4, 1.0
	v_fmac_f32_e32 v4, v5, v4
	v_div_scale_f32 v5, vcc, 1.0, v0, 1.0
	v_mul_f32_e32 v6, v5, v4
	v_fma_f32 v7, -v3, v6, v5
	v_fmac_f32_e32 v6, v7, v4
	v_fma_f32 v3, -v3, v6, v5
	v_div_fmas_f32 v3, v3, v4, v6
	v_cmp_lt_u32_e32 vcc, v2, v31
	v_add_u32_e32 v6, -1, v37
	v_lshl_add_u64 v[24:25], s[0:1], 0, v[28:29]
	v_cndmask_b32_e64 v22, 0, 1.0, vcc
	v_cndmask_b32_e32 v2, v37, v2, vcc
	v_cmp_lt_u32_e32 vcc, v6, v31
	v_add_u32_e32 v2, v23, v2
	v_subrev_u32_e32 v2, s56, v2
	v_cndmask_b32_e32 v6, v37, v6, vcc
	v_add_u32_e32 v6, v23, v6
	v_cmp_lt_u32_e64 s[0:1], v26, v31
	v_sub_u32_e32 v2, v2, v37
	v_subrev_u32_e32 v6, s56, v6
	v_cndmask_b32_e64 v26, v37, v26, s[0:1]
	v_add_u32_e32 v2, s59, v2
	v_sub_u32_e32 v6, v6, v37
	v_add_u32_e32 v23, v23, v26
	v_div_fixup_f32 v20, v3, v0, 1.0
	v_ashrrev_i32_e32 v3, 31, v2
	v_add_u32_e32 v6, s59, v6
	v_subrev_u32_e32 v23, s56, v23
	v_lshlrev_b64 v[2:3], 10, v[2:3]
	v_ashrrev_i32_e32 v7, 31, v6
	v_sub_u32_e32 v23, v23, v37
	v_lshl_add_u64 v[14:15], v[24:25], 0, v[2:3]
	v_lshlrev_b64 v[6:7], 10, v[6:7]
	v_add_u32_e32 v26, s59, v23
	global_load_dwordx4 v[2:5], v[14:15], off offset:256
	v_lshl_add_u64 v[34:35], v[24:25], 0, v[6:7]
	v_ashrrev_i32_e32 v27, 31, v26
	global_load_dwordx4 v[6:9], v[34:35], off offset:256
	v_lshl_add_u64 v[16:17], v[24:25], 0, v[10:11]
	v_lshlrev_b64 v[26:27], 10, v[26:27]
	global_load_dwordx4 v[10:13], v[16:17], off offset:256
	v_lshl_add_u64 v[32:33], v[24:25], 0, v[26:27]
	global_load_dwordx4 v[38:41], v[32:33], off offset:256
	global_load_dwordx4 v[92:95], v[14:15], off offset:320
	global_load_dwordx4 v[96:99], v[34:35], off offset:320
	global_load_dwordx4 v[100:103], v[16:17], off offset:320
	global_load_dwordx4 v[104:107], v[32:33], off offset:320
	global_load_dwordx4 v[108:111], v[14:15], off offset:384
	global_load_dwordx4 v[112:115], v[34:35], off offset:384
	global_load_dwordx4 v[116:119], v[16:17], off offset:384
	global_load_dwordx4 v[120:123], v[32:33], off offset:384
	global_load_dwordx4 v[124:127], v[14:15], off offset:448
	global_load_dwordx4 v[128:131], v[34:35], off offset:448
	global_load_dwordx4 v[132:135], v[16:17], off offset:448
	global_load_dwordx4 v[136:139], v[32:33], off offset:448
	v_cndmask_b32_e64 v30, 0, 1.0, vcc
	v_cmp_lt_u32_e32 vcc, v37, v31
	v_cndmask_b32_e64 v24, 0, 1.0, s[0:1]
	s_mov_b64 s[0:1], 0x400
	v_cndmask_b32_e64 v26, 0, 1.0, vcc
	v_lshlrev_b32_e32 v0, 3, v36
	s_waitcnt vmcnt(15)
	v_lshlrev_b32_e32 v42, 16, v2
	v_and_b32_e32 v43, 0xffff0000, v2
	v_pk_fma_f32 v[42:43], v[22:23], v[42:43], 0 op_sel_hi:[0, 1, 0]
	s_waitcnt vmcnt(14)
	v_lshlrev_b32_e32 v44, 16, v6
	v_and_b32_e32 v45, 0xffff0000, v6
	v_pk_fma_f32 v[42:43], v[30:31], v[44:45], v[42:43] op_sel_hi:[0, 1, 1]
	s_waitcnt vmcnt(13)
	v_lshlrev_b32_e32 v44, 16, v10
	v_and_b32_e32 v45, 0xffff0000, v10
	v_pk_fma_f32 v[42:43], v[26:27], v[44:45], v[42:43] op_sel_hi:[0, 1, 1]
	s_waitcnt vmcnt(12)
	v_lshlrev_b32_e32 v46, 16, v38
	v_and_b32_e32 v47, 0xffff0000, v38
	v_pk_fma_f32 v[42:43], v[24:25], v[46:47], v[42:43] op_sel_hi:[0, 1, 1]
	v_pk_fma_f32 v[42:43], v[20:21], v[42:43], v[44:45] op_sel_hi:[0, 1, 1] neg_lo:[0, 0, 1] neg_hi:[0, 0, 1]
	v_cvt_pk_bf16_f32 v2, v42, v43
	v_lshlrev_b32_e32 v42, 16, v3
	v_and_b32_e32 v43, 0xffff0000, v3
	v_pk_fma_f32 v[42:43], v[22:23], v[42:43], 0 op_sel_hi:[0, 1, 0]
	v_lshlrev_b32_e32 v6, 16, v7
	v_and_b32_e32 v7, 0xffff0000, v7
	v_pk_fma_f32 v[6:7], v[30:31], v[6:7], v[42:43] op_sel_hi:[0, 1, 1]
	v_lshlrev_b32_e32 v10, 16, v11
	v_and_b32_e32 v11, 0xffff0000, v11
	v_pk_fma_f32 v[6:7], v[26:27], v[10:11], v[6:7] op_sel_hi:[0, 1, 1]
	v_lshlrev_b32_e32 v38, 16, v39
	v_and_b32_e32 v39, 0xffff0000, v39
	v_pk_fma_f32 v[6:7], v[24:25], v[38:39], v[6:7] op_sel_hi:[0, 1, 1]
	v_pk_fma_f32 v[6:7], v[20:21], v[6:7], v[10:11] op_sel_hi:[0, 1, 1] neg_lo:[0, 0, 1] neg_hi:[0, 0, 1]
	v_cvt_pk_bf16_f32 v3, v6, v7
	v_lshlrev_b32_e32 v6, 16, v4
	v_and_b32_e32 v7, 0xffff0000, v4
	v_pk_fma_f32 v[6:7], v[22:23], v[6:7], 0 op_sel_hi:[0, 1, 0]
	v_lshlrev_b32_e32 v10, 16, v8
	v_and_b32_e32 v11, 0xffff0000, v8
	v_pk_fma_f32 v[6:7], v[30:31], v[10:11], v[6:7] op_sel_hi:[0, 1, 1]
	v_lshlrev_b32_e32 v10, 16, v12
	v_and_b32_e32 v11, 0xffff0000, v12
	v_pk_fma_f32 v[6:7], v[26:27], v[10:11], v[6:7] op_sel_hi:[0, 1, 1]
	v_lshlrev_b32_e32 v38, 16, v40
	v_and_b32_e32 v39, 0xffff0000, v40
	v_pk_fma_f32 v[6:7], v[24:25], v[38:39], v[6:7] op_sel_hi:[0, 1, 1]
	v_pk_fma_f32 v[6:7], v[20:21], v[6:7], v[10:11] op_sel_hi:[0, 1, 1] neg_lo:[0, 0, 1] neg_hi:[0, 0, 1]
	v_cvt_pk_bf16_f32 v4, v6, v7
	v_lshlrev_b32_e32 v6, 16, v5
	v_and_b32_e32 v7, 0xffff0000, v5
	v_pk_fma_f32 v[6:7], v[22:23], v[6:7], 0 op_sel_hi:[0, 1, 0]
	v_lshlrev_b32_e32 v8, 16, v9
	v_and_b32_e32 v9, 0xffff0000, v9
	v_pk_fma_f32 v[6:7], v[30:31], v[8:9], v[6:7] op_sel_hi:[0, 1, 1]
	v_lshlrev_b32_e32 v8, 16, v13
	v_and_b32_e32 v9, 0xffff0000, v13
	v_pk_fma_f32 v[6:7], v[26:27], v[8:9], v[6:7] op_sel_hi:[0, 1, 1]
	v_lshlrev_b32_e32 v10, 16, v41
	v_and_b32_e32 v11, 0xffff0000, v41
	v_pk_fma_f32 v[6:7], v[24:25], v[10:11], v[6:7] op_sel_hi:[0, 1, 1]
	v_pk_fma_f32 v[6:7], v[20:21], v[6:7], v[8:9] op_sel_hi:[0, 1, 1] neg_lo:[0, 0, 1] neg_hi:[0, 0, 1]
	v_cvt_pk_bf16_f32 v5, v6, v7
	s_nop 0
	s_nop 0
	s_nop 0
	s_nop 0
	s_waitcnt vmcnt(11)
	v_lshlrev_b32_e32 v46, 16, v92
	v_and_b32_e32 v47, 0xffff0000, v92
	v_pk_fma_f32 v[46:47], v[22:23], v[46:47], 0 op_sel_hi:[0, 1, 0]
	s_waitcnt vmcnt(10)
	v_lshlrev_b32_e32 v48, 16, v96
	v_and_b32_e32 v49, 0xffff0000, v96
	v_pk_fma_f32 v[46:47], v[30:31], v[48:49], v[46:47] op_sel_hi:[0, 1, 1]
	s_waitcnt vmcnt(9)
	v_lshlrev_b32_e32 v48, 16, v100
	v_and_b32_e32 v49, 0xffff0000, v100
	v_pk_fma_f32 v[46:47], v[26:27], v[48:49], v[46:47] op_sel_hi:[0, 1, 1]
	s_waitcnt vmcnt(8)
	v_lshlrev_b32_e32 v50, 16, v104
	v_and_b32_e32 v51, 0xffff0000, v104
	v_pk_fma_f32 v[46:47], v[24:25], v[50:51], v[46:47] op_sel_hi:[0, 1, 1]
	v_pk_fma_f32 v[46:47], v[20:21], v[46:47], v[48:49] op_sel_hi:[0, 1, 1] neg_lo:[0, 0, 1] neg_hi:[0, 0, 1]
	v_lshlrev_b32_e32 v10, 16, v93
	v_and_b32_e32 v11, 0xffff0000, v93
	v_cvt_pk_bf16_f32 v6, v46, v47
	v_pk_fma_f32 v[10:11], v[22:23], v[10:11], 0 op_sel_hi:[0, 1, 0]
	v_lshlrev_b32_e32 v46, 16, v97
	v_and_b32_e32 v47, 0xffff0000, v97
	v_pk_fma_f32 v[10:11], v[30:31], v[46:47], v[10:11] op_sel_hi:[0, 1, 1]
	v_lshlrev_b32_e32 v38, 16, v101
	v_and_b32_e32 v39, 0xffff0000, v101
	v_pk_fma_f32 v[10:11], v[26:27], v[38:39], v[10:11] op_sel_hi:[0, 1, 1]
	v_lshlrev_b32_e32 v42, 16, v105
	v_and_b32_e32 v43, 0xffff0000, v105
	v_pk_fma_f32 v[10:11], v[24:25], v[42:43], v[10:11] op_sel_hi:[0, 1, 1]
	v_pk_fma_f32 v[10:11], v[20:21], v[10:11], v[38:39] op_sel_hi:[0, 1, 1] neg_lo:[0, 0, 1] neg_hi:[0, 0, 1]
	v_cvt_pk_bf16_f32 v7, v10, v11
	v_lshlrev_b32_e32 v10, 16, v94
	v_and_b32_e32 v11, 0xffff0000, v94
	v_pk_fma_f32 v[10:11], v[22:23], v[10:11], 0 op_sel_hi:[0, 1, 0]
	v_lshlrev_b32_e32 v38, 16, v98
	v_and_b32_e32 v39, 0xffff0000, v98
	v_pk_fma_f32 v[10:11], v[30:31], v[38:39], v[10:11] op_sel_hi:[0, 1, 1]
	v_lshlrev_b32_e32 v38, 16, v102
	v_and_b32_e32 v39, 0xffff0000, v102
	v_pk_fma_f32 v[10:11], v[26:27], v[38:39], v[10:11] op_sel_hi:[0, 1, 1]
	v_lshlrev_b32_e32 v42, 16, v106
	v_and_b32_e32 v43, 0xffff0000, v106
	v_pk_fma_f32 v[10:11], v[24:25], v[42:43], v[10:11] op_sel_hi:[0, 1, 1]
	v_pk_fma_f32 v[10:11], v[20:21], v[10:11], v[38:39] op_sel_hi:[0, 1, 1] neg_lo:[0, 0, 1] neg_hi:[0, 0, 1]
	v_cvt_pk_bf16_f32 v8, v10, v11
	v_lshlrev_b32_e32 v10, 16, v95
	v_and_b32_e32 v11, 0xffff0000, v95
	v_pk_fma_f32 v[10:11], v[22:23], v[10:11], 0 op_sel_hi:[0, 1, 0]
	v_lshlrev_b32_e32 v12, 16, v99
	v_and_b32_e32 v13, 0xffff0000, v99
	v_pk_fma_f32 v[10:11], v[30:31], v[12:13], v[10:11] op_sel_hi:[0, 1, 1]
	v_lshlrev_b32_e32 v12, 16, v103
	v_and_b32_e32 v13, 0xffff0000, v103
	v_pk_fma_f32 v[10:11], v[26:27], v[12:13], v[10:11] op_sel_hi:[0, 1, 1]
	v_lshlrev_b32_e32 v38, 16, v107
	v_and_b32_e32 v39, 0xffff0000, v107
	v_pk_fma_f32 v[10:11], v[24:25], v[38:39], v[10:11] op_sel_hi:[0, 1, 1]
	v_pk_fma_f32 v[10:11], v[20:21], v[10:11], v[12:13] op_sel_hi:[0, 1, 1] neg_lo:[0, 0, 1] neg_hi:[0, 0, 1]
	v_cvt_pk_bf16_f32 v9, v10, v11
	s_nop 0
	s_nop 0
	s_nop 0
	s_nop 0
	s_waitcnt vmcnt(7)
	v_lshlrev_b32_e32 v50, 16, v108
	v_and_b32_e32 v51, 0xffff0000, v108
	v_pk_fma_f32 v[50:51], v[22:23], v[50:51], 0 op_sel_hi:[0, 1, 0]
	s_waitcnt vmcnt(6)
	v_lshlrev_b32_e32 v52, 16, v112
	v_and_b32_e32 v53, 0xffff0000, v112
	v_pk_fma_f32 v[50:51], v[30:31], v[52:53], v[50:51] op_sel_hi:[0, 1, 1]
	s_waitcnt vmcnt(5)
	v_lshlrev_b32_e32 v52, 16, v116
	v_and_b32_e32 v53, 0xffff0000, v116
	v_pk_fma_f32 v[50:51], v[26:27], v[52:53], v[50:51] op_sel_hi:[0, 1, 1]
	s_waitcnt vmcnt(4)
	v_lshlrev_b32_e32 v54, 16, v120
	v_and_b32_e32 v55, 0xffff0000, v120
	v_pk_fma_f32 v[50:51], v[24:25], v[54:55], v[50:51] op_sel_hi:[0, 1, 1]
	v_pk_fma_f32 v[50:51], v[20:21], v[50:51], v[52:53] op_sel_hi:[0, 1, 1] neg_lo:[0, 0, 1] neg_hi:[0, 0, 1]
	v_cvt_pk_bf16_f32 v10, v50, v51
	v_lshlrev_b32_e32 v50, 16, v109
	v_and_b32_e32 v51, 0xffff0000, v109
	v_pk_fma_f32 v[50:51], v[22:23], v[50:51], 0 op_sel_hi:[0, 1, 0]
	v_lshlrev_b32_e32 v38, 16, v113
	v_and_b32_e32 v39, 0xffff0000, v113
	v_pk_fma_f32 v[38:39], v[30:31], v[38:39], v[50:51] op_sel_hi:[0, 1, 1]
	v_lshlrev_b32_e32 v42, 16, v117
	v_and_b32_e32 v43, 0xffff0000, v117
	v_pk_fma_f32 v[38:39], v[26:27], v[42:43], v[38:39] op_sel_hi:[0, 1, 1]
	v_lshlrev_b32_e32 v46, 16, v121
	v_and_b32_e32 v47, 0xffff0000, v121
	v_pk_fma_f32 v[38:39], v[24:25], v[46:47], v[38:39] op_sel_hi:[0, 1, 1]
	v_pk_fma_f32 v[38:39], v[20:21], v[38:39], v[42:43] op_sel_hi:[0, 1, 1] neg_lo:[0, 0, 1] neg_hi:[0, 0, 1]
	v_cvt_pk_bf16_f32 v11, v38, v39
	v_lshlrev_b32_e32 v38, 16, v110
	v_and_b32_e32 v39, 0xffff0000, v110
	v_pk_fma_f32 v[38:39], v[22:23], v[38:39], 0 op_sel_hi:[0, 1, 0]
	v_lshlrev_b32_e32 v42, 16, v114
	v_and_b32_e32 v43, 0xffff0000, v114
	v_pk_fma_f32 v[38:39], v[30:31], v[42:43], v[38:39] op_sel_hi:[0, 1, 1]
	v_lshlrev_b32_e32 v42, 16, v118
	v_and_b32_e32 v43, 0xffff0000, v118
	v_pk_fma_f32 v[38:39], v[26:27], v[42:43], v[38:39] op_sel_hi:[0, 1, 1]
	v_lshlrev_b32_e32 v46, 16, v122
	v_and_b32_e32 v47, 0xffff0000, v122
	v_pk_fma_f32 v[38:39], v[24:25], v[46:47], v[38:39] op_sel_hi:[0, 1, 1]
	v_pk_fma_f32 v[38:39], v[20:21], v[38:39], v[42:43] op_sel_hi:[0, 1, 1] neg_lo:[0, 0, 1] neg_hi:[0, 0, 1]
	v_cvt_pk_bf16_f32 v12, v38, v39
	v_lshlrev_b32_e32 v38, 16, v111
	v_and_b32_e32 v39, 0xffff0000, v111
	v_pk_fma_f32 v[38:39], v[22:23], v[38:39], 0 op_sel_hi:[0, 1, 0]
	v_lshlrev_b32_e32 v40, 16, v115
	v_and_b32_e32 v41, 0xffff0000, v115
	v_pk_fma_f32 v[38:39], v[30:31], v[40:41], v[38:39] op_sel_hi:[0, 1, 1]
	v_lshlrev_b32_e32 v40, 16, v119
	v_and_b32_e32 v41, 0xffff0000, v119
	v_pk_fma_f32 v[38:39], v[26:27], v[40:41], v[38:39] op_sel_hi:[0, 1, 1]
	v_lshlrev_b32_e32 v42, 16, v123
	v_and_b32_e32 v43, 0xffff0000, v123
	v_pk_fma_f32 v[38:39], v[24:25], v[42:43], v[38:39] op_sel_hi:[0, 1, 1]
	v_pk_fma_f32 v[38:39], v[20:21], v[38:39], v[40:41] op_sel_hi:[0, 1, 1] neg_lo:[0, 0, 1] neg_hi:[0, 0, 1]
	v_cvt_pk_bf16_f32 v13, v38, v39
	s_nop 0
	s_nop 0
	s_nop 0
	s_nop 0
	s_nop 0
	s_nop 0
	s_waitcnt vmcnt(3)
	v_lshlrev_b32_e32 v46, 16, v124
	v_and_b32_e32 v47, 0xffff0000, v124
	v_lshlrev_b32_e32 v38, 16, v125
	v_and_b32_e32 v39, 0xffff0000, v125
	s_waitcnt vmcnt(2)
	v_lshlrev_b32_e32 v48, 16, v128
	v_and_b32_e32 v49, 0xffff0000, v128
	v_pk_fma_f32 v[38:39], v[22:23], v[38:39], 0 op_sel_hi:[0, 1, 0]
	v_lshlrev_b32_e32 v42, 16, v129
	v_and_b32_e32 v43, 0xffff0000, v129
	v_pk_fma_f32 v[38:39], v[30:31], v[42:43], v[38:39] op_sel_hi:[0, 1, 1]
	s_waitcnt vmcnt(1)
	v_lshlrev_b32_e32 v42, 16, v133
	v_and_b32_e32 v43, 0xffff0000, v133
	s_waitcnt vmcnt(0)
	v_lshlrev_b32_e32 v50, 16, v136
	v_and_b32_e32 v51, 0xffff0000, v136
	v_pk_fma_f32 v[38:39], v[26:27], v[42:43], v[38:39] op_sel_hi:[0, 1, 1]
	v_lshlrev_b32_e32 v32, 16, v137
	v_and_b32_e32 v33, 0xffff0000, v137
	v_pk_fma_f32 v[32:33], v[24:25], v[32:33], v[38:39] op_sel_hi:[0, 1, 1]
	v_pk_fma_f32 v[32:33], v[20:21], v[32:33], v[42:43] op_sel_hi:[0, 1, 1] neg_lo:[0, 0, 1] neg_hi:[0, 0, 1]
	v_cvt_pk_bf16_f32 v15, v32, v33
	v_lshlrev_b32_e32 v32, 16, v126
	v_and_b32_e32 v33, 0xffff0000, v126
	v_pk_fma_f32 v[32:33], v[22:23], v[32:33], 0 op_sel_hi:[0, 1, 0]
	v_lshlrev_b32_e32 v38, 16, v130
	v_and_b32_e32 v39, 0xffff0000, v130
	v_pk_fma_f32 v[32:33], v[30:31], v[38:39], v[32:33] op_sel_hi:[0, 1, 1]
	v_lshlrev_b32_e32 v38, 16, v134
	v_and_b32_e32 v39, 0xffff0000, v134
	v_pk_fma_f32 v[32:33], v[26:27], v[38:39], v[32:33] op_sel_hi:[0, 1, 1]
	v_lshlrev_b32_e32 v42, 16, v138
	v_and_b32_e32 v43, 0xffff0000, v138
	v_pk_fma_f32 v[32:33], v[24:25], v[42:43], v[32:33] op_sel_hi:[0, 1, 1]
	v_pk_fma_f32 v[32:33], v[20:21], v[32:33], v[38:39] op_sel_hi:[0, 1, 1] neg_lo:[0, 0, 1] neg_hi:[0, 0, 1]
	v_cvt_pk_bf16_f32 v16, v32, v33
	v_lshlrev_b32_e32 v32, 16, v127
	v_and_b32_e32 v33, 0xffff0000, v127
	v_pk_fma_f32 v[46:47], v[22:23], v[46:47], 0 op_sel_hi:[0, 1, 0]
	v_pk_fma_f32 v[22:23], v[22:23], v[32:33], 0 op_sel_hi:[0, 1, 0]
	v_lshlrev_b32_e32 v32, 16, v131
	v_and_b32_e32 v33, 0xffff0000, v131
	v_pk_fma_f32 v[46:47], v[30:31], v[48:49], v[46:47] op_sel_hi:[0, 1, 1]
	v_lshlrev_b32_e32 v48, 16, v132
	v_and_b32_e32 v49, 0xffff0000, v132
	v_pk_fma_f32 v[22:23], v[30:31], v[32:33], v[22:23] op_sel_hi:[0, 1, 1]
	v_lshlrev_b32_e32 v30, 16, v135
	v_and_b32_e32 v31, 0xffff0000, v135
	v_pk_fma_f32 v[46:47], v[26:27], v[48:49], v[46:47] op_sel_hi:[0, 1, 1]
	v_pk_fma_f32 v[22:23], v[26:27], v[30:31], v[22:23] op_sel_hi:[0, 1, 1]
	v_lshlrev_b32_e32 v26, 16, v139
	v_and_b32_e32 v27, 0xffff0000, v139
	v_pk_fma_f32 v[22:23], v[24:25], v[26:27], v[22:23] op_sel_hi:[0, 1, 1]
	v_pk_fma_f32 v[22:23], v[20:21], v[22:23], v[30:31] op_sel_hi:[0, 1, 1] neg_lo:[0, 0, 1] neg_hi:[0, 0, 1]
	v_cvt_pk_bf16_f32 v17, v22, v23
	v_lshl_add_u64 v[22:23], s[36:37], 0, v[28:29]
	v_lshl_add_u64 v[32:33], s[84:85], 0, v[18:19]
	v_lshlrev_b32_e32 v18, 8, v21
	v_mov_b32_e32 v19, v1
	v_pk_fma_f32 v[46:47], v[24:25], v[50:51], v[46:47] op_sel_hi:[0, 1, 1]
	v_lshl_add_u64 v[30:31], v[22:23], 0, v[18:19]
	v_pk_fma_f32 v[46:47], v[20:21], v[46:47], v[48:49] op_sel_hi:[0, 1, 1] neg_lo:[0, 0, 1] neg_hi:[0, 0, 1]
	v_add_co_u32_e32 v56, vcc, 0x1000, v30
	s_nop 1
	v_addc_co_u32_e32 v57, vcc, 0, v31, vcc
	v_add_co_u32_e32 v58, vcc, 0x3000, v30
	s_nop 1
	v_addc_co_u32_e32 v59, vcc, 0, v31, vcc
	v_add_co_u32_e32 v60, vcc, 0x5000, v30
	s_nop 1
	v_addc_co_u32_e32 v61, vcc, 0, v31, vcc
	v_add_co_u32_e32 v62, vcc, 0x7000, v30
	s_nop 1
	v_addc_co_u32_e32 v63, vcc, 0, v31, vcc
	global_load_dwordx4 v[84:87], v[56:57], off offset:-4096
	global_load_dwordx4 v[88:91], v[56:57], off offset:-4032
	global_load_dwordx4 v[92:95], v[56:57], off offset:-3968
	global_load_dwordx4 v[96:99], v[56:57], off offset:-3904
	global_load_dwordx4 v[100:103], v28, s[30:31] offset:512
	global_load_dwordx4 v[104:107], v[56:57], off
	global_load_dwordx4 v[108:111], v[56:57], off offset:64
	global_load_dwordx4 v[112:115], v[56:57], off offset:128
	global_load_dwordx4 v[116:119], v[56:57], off offset:192
	global_load_dwordx4 v[120:123], v28, s[30:31] offset:576
	global_load_dwordx4 v[124:127], v[58:59], off offset:-4096
	global_load_dwordx4 v[128:131], v[58:59], off offset:-4032
	global_load_dwordx4 v[132:135], v[58:59], off offset:-3968
	global_load_dwordx4 v[136:139], v[58:59], off offset:-3904
	global_load_dwordx4 v[140:143], v28, s[30:31] offset:640
	global_load_dwordx4 v[144:147], v[58:59], off
	global_load_dwordx4 v[148:151], v[58:59], off offset:64
	global_load_dwordx4 v[152:155], v[58:59], off offset:128
	global_load_dwordx4 v[156:159], v[58:59], off offset:192
	global_load_dwordx4 v[160:163], v28, s[30:31] offset:704
	global_load_dwordx4 v[164:167], v[60:61], off offset:-4096
	global_load_dwordx4 v[168:171], v[60:61], off offset:-4032
	global_load_dwordx4 v[172:175], v[60:61], off offset:-3968
	global_load_dwordx4 v[176:179], v[60:61], off offset:-3904
	global_load_dwordx4 v[180:183], v28, s[30:31] offset:768
	global_load_dwordx4 v[184:187], v[60:61], off
	global_load_dwordx4 v[188:191], v[60:61], off offset:64
	global_load_dwordx4 v[192:195], v[60:61], off offset:128
	global_load_dwordx4 v[196:199], v[60:61], off offset:192
	global_load_dwordx4 v[200:203], v28, s[30:31] offset:832
	global_load_dwordx4 v[204:207], v[62:63], off offset:-4096
	global_load_dwordx4 v[222:225], v[62:63], off offset:-4032
	global_load_dwordx4 v[226:229], v[62:63], off offset:-3968
	global_load_dwordx4 v[230:233], v[62:63], off offset:-3904
	global_load_dwordx4 v[234:237], v28, s[30:31] offset:896
	global_load_dwordx4 v[238:241], v[62:63], off
	global_load_dwordx4 v[242:245], v[62:63], off offset:64
	global_load_dwordx4 v[246:249], v[62:63], off offset:128
	global_load_dwordx4 v[52:55], v[62:63], off offset:192
	s_nop 0
	s_nop 0
	s_waitcnt vmcnt(38)
	v_mfma_f32_16x16x32_bf16 v[18:21], v[84:87], v[2:5], 0
	v_cvt_pk_bf16_f32 v14, v46, v47
	v_lshl_add_u64 v[26:27], v[32:33], 0, s[0:1]
	s_movk_i32 s0, 0x1000
	s_waitcnt vmcnt(37)
	v_mfma_f32_16x16x32_bf16 v[18:21], v[88:91], v[6:9], v[18:21]
	s_nop 0
	s_waitcnt vmcnt(36)
	v_mfma_f32_16x16x32_bf16 v[18:21], v[92:95], v[10:13], v[18:21]
	s_nop 0
	s_waitcnt vmcnt(35)
	v_mfma_f32_16x16x32_bf16 v[18:21], v[96:99], v[14:17], v[18:21]
	s_nop 0
	s_waitcnt vmcnt(34)
	s_nop 5
	v_pk_mul_f32 v[20:21], v[20:21], v[102:103]
	v_add_co_u32_e32 v24, vcc, s0, v30
	v_pk_mul_f32 v[18:19], v[18:19], v[100:101]
	s_nop 0
	v_addc_co_u32_e32 v25, vcc, 0, v31, vcc
	s_movk_i32 s0, 0x2000
	v_cvt_pk_bf16_f32 v22, v18, v19
	v_cvt_pk_bf16_f32 v23, v20, v21
	v_lshl_add_u64 v[18:19], v[32:33], 0, v[0:1]
	v_add_co_u32_e32 v38, vcc, s0, v30
	global_store_dwordx2 v[18:19], v[22:23], off offset:1280
	s_nop 0
	v_addc_co_u32_e32 v39, vcc, 0, v31, vcc
	s_nop 0
	s_nop 0
	s_waitcnt vmcnt(34)
	v_mfma_f32_16x16x32_bf16 v[20:23], v[104:107], v[2:5], 0
	s_movk_i32 s0, 0x3000
	v_mov_b32_e32 v0, 0xf0
	v_lshl_or_b32 v0, v36, 2, v0
	s_waitcnt vmcnt(33)
	v_mfma_f32_16x16x32_bf16 v[20:23], v[108:111], v[6:9], v[20:23]
	s_nop 0
	s_waitcnt vmcnt(32)
	v_mfma_f32_16x16x32_bf16 v[20:23], v[112:115], v[10:13], v[20:23]
	s_nop 0
	v_add_co_u32_e32 v24, vcc, s0, v30
	s_waitcnt vmcnt(31)
	v_mfma_f32_16x16x32_bf16 v[20:23], v[116:119], v[14:17], v[20:23]
	s_nop 0
	v_addc_co_u32_e32 v25, vcc, 0, v31, vcc
	s_movk_i32 s0, 0x4000
	s_waitcnt vmcnt(30)
	s_nop 3
	v_pk_mul_f32 v[22:23], v[22:23], v[122:123]
	v_pk_mul_f32 v[20:21], v[20:21], v[120:121]
	s_nop 0
	v_cvt_pk_bf16_f32 v20, v20, v21
	v_cvt_pk_bf16_f32 v21, v22, v23
	global_store_dwordx2 v[18:19], v[20:21], off offset:1312
	s_nop 0
	s_nop 0
	s_nop 0
	s_waitcnt vmcnt(30)
	v_mfma_f32_16x16x32_bf16 v[20:23], v[124:127], v[2:5], 0
	s_waitcnt vmcnt(29)
	v_mfma_f32_16x16x32_bf16 v[20:23], v[128:131], v[6:9], v[20:23]
	s_nop 0
	s_waitcnt vmcnt(28)
	v_mfma_f32_16x16x32_bf16 v[20:23], v[132:135], v[10:13], v[20:23]
	s_nop 0
	v_add_co_u32_e32 v38, vcc, s0, v30
	s_waitcnt vmcnt(27)
	v_mfma_f32_16x16x32_bf16 v[20:23], v[136:139], v[14:17], v[20:23]
	s_nop 0
	v_addc_co_u32_e32 v39, vcc, 0, v31, vcc
	s_movk_i32 s0, 0x5000
	s_waitcnt vmcnt(26)
	s_nop 3
	v_pk_mul_f32 v[22:23], v[22:23], v[142:143]
	v_pk_mul_f32 v[20:21], v[20:21], v[140:141]
	s_nop 0
	v_cvt_pk_bf16_f32 v20, v20, v21
	v_cvt_pk_bf16_f32 v21, v22, v23
	global_store_dwordx2 v[18:19], v[20:21], off offset:1344
	s_nop 0
	s_nop 0
	s_nop 0
	s_waitcnt vmcnt(26)
	v_mfma_f32_16x16x32_bf16 v[20:23], v[144:147], v[2:5], 0
	s_waitcnt vmcnt(25)
	v_mfma_f32_16x16x32_bf16 v[20:23], v[148:151], v[6:9], v[20:23]
	s_nop 0
	s_waitcnt vmcnt(24)
	v_mfma_f32_16x16x32_bf16 v[20:23], v[152:155], v[10:13], v[20:23]
	s_nop 0
	v_add_co_u32_e32 v24, vcc, s0, v30
	s_waitcnt vmcnt(23)
	v_mfma_f32_16x16x32_bf16 v[20:23], v[156:159], v[14:17], v[20:23]
	s_nop 0
	v_addc_co_u32_e32 v25, vcc, 0, v31, vcc
	s_movk_i32 s0, 0x6000
	s_waitcnt vmcnt(22)
	s_nop 3
	v_pk_mul_f32 v[22:23], v[22:23], v[162:163]
	v_pk_mul_f32 v[20:21], v[20:21], v[160:161]
	s_nop 0
	v_cvt_pk_bf16_f32 v20, v20, v21
	v_cvt_pk_bf16_f32 v21, v22, v23
	global_store_dwordx2 v[18:19], v[20:21], off offset:1376
	s_nop 0
	s_nop 0
	s_nop 0
	s_waitcnt vmcnt(22)
	v_mfma_f32_16x16x32_bf16 v[20:23], v[164:167], v[2:5], 0
	s_waitcnt vmcnt(21)
	v_mfma_f32_16x16x32_bf16 v[20:23], v[168:171], v[6:9], v[20:23]
	s_nop 0
	s_waitcnt vmcnt(20)
	v_mfma_f32_16x16x32_bf16 v[20:23], v[172:175], v[10:13], v[20:23]
	s_nop 0
	v_add_co_u32_e32 v38, vcc, s0, v30
	s_waitcnt vmcnt(19)
	v_mfma_f32_16x16x32_bf16 v[20:23], v[176:179], v[14:17], v[20:23]
	s_nop 0
	v_addc_co_u32_e32 v39, vcc, 0, v31, vcc
	s_waitcnt vmcnt(18)
	s_nop 4
	v_pk_mul_f32 v[22:23], v[22:23], v[182:183]
	v_pk_mul_f32 v[20:21], v[20:21], v[180:181]
	s_nop 0
	v_cvt_pk_bf16_f32 v20, v20, v21
	v_cvt_pk_bf16_f32 v21, v22, v23
	global_store_dwordx2 v[18:19], v[20:21], off offset:1408
	s_nop 0
	s_nop 0
	s_nop 0
	s_waitcnt vmcnt(18)
	v_mfma_f32_16x16x32_bf16 v[20:23], v[184:187], v[2:5], 0
	s_waitcnt vmcnt(17)
	v_mfma_f32_16x16x32_bf16 v[20:23], v[188:191], v[6:9], v[20:23]
	s_nop 0
	s_waitcnt vmcnt(16)
	v_mfma_f32_16x16x32_bf16 v[20:23], v[192:195], v[10:13], v[20:23]
	s_nop 0
	s_waitcnt vmcnt(15)
	v_mfma_f32_16x16x32_bf16 v[20:23], v[196:199], v[14:17], v[20:23]
	s_nop 0
	s_waitcnt vmcnt(14)
	s_nop 5
	v_pk_mul_f32 v[22:23], v[22:23], v[202:203]
	v_pk_mul_f32 v[20:21], v[20:21], v[200:201]
	s_nop 0
	v_cvt_pk_bf16_f32 v20, v20, v21
	v_cvt_pk_bf16_f32 v21, v22, v23
	global_store_dwordx2 v[18:19], v[20:21], off offset:1440
	s_nop 0
	s_nop 0
	s_nop 0
	s_waitcnt vmcnt(14)
	v_mfma_f32_16x16x32_bf16 v[20:23], v[204:207], v[2:5], 0
	s_waitcnt vmcnt(13)
	v_mfma_f32_16x16x32_bf16 v[20:23], v[222:225], v[6:9], v[20:23]
	s_nop 0
	s_waitcnt vmcnt(12)
	v_mfma_f32_16x16x32_bf16 v[20:23], v[226:229], v[10:13], v[20:23]
	s_nop 0
	s_waitcnt vmcnt(11)
	v_mfma_f32_16x16x32_bf16 v[20:23], v[230:233], v[14:17], v[20:23]
	s_nop 0
	s_waitcnt vmcnt(10)
	s_nop 5
	v_pk_mul_f32 v[22:23], v[22:23], v[236:237]
	v_pk_mul_f32 v[20:21], v[20:21], v[234:235]
	s_nop 0
	v_cvt_pk_bf16_f32 v20, v20, v21
	v_cvt_pk_bf16_f32 v21, v22, v23
	v_add_co_u32_e32 v22, vcc, 0x7000, v30
	global_store_dwordx2 v[18:19], v[20:21], off offset:1472
	s_nop 0
	v_addc_co_u32_e32 v23, vcc, 0, v31, vcc
	s_nop 0
	s_waitcnt vmcnt(10)
	v_mfma_f32_16x16x32_bf16 v[2:5], v[238:241], v[2:5], 0
	s_nop 0
	s_waitcnt vmcnt(9)
	v_mfma_f32_16x16x32_bf16 v[2:5], v[242:245], v[6:9], v[2:5]
	s_nop 0
	s_waitcnt vmcnt(8)
	v_mfma_f32_16x16x32_bf16 v[2:5], v[246:249], v[10:13], v[2:5]
	s_nop 0
	s_waitcnt vmcnt(7)
	v_mfma_f32_16x16x32_bf16 v[2:5], v[52:55], v[14:17], v[2:5]

.LBB0_592:
	v_mov_b32_e32 v0, v209
	s_mul_i32 s6, s56, s16
	v_readfirstlane_b32 s0, v0
	s_ashr_i32 s0, s0, 2
	v_and_b32_e32 v85, 15, v0
	v_bfi_b32 v64, -16, s0, v0
	v_bfe_u32 v83, v0, 4, 2
	v_subrev_u32_e32 v0, s6, v64
	v_add_u32_e32 v80, s59, v0
	s_mov_b32 s0, 0x38e38e39
	v_mul_hi_i32 v0, v80, s0
	v_lshrrev_b32_e32 v2, 31, v0
	v_ashrrev_i32_e32 v0, 13, v0
	v_add_u32_e32 v0, v0, v2
	v_mul_i32_i24_e32 v0, 0x9000, v0
	v_sub_u32_e32 v0, v80, v0
	s_mov_b32 s0, 0x8000
	v_cmp_gt_i32_e32 vcc, s0, v0
	v_lshlrev_b32_e32 v78, 4, v83
	v_mov_b32_e32 v79, v1
	v_cndmask_b32_e32 v2, v220, v221, vcc
	v_and_b32_e32 v88, v2, v0
	v_cndmask_b32_e32 v87, v217, v210, vcc
	v_add_u32_e32 v4, -8, v88
	v_add_u32_e32 v2, 8, v88
	v_max_i32_e32 v0, 0, v4
	v_min_u32_e32 v2, v2, v87
	v_sub_u32_e32 v0, v2, v0
	v_cvt_f32_i32_e32 v0, v0
	v_add_u32_e32 v10, 1, v88
	v_add_u32_e32 v50, 4, v88
	v_cmp_lt_u32_e64 s[14:15], v50, v87
	v_div_scale_f32 v2, s[0:1], v0, v0, 1.0
	v_rcp_f32_e32 v3, v2
	v_readlane_b32 s0, v253, 62
	v_readlane_b32 s1, v253, 63
	v_add_u32_e32 v54, 5, v88
	v_fma_f32 v5, -v2, v3, 1.0
	v_fmac_f32_e32 v3, v5, v3
	v_div_scale_f32 v5, vcc, 1.0, v0, 1.0
	v_mul_f32_e32 v6, v5, v3
	v_fma_f32 v7, -v2, v6, v5
	v_fmac_f32_e32 v6, v7, v3
	v_fma_f32 v2, -v2, v6, v5
	v_div_fmas_f32 v2, v2, v3, v6
	v_cmp_lt_u32_e32 vcc, v4, v87
	v_lshl_add_u64 v[62:63], s[0:1], 0, v[78:79]
	v_cmp_lt_u32_e64 s[0:1], v10, v87
	v_cndmask_b32_e32 v4, v88, v4, vcc
	v_add_u32_e32 v4, v64, v4
	v_subrev_u32_e32 v4, s6, v4
	v_sub_u32_e32 v4, v4, v88
	v_add_u32_e32 v4, s59, v4
	v_ashrrev_i32_e32 v5, 31, v4
	v_lshlrev_b64 v[4:5], 10, v[4:5]
	v_lshl_add_u64 v[126:127], v[62:63], 0, v[4:5]
	v_add_u32_e32 v4, -7, v88
	v_cmp_lt_u32_e64 s[8:9], v4, v87
	v_cndmask_b32_e64 v10, v88, v10, s[0:1]
	v_add_u32_e32 v10, v64, v10
	v_cndmask_b32_e64 v4, v88, v4, s[8:9]
	v_add_u32_e32 v4, v64, v4
	v_subrev_u32_e32 v4, s6, v4
	v_sub_u32_e32 v4, v4, v88
	v_add_u32_e32 v4, s59, v4
	v_ashrrev_i32_e32 v5, 31, v4
	v_lshlrev_b64 v[4:5], 10, v[4:5]
	v_lshl_add_u64 v[128:129], v[62:63], 0, v[4:5]
	v_add_u32_e32 v4, -6, v88
	v_cmp_lt_u32_e64 s[12:13], v4, v87
	v_subrev_u32_e32 v10, s6, v10
	v_sub_u32_e32 v10, v10, v88
	v_cndmask_b32_e64 v4, v88, v4, s[12:13]
	v_add_u32_e32 v4, v64, v4
	v_subrev_u32_e32 v4, s6, v4
	v_sub_u32_e32 v4, v4, v88
	v_add_u32_e32 v4, s59, v4
	v_ashrrev_i32_e32 v5, 31, v4
	v_lshlrev_b64 v[4:5], 10, v[4:5]
	v_lshl_add_u64 v[130:131], v[62:63], 0, v[4:5]
	v_add_u32_e32 v4, -5, v88
	v_cmp_lt_u32_e64 s[16:17], v4, v87
	v_add_u32_e32 v10, s59, v10
	v_ashrrev_i32_e32 v11, 31, v10
	v_cndmask_b32_e64 v4, v88, v4, s[16:17]
	v_add_u32_e32 v4, v64, v4
	v_subrev_u32_e32 v4, s6, v4
	v_sub_u32_e32 v4, v4, v88
	v_add_u32_e32 v4, s59, v4
	v_ashrrev_i32_e32 v5, 31, v4
	v_lshlrev_b64 v[4:5], 10, v[4:5]
	v_lshl_add_u64 v[132:133], v[62:63], 0, v[4:5]
	v_add_u32_e32 v4, -4, v88
	v_cmp_lt_u32_e64 s[20:21], v4, v87
	v_lshlrev_b64 v[10:11], 10, v[10:11]
	v_lshl_add_u64 v[76:77], v[62:63], 0, v[10:11]
	v_cndmask_b32_e64 v4, v88, v4, s[20:21]
	v_add_u32_e32 v4, v64, v4
	v_subrev_u32_e32 v4, s6, v4
	v_sub_u32_e32 v4, v4, v88
	v_add_u32_e32 v4, s59, v4
	v_ashrrev_i32_e32 v5, 31, v4
	v_lshlrev_b64 v[4:5], 10, v[4:5]
	v_lshl_add_u64 v[134:135], v[62:63], 0, v[4:5]
	v_add_u32_e32 v4, -3, v88
	v_cmp_lt_u32_e64 s[24:25], v4, v87
	v_add_u32_e32 v10, 2, v88
	global_load_dwordx4 v[6:9], v[126:127], off offset:768
	v_cndmask_b32_e64 v4, v88, v4, s[24:25]
	v_add_u32_e32 v4, v64, v4
	v_subrev_u32_e32 v4, s6, v4
	v_sub_u32_e32 v4, v4, v88
	v_add_u32_e32 v4, s59, v4
	v_ashrrev_i32_e32 v5, 31, v4
	v_lshlrev_b64 v[4:5], 10, v[4:5]
	v_lshl_add_u64 v[136:137], v[62:63], 0, v[4:5]
	v_add_u32_e32 v4, -2, v88
	v_cmp_lt_u32_e64 s[28:29], v4, v87
	v_cmp_lt_u32_e64 s[4:5], v10, v87
	global_load_dwordx4 v[14:17], v[128:129], off offset:768
	global_load_dwordx4 v[18:21], v[130:131], off offset:768
	v_cndmask_b32_e64 v4, v88, v4, s[28:29]
	v_add_u32_e32 v4, v64, v4
	v_subrev_u32_e32 v4, s6, v4
	v_sub_u32_e32 v4, v4, v88
	v_add_u32_e32 v4, s59, v4
	v_cndmask_b32_e64 v10, v88, v10, s[4:5]
	v_ashrrev_i32_e32 v5, 31, v4
	v_add_u32_e32 v10, v64, v10
	global_load_dwordx4 v[22:25], v[132:133], off offset:768
	global_load_dwordx4 v[26:29], v[134:135], off offset:768
	v_lshlrev_b64 v[4:5], 10, v[4:5]
	v_subrev_u32_e32 v10, s6, v10
	v_lshl_add_u64 v[138:139], v[62:63], 0, v[4:5]
	v_add_u32_e32 v4, -1, v88
	v_sub_u32_e32 v10, v10, v88
	v_cndmask_b32_e64 v84, 0, 1.0, vcc
	global_load_dwordx4 v[30:33], v[136:137], off offset:768
	global_load_dwordx4 v[34:37], v[138:139], off offset:768
	v_cmp_lt_u32_e32 vcc, v4, v87
	v_add_u32_e32 v10, s59, v10
	v_ashrrev_i32_e32 v11, 31, v10
	v_cndmask_b32_e32 v4, v88, v4, vcc
	v_add_u32_e32 v4, v64, v4
	v_lshlrev_b64 v[10:11], 10, v[10:11]
	v_subrev_u32_e32 v4, s6, v4
	v_lshl_add_u64 v[74:75], v[62:63], 0, v[10:11]
	v_add_u32_e32 v10, 3, v88
	v_sub_u32_e32 v4, v4, v88
	v_cmp_lt_u32_e64 s[10:11], v10, v87
	v_add_u32_e32 v4, s59, v4
	v_ashrrev_i32_e32 v5, 31, v4
	v_cndmask_b32_e64 v10, v88, v10, s[10:11]
	v_add_u32_e32 v10, v64, v10
	v_cndmask_b32_e64 v50, v88, v50, s[14:15]
	v_cmp_lt_u32_e64 s[18:19], v54, v87
	v_add_u32_e32 v58, 6, v88
	v_ashrrev_i32_e32 v81, 31, v80
	v_lshlrev_b64 v[4:5], 10, v[4:5]
	v_subrev_u32_e32 v10, s6, v10
	v_add_u32_e32 v50, v64, v50
	v_cndmask_b32_e64 v54, v88, v54, s[18:19]
	v_cmp_lt_u32_e64 s[22:23], v58, v87
	v_add_u32_e32 v65, 7, v88
	v_div_fixup_f32 v82, v2, v0, 1.0
	v_lshlrev_b64 v[2:3], 10, v[80:81]
	v_lshl_add_u64 v[122:123], v[62:63], 0, v[4:5]
	v_sub_u32_e32 v10, v10, v88
	v_subrev_u32_e32 v50, s6, v50
	v_add_u32_e32 v54, v64, v54
	v_cndmask_b32_e64 v58, v88, v58, s[22:23]
	v_cmp_lt_u32_e64 s[26:27], v65, v87
	global_load_dwordx4 v[38:41], v[122:123], off offset:768
	v_lshl_add_u64 v[124:125], v[62:63], 0, v[2:3]
	v_add_u32_e32 v10, s59, v10
	v_sub_u32_e32 v50, v50, v88
	v_subrev_u32_e32 v54, s6, v54
	v_add_u32_e32 v58, v64, v58
	v_cndmask_b32_e64 v65, v88, v65, s[26:27]
	global_load_dwordx4 v[2:5], v[124:125], off offset:768
	v_ashrrev_i32_e32 v11, 31, v10
	v_add_u32_e32 v50, s59, v50
	v_sub_u32_e32 v54, v54, v88
	v_subrev_u32_e32 v58, s6, v58
	v_add_u32_e32 v64, v64, v65
	global_load_dwordx4 v[42:45], v[76:77], off offset:768
	global_load_dwordx4 v[46:49], v[74:75], off offset:768
	v_lshlrev_b64 v[10:11], 10, v[10:11]
	v_ashrrev_i32_e32 v51, 31, v50
	v_add_u32_e32 v54, s59, v54
	v_sub_u32_e32 v58, v58, v88
	v_subrev_u32_e32 v64, s6, v64
	v_lshl_add_u64 v[70:71], v[62:63], 0, v[10:11]
	v_lshlrev_b64 v[50:51], 10, v[50:51]
	v_ashrrev_i32_e32 v55, 31, v54
	v_add_u32_e32 v58, s59, v58
	v_sub_u32_e32 v64, v64, v88
	global_load_dwordx4 v[10:13], v[70:71], off offset:768
	v_lshl_add_u64 v[72:73], v[62:63], 0, v[50:51]
	v_lshlrev_b64 v[54:55], 10, v[54:55]
	v_ashrrev_i32_e32 v59, 31, v58
	v_add_u32_e32 v64, s59, v64
	global_load_dwordx4 v[50:53], v[72:73], off offset:768
	v_lshl_add_u64 v[116:117], v[62:63], 0, v[54:55]
	v_lshlrev_b64 v[58:59], 10, v[58:59]
	v_ashrrev_i32_e32 v65, 31, v64
	global_load_dwordx4 v[54:57], v[116:117], off offset:768
	v_lshl_add_u64 v[118:119], v[62:63], 0, v[58:59]
	v_lshlrev_b64 v[64:65], 10, v[64:65]
	global_load_dwordx4 v[58:61], v[118:119], off offset:768
	v_lshl_add_u64 v[120:121], v[62:63], 0, v[64:65]
	global_load_dwordx4 v[62:65], v[120:121], off offset:768
	global_load_dwordx4 v[148:151], v[126:127], off offset:832
	global_load_dwordx4 v[152:155], v[128:129], off offset:832
	global_load_dwordx4 v[156:159], v[130:131], off offset:832
	global_load_dwordx4 v[160:163], v[132:133], off offset:832
	global_load_dwordx4 v[164:167], v[134:135], off offset:832
	global_load_dwordx4 v[168:171], v[136:137], off offset:832
	global_load_dwordx4 v[172:175], v[138:139], off offset:832
	global_load_dwordx4 v[176:179], v[122:123], off offset:832
	global_load_dwordx4 v[180:183], v[124:125], off offset:832
	global_load_dwordx4 v[184:187], v[76:77], off offset:832
	global_load_dwordx4 v[188:191], v[74:75], off offset:832
	global_load_dwordx4 v[192:195], v[70:71], off offset:832
	global_load_dwordx4 v[196:199], v[72:73], off offset:832
	global_load_dwordx4 v[200:203], v[116:117], off offset:832
	global_load_dwordx4 v[204:207], v[118:119], off offset:832
	global_load_dwordx4 v[222:225], v[120:121], off offset:832
	global_load_dwordx4 v[226:229], v[126:127], off offset:896
	global_load_dwordx4 v[230:233], v[128:129], off offset:896
	global_load_dwordx4 v[234:237], v[130:131], off offset:896
	global_load_dwordx4 v[238:241], v[132:133], off offset:896
	global_load_dwordx4 v[242:245], v[134:135], off offset:896
	global_load_dwordx4 v[246:249], v[136:137], off offset:896
	s_waitcnt vmcnt(37)
	v_lshlrev_b32_e32 v66, 16, v6
	v_and_b32_e32 v67, 0xffff0000, v6
	v_lshlrev_b32_e32 v6, 16, v7
	v_and_b32_e32 v7, 0xffff0000, v7
	v_cndmask_b32_e64 v114, 0, 1.0, s[8:9]
	s_waitcnt vmcnt(36)
	v_lshlrev_b32_e32 v68, 16, v14
	v_and_b32_e32 v69, 0xffff0000, v14
	v_pk_fma_f32 v[6:7], v[84:85], v[6:7], 0 op_sel_hi:[0, 1, 0]
	v_lshlrev_b32_e32 v14, 16, v15
	v_and_b32_e32 v15, 0xffff0000, v15
	v_cndmask_b32_e64 v112, 0, 1.0, s[12:13]
	v_pk_fma_f32 v[6:7], v[114:115], v[14:15], v[6:7] op_sel_hi:[0, 1, 1]
	s_waitcnt vmcnt(35)
	v_lshlrev_b32_e32 v14, 16, v19
	v_and_b32_e32 v15, 0xffff0000, v19
	v_cndmask_b32_e64 v110, 0, 1.0, s[16:17]
	v_pk_fma_f32 v[6:7], v[112:113], v[14:15], v[6:7] op_sel_hi:[0, 1, 1]
	s_waitcnt vmcnt(34)
	v_lshlrev_b32_e32 v14, 16, v23
	v_and_b32_e32 v15, 0xffff0000, v23
	v_cndmask_b32_e64 v108, 0, 1.0, s[20:21]
	v_pk_fma_f32 v[6:7], v[110:111], v[14:15], v[6:7] op_sel_hi:[0, 1, 1]
	s_waitcnt vmcnt(33)
	v_lshlrev_b32_e32 v14, 16, v27
	v_and_b32_e32 v15, 0xffff0000, v27
	v_cndmask_b32_e64 v106, 0, 1.0, s[24:25]
	v_pk_fma_f32 v[6:7], v[108:109], v[14:15], v[6:7] op_sel_hi:[0, 1, 1]
	s_waitcnt vmcnt(32)
	v_lshlrev_b32_e32 v14, 16, v31
	v_and_b32_e32 v15, 0xffff0000, v31
	v_cndmask_b32_e64 v104, 0, 1.0, s[28:29]
	v_pk_fma_f32 v[6:7], v[106:107], v[14:15], v[6:7] op_sel_hi:[0, 1, 1]
	s_waitcnt vmcnt(31)
	v_lshlrev_b32_e32 v14, 16, v35
	v_and_b32_e32 v15, 0xffff0000, v35
	v_pk_fma_f32 v[66:67], v[84:85], v[66:67], 0 op_sel_hi:[0, 1, 0]
	v_pk_fma_f32 v[6:7], v[104:105], v[14:15], v[6:7] op_sel_hi:[0, 1, 1]
	v_lshlrev_b32_e32 v14, 16, v8
	v_and_b32_e32 v15, 0xffff0000, v8
	v_lshlrev_b32_e32 v8, 16, v9
	v_and_b32_e32 v9, 0xffff0000, v9
	v_pk_fma_f32 v[66:67], v[114:115], v[68:69], v[66:67] op_sel_hi:[0, 1, 1]
	v_lshlrev_b32_e32 v68, 16, v18
	v_and_b32_e32 v69, 0xffff0000, v18
	v_lshlrev_b32_e32 v18, 16, v16
	v_and_b32_e32 v19, 0xffff0000, v16
	v_pk_fma_f32 v[8:9], v[84:85], v[8:9], 0 op_sel_hi:[0, 1, 0]
	v_lshlrev_b32_e32 v16, 16, v17
	v_and_b32_e32 v17, 0xffff0000, v17
	v_pk_fma_f32 v[8:9], v[114:115], v[16:17], v[8:9] op_sel_hi:[0, 1, 1]
	v_lshlrev_b32_e32 v16, 16, v21
	v_and_b32_e32 v17, 0xffff0000, v21
	v_pk_fma_f32 v[66:67], v[112:113], v[68:69], v[66:67] op_sel_hi:[0, 1, 1]
	v_lshlrev_b32_e32 v68, 16, v22
	v_and_b32_e32 v69, 0xffff0000, v22
	v_pk_fma_f32 v[8:9], v[112:113], v[16:17], v[8:9] op_sel_hi:[0, 1, 1]
	v_lshlrev_b32_e32 v16, 16, v25
	v_and_b32_e32 v17, 0xffff0000, v25
	v_pk_fma_f32 v[66:67], v[110:111], v[68:69], v[66:67] op_sel_hi:[0, 1, 1]
	v_lshlrev_b32_e32 v68, 16, v26
	v_and_b32_e32 v69, 0xffff0000, v26
	v_pk_fma_f32 v[8:9], v[110:111], v[16:17], v[8:9] op_sel_hi:[0, 1, 1]
	v_lshlrev_b32_e32 v16, 16, v29
	v_and_b32_e32 v17, 0xffff0000, v29
	v_pk_fma_f32 v[66:67], v[108:109], v[68:69], v[66:67] op_sel_hi:[0, 1, 1]
	v_lshlrev_b32_e32 v68, 16, v30
	v_and_b32_e32 v69, 0xffff0000, v30
	v_pk_fma_f32 v[8:9], v[108:109], v[16:17], v[8:9] op_sel_hi:[0, 1, 1]
	v_lshlrev_b32_e32 v16, 16, v33
	v_and_b32_e32 v17, 0xffff0000, v33
	v_pk_fma_f32 v[66:67], v[106:107], v[68:69], v[66:67] op_sel_hi:[0, 1, 1]
	v_lshlrev_b32_e32 v68, 16, v34
	v_and_b32_e32 v69, 0xffff0000, v34
	v_pk_fma_f32 v[14:15], v[84:85], v[14:15], 0 op_sel_hi:[0, 1, 0]
	v_pk_fma_f32 v[8:9], v[106:107], v[16:17], v[8:9] op_sel_hi:[0, 1, 1]
	v_lshlrev_b32_e32 v16, 16, v37
	v_and_b32_e32 v17, 0xffff0000, v37
	v_pk_fma_f32 v[66:67], v[104:105], v[68:69], v[66:67] op_sel_hi:[0, 1, 1]
	v_pk_fma_f32 v[14:15], v[114:115], v[18:19], v[14:15] op_sel_hi:[0, 1, 1]
	v_lshlrev_b32_e32 v18, 16, v20
	v_and_b32_e32 v19, 0xffff0000, v20
	v_pk_fma_f32 v[8:9], v[104:105], v[16:17], v[8:9] op_sel_hi:[0, 1, 1]
	v_cndmask_b32_e64 v86, 0, 1.0, vcc
	s_waitcnt vmcnt(30)
	v_lshlrev_b32_e32 v16, 16, v38
	v_and_b32_e32 v17, 0xffff0000, v38
	v_cmp_lt_u32_e32 vcc, v88, v87
	v_pk_fma_f32 v[14:15], v[112:113], v[18:19], v[14:15] op_sel_hi:[0, 1, 1]
	v_lshlrev_b32_e32 v18, 16, v24
	v_and_b32_e32 v19, 0xffff0000, v24
	v_lshlrev_b32_e32 v20, 16, v40
	v_and_b32_e32 v21, 0xffff0000, v40
	v_lshlrev_b32_e32 v22, 16, v41
	v_and_b32_e32 v23, 0xffff0000, v41
	v_cndmask_b32_e64 v88, 0, 1.0, vcc
	v_pk_fma_f32 v[16:17], v[86:87], v[16:17], v[66:67] op_sel_hi:[0, 1, 1]
	s_waitcnt vmcnt(29)
	v_lshlrev_b32_e32 v40, 16, v2
	v_and_b32_e32 v41, 0xffff0000, v2
	v_pk_fma_f32 v[14:15], v[110:111], v[18:19], v[14:15] op_sel_hi:[0, 1, 1]
	v_lshlrev_b32_e32 v18, 16, v28
	v_and_b32_e32 v19, 0xffff0000, v28
	v_cndmask_b32_e64 v90, 0, 1.0, s[0:1]
	s_waitcnt vmcnt(28)
	v_lshlrev_b32_e32 v24, 16, v42
	v_and_b32_e32 v25, 0xffff0000, v42
	v_pk_fma_f32 v[16:17], v[88:89], v[40:41], v[16:17] op_sel_hi:[0, 1, 1]
	v_pk_fma_f32 v[14:15], v[108:109], v[18:19], v[14:15] op_sel_hi:[0, 1, 1]
	v_lshlrev_b32_e32 v18, 16, v32
	v_and_b32_e32 v19, 0xffff0000, v32
	v_cndmask_b32_e64 v94, 0, 1.0, s[4:5]
	s_waitcnt vmcnt(27)
	v_lshlrev_b32_e32 v32, 16, v46
	v_and_b32_e32 v33, 0xffff0000, v46
	v_pk_fma_f32 v[16:17], v[90:91], v[24:25], v[16:17] op_sel_hi:[0, 1, 1]
	v_cndmask_b32_e64 v102, 0, 1.0, s[10:11]
	v_pk_fma_f32 v[16:17], v[94:95], v[32:33], v[16:17] op_sel_hi:[0, 1, 1]
	s_waitcnt vmcnt(26)
	v_lshlrev_b32_e32 v24, 16, v10
	v_and_b32_e32 v25, 0xffff0000, v10
	v_cndmask_b32_e64 v100, 0, 1.0, s[14:15]
	v_pk_fma_f32 v[16:17], v[102:103], v[24:25], v[16:17] op_sel_hi:[0, 1, 1]
	s_waitcnt vmcnt(25)
	v_lshlrev_b32_e32 v24, 16, v50
	v_and_b32_e32 v25, 0xffff0000, v50
	v_cndmask_b32_e64 v98, 0, 1.0, s[18:19]
	v_pk_fma_f32 v[16:17], v[100:101], v[24:25], v[16:17] op_sel_hi:[0, 1, 1]
	s_waitcnt vmcnt(24)
	v_lshlrev_b32_e32 v24, 16, v54
	v_and_b32_e32 v25, 0xffff0000, v54
	v_cndmask_b32_e64 v96, 0, 1.0, s[22:23]
	v_pk_fma_f32 v[16:17], v[98:99], v[24:25], v[16:17] op_sel_hi:[0, 1, 1]
	s_waitcnt vmcnt(23)
	v_lshlrev_b32_e32 v24, 16, v58
	v_and_b32_e32 v25, 0xffff0000, v58
	v_cndmask_b32_e64 v92, 0, 1.0, s[26:27]
	v_pk_fma_f32 v[16:17], v[96:97], v[24:25], v[16:17] op_sel_hi:[0, 1, 1]
	s_waitcnt vmcnt(22)
	v_lshlrev_b32_e32 v24, 16, v62
	v_and_b32_e32 v25, 0xffff0000, v62
	v_pk_fma_f32 v[14:15], v[106:107], v[18:19], v[14:15] op_sel_hi:[0, 1, 1]
	v_lshlrev_b32_e32 v18, 16, v36
	v_and_b32_e32 v19, 0xffff0000, v36
	v_pk_fma_f32 v[16:17], v[92:93], v[24:25], v[16:17] op_sel_hi:[0, 1, 1]
	v_pk_fma_f32 v[14:15], v[104:105], v[18:19], v[14:15] op_sel_hi:[0, 1, 1]
	v_lshlrev_b32_e32 v18, 16, v39
	v_and_b32_e32 v19, 0xffff0000, v39
	v_pk_fma_f32 v[16:17], v[82:83], v[16:17], v[40:41] op_sel_hi:[0, 1, 1] neg_lo:[0, 0, 1] neg_hi:[0, 0, 1]
	v_cvt_pk_bf16_f32 v2, v16, v17
	v_pk_fma_f32 v[6:7], v[86:87], v[18:19], v[6:7] op_sel_hi:[0, 1, 1]
	v_lshlrev_b32_e32 v16, 16, v3
	v_and_b32_e32 v17, 0xffff0000, v3
	v_lshlrev_b32_e32 v26, 16, v43
	v_and_b32_e32 v27, 0xffff0000, v43
	v_pk_fma_f32 v[6:7], v[88:89], v[16:17], v[6:7] op_sel_hi:[0, 1, 1]
	v_lshlrev_b32_e32 v34, 16, v47
	v_and_b32_e32 v35, 0xffff0000, v47
	v_pk_fma_f32 v[6:7], v[90:91], v[26:27], v[6:7] op_sel_hi:[0, 1, 1]
	v_pk_fma_f32 v[6:7], v[94:95], v[34:35], v[6:7] op_sel_hi:[0, 1, 1]
	v_lshlrev_b32_e32 v10, 16, v11
	v_and_b32_e32 v11, 0xffff0000, v11
	v_pk_fma_f32 v[6:7], v[102:103], v[10:11], v[6:7] op_sel_hi:[0, 1, 1]
	v_lshlrev_b32_e32 v10, 16, v51
	v_and_b32_e32 v11, 0xffff0000, v51
	v_pk_fma_f32 v[6:7], v[100:101], v[10:11], v[6:7] op_sel_hi:[0, 1, 1]
	v_lshlrev_b32_e32 v10, 16, v55
	v_and_b32_e32 v11, 0xffff0000, v55
	v_pk_fma_f32 v[6:7], v[98:99], v[10:11], v[6:7] op_sel_hi:[0, 1, 1]
	v_lshlrev_b32_e32 v10, 16, v59
	v_and_b32_e32 v11, 0xffff0000, v59
	v_pk_fma_f32 v[6:7], v[96:97], v[10:11], v[6:7] op_sel_hi:[0, 1, 1]
	v_lshlrev_b32_e32 v10, 16, v63
	v_and_b32_e32 v11, 0xffff0000, v63
	v_pk_fma_f32 v[6:7], v[92:93], v[10:11], v[6:7] op_sel_hi:[0, 1, 1]
	v_pk_fma_f32 v[6:7], v[82:83], v[6:7], v[16:17] op_sel_hi:[0, 1, 1] neg_lo:[0, 0, 1] neg_hi:[0, 0, 1]
	v_cvt_pk_bf16_f32 v3, v6, v7
	v_pk_fma_f32 v[6:7], v[86:87], v[20:21], v[14:15] op_sel_hi:[0, 1, 1]
	v_lshlrev_b32_e32 v10, 16, v4
	v_and_b32_e32 v11, 0xffff0000, v4
	v_lshlrev_b32_e32 v28, 16, v44
	v_and_b32_e32 v29, 0xffff0000, v44
	v_pk_fma_f32 v[6:7], v[88:89], v[10:11], v[6:7] op_sel_hi:[0, 1, 1]
	v_lshlrev_b32_e32 v36, 16, v48
	v_and_b32_e32 v37, 0xffff0000, v48
	v_pk_fma_f32 v[6:7], v[90:91], v[28:29], v[6:7] op_sel_hi:[0, 1, 1]
	v_pk_fma_f32 v[6:7], v[94:95], v[36:37], v[6:7] op_sel_hi:[0, 1, 1]
	v_lshlrev_b32_e32 v14, 16, v12
	v_and_b32_e32 v15, 0xffff0000, v12
	v_pk_fma_f32 v[6:7], v[102:103], v[14:15], v[6:7] op_sel_hi:[0, 1, 1]
	v_lshlrev_b32_e32 v14, 16, v52
	v_and_b32_e32 v15, 0xffff0000, v52
	v_pk_fma_f32 v[6:7], v[100:101], v[14:15], v[6:7] op_sel_hi:[0, 1, 1]
	v_lshlrev_b32_e32 v14, 16, v56
	v_and_b32_e32 v15, 0xffff0000, v56
	v_pk_fma_f32 v[6:7], v[98:99], v[14:15], v[6:7] op_sel_hi:[0, 1, 1]
	v_lshlrev_b32_e32 v14, 16, v60
	v_and_b32_e32 v15, 0xffff0000, v60
	v_pk_fma_f32 v[6:7], v[96:97], v[14:15], v[6:7] op_sel_hi:[0, 1, 1]
	v_lshlrev_b32_e32 v14, 16, v64
	v_and_b32_e32 v15, 0xffff0000, v64
	v_pk_fma_f32 v[6:7], v[92:93], v[14:15], v[6:7] op_sel_hi:[0, 1, 1]
	v_pk_fma_f32 v[6:7], v[82:83], v[6:7], v[10:11] op_sel_hi:[0, 1, 1] neg_lo:[0, 0, 1] neg_hi:[0, 0, 1]
	v_cvt_pk_bf16_f32 v4, v6, v7
	v_pk_fma_f32 v[6:7], v[86:87], v[22:23], v[8:9] op_sel_hi:[0, 1, 1]
	v_lshlrev_b32_e32 v8, 16, v5
	v_and_b32_e32 v9, 0xffff0000, v5
	v_lshlrev_b32_e32 v30, 16, v45
	v_and_b32_e32 v31, 0xffff0000, v45
	v_pk_fma_f32 v[6:7], v[88:89], v[8:9], v[6:7] op_sel_hi:[0, 1, 1]
	v_lshlrev_b32_e32 v38, 16, v49
	v_and_b32_e32 v39, 0xffff0000, v49
	v_pk_fma_f32 v[6:7], v[90:91], v[30:31], v[6:7] op_sel_hi:[0, 1, 1]
	v_pk_fma_f32 v[6:7], v[94:95], v[38:39], v[6:7] op_sel_hi:[0, 1, 1]
	v_lshlrev_b32_e32 v10, 16, v13
	v_and_b32_e32 v11, 0xffff0000, v13
	v_pk_fma_f32 v[6:7], v[102:103], v[10:11], v[6:7] op_sel_hi:[0, 1, 1]
	v_lshlrev_b32_e32 v10, 16, v53
	v_and_b32_e32 v11, 0xffff0000, v53
	v_pk_fma_f32 v[6:7], v[100:101], v[10:11], v[6:7] op_sel_hi:[0, 1, 1]
	v_lshlrev_b32_e32 v10, 16, v57
	v_and_b32_e32 v11, 0xffff0000, v57
	v_pk_fma_f32 v[6:7], v[98:99], v[10:11], v[6:7] op_sel_hi:[0, 1, 1]
	v_lshlrev_b32_e32 v10, 16, v61
	v_and_b32_e32 v11, 0xffff0000, v61
	v_pk_fma_f32 v[6:7], v[96:97], v[10:11], v[6:7] op_sel_hi:[0, 1, 1]
	v_lshlrev_b32_e32 v10, 16, v65
	v_and_b32_e32 v11, 0xffff0000, v65
	v_pk_fma_f32 v[6:7], v[92:93], v[10:11], v[6:7] op_sel_hi:[0, 1, 1]
	v_pk_fma_f32 v[6:7], v[82:83], v[6:7], v[8:9] op_sel_hi:[0, 1, 1] neg_lo:[0, 0, 1] neg_hi:[0, 0, 1]
	v_cvt_pk_bf16_f32 v5, v6, v7
	s_nop 0
	s_nop 0
	s_nop 0
	s_nop 0
	s_nop 0
	s_nop 0
	s_nop 0
	s_nop 0
	s_nop 0
	s_nop 0
	s_nop 0
	s_nop 0
	s_nop 0
	s_nop 0
	s_nop 0
	s_nop 0
	s_mov_b64 s[0:1], 0x400
	v_lshlrev_b32_e32 v0, 3, v83
	s_waitcnt vmcnt(21)
	v_lshlrev_b32_e32 v140, 16, v148
	v_and_b32_e32 v141, 0xffff0000, v148
	v_lshlrev_b32_e32 v6, 16, v149
	v_and_b32_e32 v7, 0xffff0000, v149
	s_waitcnt vmcnt(20)
	v_lshlrev_b32_e32 v142, 16, v152
	v_and_b32_e32 v143, 0xffff0000, v152
	v_pk_fma_f32 v[6:7], v[84:85], v[6:7], 0 op_sel_hi:[0, 1, 0]
	v_lshlrev_b32_e32 v10, 16, v153
	v_and_b32_e32 v11, 0xffff0000, v153
	v_pk_fma_f32 v[6:7], v[114:115], v[10:11], v[6:7] op_sel_hi:[0, 1, 1]
	s_waitcnt vmcnt(19)
	v_lshlrev_b32_e32 v10, 16, v157
	v_and_b32_e32 v11, 0xffff0000, v157
	v_pk_fma_f32 v[6:7], v[112:113], v[10:11], v[6:7] op_sel_hi:[0, 1, 1]
	s_waitcnt vmcnt(18)
	v_lshlrev_b32_e32 v10, 16, v161
	v_and_b32_e32 v11, 0xffff0000, v161
	v_pk_fma_f32 v[6:7], v[110:111], v[10:11], v[6:7] op_sel_hi:[0, 1, 1]
	s_waitcnt vmcnt(17)
	v_lshlrev_b32_e32 v10, 16, v165
	v_and_b32_e32 v11, 0xffff0000, v165
	v_pk_fma_f32 v[6:7], v[108:109], v[10:11], v[6:7] op_sel_hi:[0, 1, 1]
	s_waitcnt vmcnt(16)
	v_lshlrev_b32_e32 v10, 16, v169
	v_and_b32_e32 v11, 0xffff0000, v169
	v_pk_fma_f32 v[6:7], v[106:107], v[10:11], v[6:7] op_sel_hi:[0, 1, 1]
	s_waitcnt vmcnt(15)
	v_lshlrev_b32_e32 v10, 16, v173
	v_and_b32_e32 v11, 0xffff0000, v173
	v_pk_fma_f32 v[140:141], v[84:85], v[140:141], 0 op_sel_hi:[0, 1, 0]
	v_pk_fma_f32 v[10:11], v[104:105], v[10:11], v[6:7] op_sel_hi:[0, 1, 1]
	v_lshlrev_b32_e32 v6, 16, v150
	v_and_b32_e32 v7, 0xffff0000, v150
	v_pk_fma_f32 v[140:141], v[114:115], v[142:143], v[140:141] op_sel_hi:[0, 1, 1]
	v_lshlrev_b32_e32 v142, 16, v156
	v_and_b32_e32 v143, 0xffff0000, v156
	v_pk_fma_f32 v[6:7], v[84:85], v[6:7], 0 op_sel_hi:[0, 1, 0]
	v_lshlrev_b32_e32 v14, 16, v154
	v_and_b32_e32 v15, 0xffff0000, v154
	v_pk_fma_f32 v[6:7], v[114:115], v[14:15], v[6:7] op_sel_hi:[0, 1, 1]
	v_lshlrev_b32_e32 v14, 16, v158
	v_and_b32_e32 v15, 0xffff0000, v158
	v_pk_fma_f32 v[6:7], v[112:113], v[14:15], v[6:7] op_sel_hi:[0, 1, 1]
	v_lshlrev_b32_e32 v14, 16, v162
	v_and_b32_e32 v15, 0xffff0000, v162
	v_pk_fma_f32 v[6:7], v[110:111], v[14:15], v[6:7] op_sel_hi:[0, 1, 1]
	v_lshlrev_b32_e32 v14, 16, v166
	v_and_b32_e32 v15, 0xffff0000, v166
	v_pk_fma_f32 v[6:7], v[108:109], v[14:15], v[6:7] op_sel_hi:[0, 1, 1]
	v_lshlrev_b32_e32 v14, 16, v170
	v_and_b32_e32 v15, 0xffff0000, v170
	v_pk_fma_f32 v[6:7], v[106:107], v[14:15], v[6:7] op_sel_hi:[0, 1, 1]
	v_lshlrev_b32_e32 v14, 16, v174
	v_and_b32_e32 v15, 0xffff0000, v174
	v_pk_fma_f32 v[14:15], v[104:105], v[14:15], v[6:7] op_sel_hi:[0, 1, 1]
	v_lshlrev_b32_e32 v6, 16, v151
	v_and_b32_e32 v7, 0xffff0000, v151
	v_pk_fma_f32 v[6:7], v[84:85], v[6:7], 0 op_sel_hi:[0, 1, 0]
	v_lshlrev_b32_e32 v8, 16, v155
	v_and_b32_e32 v9, 0xffff0000, v155
	v_pk_fma_f32 v[6:7], v[114:115], v[8:9], v[6:7] op_sel_hi:[0, 1, 1]
	v_lshlrev_b32_e32 v8, 16, v159
	v_and_b32_e32 v9, 0xffff0000, v159
	v_pk_fma_f32 v[140:141], v[112:113], v[142:143], v[140:141] op_sel_hi:[0, 1, 1]
	v_lshlrev_b32_e32 v142, 16, v160
	v_and_b32_e32 v143, 0xffff0000, v160
	v_pk_fma_f32 v[6:7], v[112:113], v[8:9], v[6:7] op_sel_hi:[0, 1, 1]
	v_lshlrev_b32_e32 v8, 16, v163
	v_and_b32_e32 v9, 0xffff0000, v163
	v_pk_fma_f32 v[140:141], v[110:111], v[142:143], v[140:141] op_sel_hi:[0, 1, 1]
	v_lshlrev_b32_e32 v142, 16, v164
	v_and_b32_e32 v143, 0xffff0000, v164
	v_pk_fma_f32 v[6:7], v[110:111], v[8:9], v[6:7] op_sel_hi:[0, 1, 1]
	v_lshlrev_b32_e32 v8, 16, v167
	v_and_b32_e32 v9, 0xffff0000, v167
	v_pk_fma_f32 v[140:141], v[108:109], v[142:143], v[140:141] op_sel_hi:[0, 1, 1]
	v_lshlrev_b32_e32 v142, 16, v168
	v_and_b32_e32 v143, 0xffff0000, v168
	v_pk_fma_f32 v[6:7], v[108:109], v[8:9], v[6:7] op_sel_hi:[0, 1, 1]
	v_lshlrev_b32_e32 v8, 16, v171
	v_and_b32_e32 v9, 0xffff0000, v171
	v_pk_fma_f32 v[140:141], v[106:107], v[142:143], v[140:141] op_sel_hi:[0, 1, 1]
	v_lshlrev_b32_e32 v142, 16, v172
	v_and_b32_e32 v143, 0xffff0000, v172
	v_pk_fma_f32 v[6:7], v[106:107], v[8:9], v[6:7] op_sel_hi:[0, 1, 1]
	v_lshlrev_b32_e32 v8, 16, v175
	v_and_b32_e32 v9, 0xffff0000, v175
	v_pk_fma_f32 v[140:141], v[104:105], v[142:143], v[140:141] op_sel_hi:[0, 1, 1]
	v_pk_fma_f32 v[12:13], v[104:105], v[8:9], v[6:7] op_sel_hi:[0, 1, 1]
	s_waitcnt vmcnt(14)
	v_lshlrev_b32_e32 v6, 16, v176
	v_and_b32_e32 v7, 0xffff0000, v176
	v_lshlrev_b32_e32 v16, 16, v178
	v_and_b32_e32 v17, 0xffff0000, v178
	v_lshlrev_b32_e32 v18, 16, v179
	v_and_b32_e32 v19, 0xffff0000, v179
	v_pk_fma_f32 v[6:7], v[86:87], v[6:7], v[140:141] op_sel_hi:[0, 1, 1]
	s_waitcnt vmcnt(13)
	v_lshlrev_b32_e32 v40, 16, v180
	v_and_b32_e32 v41, 0xffff0000, v180
	s_waitcnt vmcnt(12)
	v_lshlrev_b32_e32 v20, 16, v184
	v_and_b32_e32 v21, 0xffff0000, v184
	v_pk_fma_f32 v[6:7], v[88:89], v[40:41], v[6:7] op_sel_hi:[0, 1, 1]
	s_waitcnt vmcnt(11)
	v_lshlrev_b32_e32 v28, 16, v188
	v_and_b32_e32 v29, 0xffff0000, v188
	v_pk_fma_f32 v[6:7], v[90:91], v[20:21], v[6:7] op_sel_hi:[0, 1, 1]
	v_pk_fma_f32 v[6:7], v[94:95], v[28:29], v[6:7] op_sel_hi:[0, 1, 1]
	s_waitcnt vmcnt(10)
	v_lshlrev_b32_e32 v20, 16, v192
	v_and_b32_e32 v21, 0xffff0000, v192
	v_lshlrev_b32_e32 v8, 16, v177
	v_and_b32_e32 v9, 0xffff0000, v177
	v_pk_fma_f32 v[6:7], v[102:103], v[20:21], v[6:7] op_sel_hi:[0, 1, 1]
	s_waitcnt vmcnt(9)
	v_lshlrev_b32_e32 v20, 16, v196
	v_and_b32_e32 v21, 0xffff0000, v196
	v_pk_fma_f32 v[6:7], v[100:101], v[20:21], v[6:7] op_sel_hi:[0, 1, 1]
	s_waitcnt vmcnt(8)
	v_lshlrev_b32_e32 v20, 16, v200
	v_and_b32_e32 v21, 0xffff0000, v200
	v_pk_fma_f32 v[8:9], v[86:87], v[8:9], v[10:11] op_sel_hi:[0, 1, 1]
	v_lshlrev_b32_e32 v10, 16, v181
	v_and_b32_e32 v11, 0xffff0000, v181
	v_lshlrev_b32_e32 v22, 16, v185
	v_and_b32_e32 v23, 0xffff0000, v185
	v_pk_fma_f32 v[6:7], v[98:99], v[20:21], v[6:7] op_sel_hi:[0, 1, 1]
	s_waitcnt vmcnt(7)
	v_lshlrev_b32_e32 v20, 16, v204
	v_and_b32_e32 v21, 0xffff0000, v204
	v_pk_fma_f32 v[8:9], v[88:89], v[10:11], v[8:9] op_sel_hi:[0, 1, 1]
	v_lshlrev_b32_e32 v30, 16, v189
	v_and_b32_e32 v31, 0xffff0000, v189
	v_pk_fma_f32 v[6:7], v[96:97], v[20:21], v[6:7] op_sel_hi:[0, 1, 1]
	s_waitcnt vmcnt(6)
	v_lshlrev_b32_e32 v20, 16, v222
	v_and_b32_e32 v21, 0xffff0000, v222
	v_pk_fma_f32 v[8:9], v[90:91], v[22:23], v[8:9] op_sel_hi:[0, 1, 1]
	v_pk_fma_f32 v[6:7], v[92:93], v[20:21], v[6:7] op_sel_hi:[0, 1, 1]
	v_pk_fma_f32 v[8:9], v[94:95], v[30:31], v[8:9] op_sel_hi:[0, 1, 1]
	v_lshlrev_b32_e32 v20, 16, v193
	v_and_b32_e32 v21, 0xffff0000, v193
	v_pk_fma_f32 v[8:9], v[102:103], v[20:21], v[8:9] op_sel_hi:[0, 1, 1]
	v_lshlrev_b32_e32 v20, 16, v197
	v_and_b32_e32 v21, 0xffff0000, v197
	v_pk_fma_f32 v[8:9], v[100:101], v[20:21], v[8:9] op_sel_hi:[0, 1, 1]
	v_lshlrev_b32_e32 v20, 16, v201
	v_and_b32_e32 v21, 0xffff0000, v201
	v_pk_fma_f32 v[8:9], v[98:99], v[20:21], v[8:9] op_sel_hi:[0, 1, 1]
	v_lshlrev_b32_e32 v20, 16, v205
	v_and_b32_e32 v21, 0xffff0000, v205
	v_pk_fma_f32 v[8:9], v[96:97], v[20:21], v[8:9] op_sel_hi:[0, 1, 1]
	v_lshlrev_b32_e32 v20, 16, v223
	v_and_b32_e32 v21, 0xffff0000, v223
	v_pk_fma_f32 v[8:9], v[92:93], v[20:21], v[8:9] op_sel_hi:[0, 1, 1]
	v_pk_fma_f32 v[6:7], v[82:83], v[6:7], v[40:41] op_sel_hi:[0, 1, 1] neg_lo:[0, 0, 1] neg_hi:[0, 0, 1]
	v_pk_fma_f32 v[8:9], v[82:83], v[8:9], v[10:11] op_sel_hi:[0, 1, 1] neg_lo:[0, 0, 1] neg_hi:[0, 0, 1]
	v_cvt_pk_bf16_f32 v6, v6, v7
	v_cvt_pk_bf16_f32 v7, v8, v9
	v_pk_fma_f32 v[8:9], v[86:87], v[16:17], v[14:15] op_sel_hi:[0, 1, 1]
	v_lshlrev_b32_e32 v10, 16, v182
	v_and_b32_e32 v11, 0xffff0000, v182
	v_lshlrev_b32_e32 v24, 16, v186
	v_and_b32_e32 v25, 0xffff0000, v186
	v_pk_fma_f32 v[8:9], v[88:89], v[10:11], v[8:9] op_sel_hi:[0, 1, 1]
	v_lshlrev_b32_e32 v32, 16, v190
	v_and_b32_e32 v33, 0xffff0000, v190
	v_pk_fma_f32 v[8:9], v[90:91], v[24:25], v[8:9] op_sel_hi:[0, 1, 1]
	v_pk_fma_f32 v[8:9], v[94:95], v[32:33], v[8:9] op_sel_hi:[0, 1, 1]
	v_lshlrev_b32_e32 v14, 16, v194
	v_and_b32_e32 v15, 0xffff0000, v194
	v_pk_fma_f32 v[8:9], v[102:103], v[14:15], v[8:9] op_sel_hi:[0, 1, 1]
	v_lshlrev_b32_e32 v14, 16, v198
	v_and_b32_e32 v15, 0xffff0000, v198
	v_pk_fma_f32 v[8:9], v[100:101], v[14:15], v[8:9] op_sel_hi:[0, 1, 1]
	v_lshlrev_b32_e32 v14, 16, v202
	v_and_b32_e32 v15, 0xffff0000, v202
	v_pk_fma_f32 v[8:9], v[98:99], v[14:15], v[8:9] op_sel_hi:[0, 1, 1]
	v_lshlrev_b32_e32 v14, 16, v206
	v_and_b32_e32 v15, 0xffff0000, v206
	v_pk_fma_f32 v[8:9], v[96:97], v[14:15], v[8:9] op_sel_hi:[0, 1, 1]
	v_lshlrev_b32_e32 v14, 16, v224
	v_and_b32_e32 v15, 0xffff0000, v224
	v_pk_fma_f32 v[8:9], v[92:93], v[14:15], v[8:9] op_sel_hi:[0, 1, 1]
	v_pk_fma_f32 v[8:9], v[82:83], v[8:9], v[10:11] op_sel_hi:[0, 1, 1] neg_lo:[0, 0, 1] neg_hi:[0, 0, 1]
	v_pk_fma_f32 v[10:11], v[86:87], v[18:19], v[12:13] op_sel_hi:[0, 1, 1]
	v_lshlrev_b32_e32 v12, 16, v183
	v_and_b32_e32 v13, 0xffff0000, v183
	v_lshlrev_b32_e32 v26, 16, v187
	v_and_b32_e32 v27, 0xffff0000, v187
	v_pk_fma_f32 v[10:11], v[88:89], v[12:13], v[10:11] op_sel_hi:[0, 1, 1]
	v_lshlrev_b32_e32 v38, 16, v191
	v_and_b32_e32 v39, 0xffff0000, v191
	v_pk_fma_f32 v[10:11], v[90:91], v[26:27], v[10:11] op_sel_hi:[0, 1, 1]
	v_pk_fma_f32 v[10:11], v[94:95], v[38:39], v[10:11] op_sel_hi:[0, 1, 1]
	v_lshlrev_b32_e32 v14, 16, v195
	v_and_b32_e32 v15, 0xffff0000, v195
	v_pk_fma_f32 v[10:11], v[102:103], v[14:15], v[10:11] op_sel_hi:[0, 1, 1]
	v_lshlrev_b32_e32 v14, 16, v199
	v_and_b32_e32 v15, 0xffff0000, v199
	v_pk_fma_f32 v[10:11], v[100:101], v[14:15], v[10:11] op_sel_hi:[0, 1, 1]
	v_lshlrev_b32_e32 v14, 16, v203
	v_and_b32_e32 v15, 0xffff0000, v203
	v_pk_fma_f32 v[10:11], v[98:99], v[14:15], v[10:11] op_sel_hi:[0, 1, 1]
	v_lshlrev_b32_e32 v14, 16, v207
	v_and_b32_e32 v15, 0xffff0000, v207
	v_pk_fma_f32 v[10:11], v[96:97], v[14:15], v[10:11] op_sel_hi:[0, 1, 1]
	v_lshlrev_b32_e32 v14, 16, v225
	v_and_b32_e32 v15, 0xffff0000, v225
	v_pk_fma_f32 v[10:11], v[92:93], v[14:15], v[10:11] op_sel_hi:[0, 1, 1]
	v_pk_fma_f32 v[10:11], v[82:83], v[10:11], v[12:13] op_sel_hi:[0, 1, 1] neg_lo:[0, 0, 1] neg_hi:[0, 0, 1]
	v_cvt_pk_bf16_f32 v8, v8, v9
	v_cvt_pk_bf16_f32 v9, v10, v11
	s_nop 0
	s_nop 0
	s_nop 0
	s_nop 0
	s_nop 0
	s_nop 0
	global_load_dwordx4 v[34:37], v[138:139], off offset:896
	global_load_dwordx4 v[38:41], v[122:123], off offset:896
	global_load_dwordx4 v[42:45], v[124:125], off offset:896
	global_load_dwordx4 v[46:49], v[76:77], off offset:896
	global_load_dwordx4 v[50:53], v[74:75], off offset:896
	global_load_dwordx4 v[54:57], v[70:71], off offset:896
	global_load_dwordx4 v[58:61], v[72:73], off offset:896
	global_load_dwordx4 v[62:65], v[116:117], off offset:896
	global_load_dwordx4 v[66:69], v[118:119], off offset:896
	global_load_dwordx4 v[140:143], v[120:121], off offset:896
	s_waitcnt vmcnt(15)
	v_lshlrev_b32_e32 v144, 16, v226
	v_and_b32_e32 v145, 0xffff0000, v226
	v_lshlrev_b32_e32 v10, 16, v227
	v_and_b32_e32 v11, 0xffff0000, v227
	s_waitcnt vmcnt(14)
	v_lshlrev_b32_e32 v146, 16, v230
	v_and_b32_e32 v147, 0xffff0000, v230
	v_pk_fma_f32 v[10:11], v[84:85], v[10:11], 0 op_sel_hi:[0, 1, 0]
	v_lshlrev_b32_e32 v14, 16, v231
	v_and_b32_e32 v15, 0xffff0000, v231
	v_pk_fma_f32 v[10:11], v[114:115], v[14:15], v[10:11] op_sel_hi:[0, 1, 1]
	s_waitcnt vmcnt(13)
	v_lshlrev_b32_e32 v14, 16, v235
	v_and_b32_e32 v15, 0xffff0000, v235
	v_pk_fma_f32 v[10:11], v[112:113], v[14:15], v[10:11] op_sel_hi:[0, 1, 1]
	s_waitcnt vmcnt(12)
	v_lshlrev_b32_e32 v14, 16, v239
	v_and_b32_e32 v15, 0xffff0000, v239
	v_pk_fma_f32 v[10:11], v[110:111], v[14:15], v[10:11] op_sel_hi:[0, 1, 1]
	s_waitcnt vmcnt(11)
	v_lshlrev_b32_e32 v14, 16, v243
	v_and_b32_e32 v15, 0xffff0000, v243
	v_pk_fma_f32 v[10:11], v[108:109], v[14:15], v[10:11] op_sel_hi:[0, 1, 1]
	s_waitcnt vmcnt(10)
	v_lshlrev_b32_e32 v14, 16, v247
	v_and_b32_e32 v15, 0xffff0000, v247
	v_pk_fma_f32 v[10:11], v[106:107], v[14:15], v[10:11] op_sel_hi:[0, 1, 1]
	s_waitcnt vmcnt(9)
	v_lshlrev_b32_e32 v14, 16, v35
	v_and_b32_e32 v15, 0xffff0000, v35
	v_pk_fma_f32 v[144:145], v[84:85], v[144:145], 0 op_sel_hi:[0, 1, 0]
	v_pk_fma_f32 v[14:15], v[104:105], v[14:15], v[10:11] op_sel_hi:[0, 1, 1]
	v_lshlrev_b32_e32 v10, 16, v228
	v_and_b32_e32 v11, 0xffff0000, v228
	v_pk_fma_f32 v[144:145], v[114:115], v[146:147], v[144:145] op_sel_hi:[0, 1, 1]
	v_lshlrev_b32_e32 v146, 16, v234
	v_and_b32_e32 v147, 0xffff0000, v234
	v_pk_fma_f32 v[10:11], v[84:85], v[10:11], 0 op_sel_hi:[0, 1, 0]
	v_lshlrev_b32_e32 v18, 16, v232
	v_and_b32_e32 v19, 0xffff0000, v232
	v_pk_fma_f32 v[10:11], v[114:115], v[18:19], v[10:11] op_sel_hi:[0, 1, 1]
	v_lshlrev_b32_e32 v18, 16, v236
	v_and_b32_e32 v19, 0xffff0000, v236
	v_pk_fma_f32 v[10:11], v[112:113], v[18:19], v[10:11] op_sel_hi:[0, 1, 1]
	v_lshlrev_b32_e32 v18, 16, v240
	v_and_b32_e32 v19, 0xffff0000, v240
	v_pk_fma_f32 v[10:11], v[110:111], v[18:19], v[10:11] op_sel_hi:[0, 1, 1]
	v_lshlrev_b32_e32 v18, 16, v244
	v_and_b32_e32 v19, 0xffff0000, v244
	v_pk_fma_f32 v[10:11], v[108:109], v[18:19], v[10:11] op_sel_hi:[0, 1, 1]
	v_lshlrev_b32_e32 v18, 16, v248
	v_and_b32_e32 v19, 0xffff0000, v248
	v_pk_fma_f32 v[10:11], v[106:107], v[18:19], v[10:11] op_sel_hi:[0, 1, 1]
	v_lshlrev_b32_e32 v18, 16, v36
	v_and_b32_e32 v19, 0xffff0000, v36
	v_pk_fma_f32 v[18:19], v[104:105], v[18:19], v[10:11] op_sel_hi:[0, 1, 1]
	v_lshlrev_b32_e32 v10, 16, v229
	v_and_b32_e32 v11, 0xffff0000, v229
	v_pk_fma_f32 v[10:11], v[84:85], v[10:11], 0 op_sel_hi:[0, 1, 0]
	v_lshlrev_b32_e32 v12, 16, v233
	v_and_b32_e32 v13, 0xffff0000, v233
	v_pk_fma_f32 v[10:11], v[114:115], v[12:13], v[10:11] op_sel_hi:[0, 1, 1]
	v_lshlrev_b32_e32 v12, 16, v237
	v_and_b32_e32 v13, 0xffff0000, v237
	v_pk_fma_f32 v[144:145], v[112:113], v[146:147], v[144:145] op_sel_hi:[0, 1, 1]
	v_lshlrev_b32_e32 v146, 16, v238
	v_and_b32_e32 v147, 0xffff0000, v238
	v_pk_fma_f32 v[10:11], v[112:113], v[12:13], v[10:11] op_sel_hi:[0, 1, 1]
	v_lshlrev_b32_e32 v12, 16, v241
	v_and_b32_e32 v13, 0xffff0000, v241
	v_pk_fma_f32 v[144:145], v[110:111], v[146:147], v[144:145] op_sel_hi:[0, 1, 1]
	v_lshlrev_b32_e32 v146, 16, v242
	v_and_b32_e32 v147, 0xffff0000, v242
	v_pk_fma_f32 v[10:11], v[110:111], v[12:13], v[10:11] op_sel_hi:[0, 1, 1]
	v_lshlrev_b32_e32 v12, 16, v245
	v_and_b32_e32 v13, 0xffff0000, v245
	v_pk_fma_f32 v[144:145], v[108:109], v[146:147], v[144:145] op_sel_hi:[0, 1, 1]
	v_lshlrev_b32_e32 v146, 16, v246
	v_and_b32_e32 v147, 0xffff0000, v246
	v_pk_fma_f32 v[10:11], v[108:109], v[12:13], v[10:11] op_sel_hi:[0, 1, 1]
	v_lshlrev_b32_e32 v12, 16, v249
	v_and_b32_e32 v13, 0xffff0000, v249
	v_pk_fma_f32 v[144:145], v[106:107], v[146:147], v[144:145] op_sel_hi:[0, 1, 1]
	v_lshlrev_b32_e32 v146, 16, v34
	v_and_b32_e32 v147, 0xffff0000, v34
	v_pk_fma_f32 v[10:11], v[106:107], v[12:13], v[10:11] op_sel_hi:[0, 1, 1]
	v_lshlrev_b32_e32 v12, 16, v37
	v_and_b32_e32 v13, 0xffff0000, v37
	v_pk_fma_f32 v[144:145], v[104:105], v[146:147], v[144:145] op_sel_hi:[0, 1, 1]
	v_pk_fma_f32 v[16:17], v[104:105], v[12:13], v[10:11] op_sel_hi:[0, 1, 1]
	s_waitcnt vmcnt(8)
	v_lshlrev_b32_e32 v10, 16, v38
	v_and_b32_e32 v11, 0xffff0000, v38
	v_lshlrev_b32_e32 v20, 16, v40
	v_and_b32_e32 v21, 0xffff0000, v40
	v_lshlrev_b32_e32 v22, 16, v41
	v_and_b32_e32 v23, 0xffff0000, v41
	v_pk_fma_f32 v[10:11], v[86:87], v[10:11], v[144:145] op_sel_hi:[0, 1, 1]
	s_waitcnt vmcnt(7)
	v_lshlrev_b32_e32 v40, 16, v42
	v_and_b32_e32 v41, 0xffff0000, v42
	s_waitcnt vmcnt(6)
	v_lshlrev_b32_e32 v24, 16, v46
	v_and_b32_e32 v25, 0xffff0000, v46
	v_pk_fma_f32 v[10:11], v[88:89], v[40:41], v[10:11] op_sel_hi:[0, 1, 1]
	s_waitcnt vmcnt(5)
	v_lshlrev_b32_e32 v32, 16, v50
	v_and_b32_e32 v33, 0xffff0000, v50
	v_pk_fma_f32 v[10:11], v[90:91], v[24:25], v[10:11] op_sel_hi:[0, 1, 1]
	v_pk_fma_f32 v[10:11], v[94:95], v[32:33], v[10:11] op_sel_hi:[0, 1, 1]
	s_waitcnt vmcnt(4)
	v_lshlrev_b32_e32 v24, 16, v54
	v_and_b32_e32 v25, 0xffff0000, v54
	v_lshlrev_b32_e32 v12, 16, v39
	v_and_b32_e32 v13, 0xffff0000, v39
	v_pk_fma_f32 v[10:11], v[102:103], v[24:25], v[10:11] op_sel_hi:[0, 1, 1]
	s_waitcnt vmcnt(3)
	v_lshlrev_b32_e32 v24, 16, v58
	v_and_b32_e32 v25, 0xffff0000, v58
	v_pk_fma_f32 v[10:11], v[100:101], v[24:25], v[10:11] op_sel_hi:[0, 1, 1]
	s_waitcnt vmcnt(2)
	v_lshlrev_b32_e32 v24, 16, v62
	v_and_b32_e32 v25, 0xffff0000, v62
	v_pk_fma_f32 v[12:13], v[86:87], v[12:13], v[14:15] op_sel_hi:[0, 1, 1]
	v_lshlrev_b32_e32 v14, 16, v43
	v_and_b32_e32 v15, 0xffff0000, v43
	v_lshlrev_b32_e32 v26, 16, v47
	v_and_b32_e32 v27, 0xffff0000, v47
	v_pk_fma_f32 v[10:11], v[98:99], v[24:25], v[10:11] op_sel_hi:[0, 1, 1]
	s_waitcnt vmcnt(1)
	v_lshlrev_b32_e32 v24, 16, v66
	v_and_b32_e32 v25, 0xffff0000, v66
	v_pk_fma_f32 v[12:13], v[88:89], v[14:15], v[12:13] op_sel_hi:[0, 1, 1]
	v_lshlrev_b32_e32 v34, 16, v51
	v_and_b32_e32 v35, 0xffff0000, v51
	v_pk_fma_f32 v[10:11], v[96:97], v[24:25], v[10:11] op_sel_hi:[0, 1, 1]
	s_waitcnt vmcnt(0)
	v_lshlrev_b32_e32 v24, 16, v140
	v_and_b32_e32 v25, 0xffff0000, v140
	v_pk_fma_f32 v[12:13], v[90:91], v[26:27], v[12:13] op_sel_hi:[0, 1, 1]
	v_pk_fma_f32 v[10:11], v[92:93], v[24:25], v[10:11] op_sel_hi:[0, 1, 1]
	v_pk_fma_f32 v[12:13], v[94:95], v[34:35], v[12:13] op_sel_hi:[0, 1, 1]
	v_lshlrev_b32_e32 v24, 16, v55
	v_and_b32_e32 v25, 0xffff0000, v55
	v_pk_fma_f32 v[12:13], v[102:103], v[24:25], v[12:13] op_sel_hi:[0, 1, 1]
	v_lshlrev_b32_e32 v24, 16, v59
	v_and_b32_e32 v25, 0xffff0000, v59
	v_pk_fma_f32 v[12:13], v[100:101], v[24:25], v[12:13] op_sel_hi:[0, 1, 1]
	v_lshlrev_b32_e32 v24, 16, v63
	v_and_b32_e32 v25, 0xffff0000, v63
	v_pk_fma_f32 v[12:13], v[98:99], v[24:25], v[12:13] op_sel_hi:[0, 1, 1]
	v_lshlrev_b32_e32 v24, 16, v67
	v_and_b32_e32 v25, 0xffff0000, v67
	v_pk_fma_f32 v[12:13], v[96:97], v[24:25], v[12:13] op_sel_hi:[0, 1, 1]
	v_lshlrev_b32_e32 v24, 16, v141
	v_and_b32_e32 v25, 0xffff0000, v141
	v_pk_fma_f32 v[12:13], v[92:93], v[24:25], v[12:13] op_sel_hi:[0, 1, 1]
	v_pk_fma_f32 v[10:11], v[82:83], v[10:11], v[40:41] op_sel_hi:[0, 1, 1] neg_lo:[0, 0, 1] neg_hi:[0, 0, 1]
	v_pk_fma_f32 v[12:13], v[82:83], v[12:13], v[14:15] op_sel_hi:[0, 1, 1] neg_lo:[0, 0, 1] neg_hi:[0, 0, 1]
	v_cvt_pk_bf16_f32 v10, v10, v11
	v_cvt_pk_bf16_f32 v11, v12, v13
	v_pk_fma_f32 v[12:13], v[86:87], v[20:21], v[18:19] op_sel_hi:[0, 1, 1]
	v_lshlrev_b32_e32 v14, 16, v44
	v_and_b32_e32 v15, 0xffff0000, v44
	v_lshlrev_b32_e32 v28, 16, v48
	v_and_b32_e32 v29, 0xffff0000, v48
	v_pk_fma_f32 v[12:13], v[88:89], v[14:15], v[12:13] op_sel_hi:[0, 1, 1]
	v_lshlrev_b32_e32 v36, 16, v52
	v_and_b32_e32 v37, 0xffff0000, v52
	v_pk_fma_f32 v[12:13], v[90:91], v[28:29], v[12:13] op_sel_hi:[0, 1, 1]
	v_pk_fma_f32 v[12:13], v[94:95], v[36:37], v[12:13] op_sel_hi:[0, 1, 1]
	v_lshlrev_b32_e32 v18, 16, v56
	v_and_b32_e32 v19, 0xffff0000, v56
	v_pk_fma_f32 v[12:13], v[102:103], v[18:19], v[12:13] op_sel_hi:[0, 1, 1]
	v_lshlrev_b32_e32 v18, 16, v60
	v_and_b32_e32 v19, 0xffff0000, v60
	v_pk_fma_f32 v[12:13], v[100:101], v[18:19], v[12:13] op_sel_hi:[0, 1, 1]
	v_lshlrev_b32_e32 v18, 16, v64
	v_and_b32_e32 v19, 0xffff0000, v64
	v_pk_fma_f32 v[12:13], v[98:99], v[18:19], v[12:13] op_sel_hi:[0, 1, 1]
	v_lshlrev_b32_e32 v18, 16, v68
	v_and_b32_e32 v19, 0xffff0000, v68
	v_pk_fma_f32 v[12:13], v[96:97], v[18:19], v[12:13] op_sel_hi:[0, 1, 1]
	v_lshlrev_b32_e32 v18, 16, v142
	v_and_b32_e32 v19, 0xffff0000, v142
	v_pk_fma_f32 v[12:13], v[92:93], v[18:19], v[12:13] op_sel_hi:[0, 1, 1]
	v_pk_fma_f32 v[12:13], v[82:83], v[12:13], v[14:15] op_sel_hi:[0, 1, 1] neg_lo:[0, 0, 1] neg_hi:[0, 0, 1]
	v_pk_fma_f32 v[14:15], v[86:87], v[22:23], v[16:17] op_sel_hi:[0, 1, 1]
	v_lshlrev_b32_e32 v16, 16, v45
	v_and_b32_e32 v17, 0xffff0000, v45
	v_lshlrev_b32_e32 v30, 16, v49
	v_and_b32_e32 v31, 0xffff0000, v49
	v_pk_fma_f32 v[14:15], v[88:89], v[16:17], v[14:15] op_sel_hi:[0, 1, 1]
	v_lshlrev_b32_e32 v38, 16, v53
	v_and_b32_e32 v39, 0xffff0000, v53
	v_pk_fma_f32 v[14:15], v[90:91], v[30:31], v[14:15] op_sel_hi:[0, 1, 1]
	v_pk_fma_f32 v[14:15], v[94:95], v[38:39], v[14:15] op_sel_hi:[0, 1, 1]
	v_lshlrev_b32_e32 v18, 16, v57
	v_and_b32_e32 v19, 0xffff0000, v57
	v_pk_fma_f32 v[14:15], v[102:103], v[18:19], v[14:15] op_sel_hi:[0, 1, 1]
	v_lshlrev_b32_e32 v18, 16, v61
	v_and_b32_e32 v19, 0xffff0000, v61
	v_pk_fma_f32 v[14:15], v[100:101], v[18:19], v[14:15] op_sel_hi:[0, 1, 1]
	v_lshlrev_b32_e32 v18, 16, v65
	v_and_b32_e32 v19, 0xffff0000, v65
	v_pk_fma_f32 v[14:15], v[98:99], v[18:19], v[14:15] op_sel_hi:[0, 1, 1]
	v_lshlrev_b32_e32 v18, 16, v69
	v_and_b32_e32 v19, 0xffff0000, v69
	v_pk_fma_f32 v[14:15], v[96:97], v[18:19], v[14:15] op_sel_hi:[0, 1, 1]
	v_lshlrev_b32_e32 v18, 16, v143
	v_and_b32_e32 v19, 0xffff0000, v143
	v_pk_fma_f32 v[14:15], v[92:93], v[18:19], v[14:15] op_sel_hi:[0, 1, 1]
	v_pk_fma_f32 v[14:15], v[82:83], v[14:15], v[16:17] op_sel_hi:[0, 1, 1] neg_lo:[0, 0, 1] neg_hi:[0, 0, 1]
	v_cvt_pk_bf16_f32 v12, v12, v13
	v_cvt_pk_bf16_f32 v13, v14, v15
	global_load_dwordx4 v[14:17], v[126:127], off offset:960
	global_load_dwordx4 v[18:21], v[128:129], off offset:960
	global_load_dwordx4 v[22:25], v[130:131], off offset:960
	global_load_dwordx4 v[26:29], v[132:133], off offset:960
	global_load_dwordx4 v[30:33], v[134:135], off offset:960
	global_load_dwordx4 v[34:37], v[136:137], off offset:960
	global_load_dwordx4 v[38:41], v[138:139], off offset:960
	global_load_dwordx4 v[50:53], v[122:123], off offset:960
	global_load_dwordx4 v[42:45], v[124:125], off offset:960
	global_load_dwordx4 v[62:65], v[76:77], off offset:960
	s_nop 0
	global_load_dwordx4 v[74:77], v[74:75], off offset:960
	s_nop 0
	global_load_dwordx4 v[46:49], v[70:71], off offset:960
	global_load_dwordx4 v[54:57], v[72:73], off offset:960
	global_load_dwordx4 v[58:61], v[116:117], off offset:960
	global_load_dwordx4 v[66:69], v[118:119], off offset:960
	s_nop 0
	global_load_dwordx4 v[70:73], v[120:121], off offset:960
	s_waitcnt vmcnt(15)
	v_lshlrev_b32_e32 v116, 16, v14
	v_and_b32_e32 v117, 0xffff0000, v14
	v_lshlrev_b32_e32 v14, 16, v15
	v_and_b32_e32 v15, 0xffff0000, v15
	s_waitcnt vmcnt(14)
	v_lshlrev_b32_e32 v118, 16, v18
	v_and_b32_e32 v119, 0xffff0000, v18
	v_pk_fma_f32 v[14:15], v[84:85], v[14:15], 0 op_sel_hi:[0, 1, 0]
	v_lshlrev_b32_e32 v18, 16, v19
	v_and_b32_e32 v19, 0xffff0000, v19
	v_pk_fma_f32 v[14:15], v[114:115], v[18:19], v[14:15] op_sel_hi:[0, 1, 1]
	s_waitcnt vmcnt(13)
	v_lshlrev_b32_e32 v18, 16, v23
	v_and_b32_e32 v19, 0xffff0000, v23
	v_pk_fma_f32 v[14:15], v[112:113], v[18:19], v[14:15] op_sel_hi:[0, 1, 1]
	s_waitcnt vmcnt(12)
	v_lshlrev_b32_e32 v18, 16, v27
	v_and_b32_e32 v19, 0xffff0000, v27
	v_pk_fma_f32 v[14:15], v[110:111], v[18:19], v[14:15] op_sel_hi:[0, 1, 1]
	s_waitcnt vmcnt(11)
	v_lshlrev_b32_e32 v18, 16, v31
	v_and_b32_e32 v19, 0xffff0000, v31
	v_pk_fma_f32 v[14:15], v[108:109], v[18:19], v[14:15] op_sel_hi:[0, 1, 1]
	s_waitcnt vmcnt(10)
	v_lshlrev_b32_e32 v18, 16, v35
	v_and_b32_e32 v19, 0xffff0000, v35
	v_pk_fma_f32 v[14:15], v[106:107], v[18:19], v[14:15] op_sel_hi:[0, 1, 1]
	s_waitcnt vmcnt(9)
	v_lshlrev_b32_e32 v18, 16, v39
	v_and_b32_e32 v19, 0xffff0000, v39
	v_pk_fma_f32 v[116:117], v[84:85], v[116:117], 0 op_sel_hi:[0, 1, 0]
	v_pk_fma_f32 v[18:19], v[104:105], v[18:19], v[14:15] op_sel_hi:[0, 1, 1]
	v_lshlrev_b32_e32 v14, 16, v16
	v_and_b32_e32 v15, 0xffff0000, v16
	v_pk_fma_f32 v[116:117], v[114:115], v[118:119], v[116:117] op_sel_hi:[0, 1, 1]
	v_lshlrev_b32_e32 v118, 16, v22
	v_and_b32_e32 v119, 0xffff0000, v22
	v_pk_fma_f32 v[14:15], v[84:85], v[14:15], 0 op_sel_hi:[0, 1, 0]
	v_lshlrev_b32_e32 v22, 16, v20
	v_and_b32_e32 v23, 0xffff0000, v20
	v_pk_fma_f32 v[14:15], v[114:115], v[22:23], v[14:15] op_sel_hi:[0, 1, 1]
	v_lshlrev_b32_e32 v22, 16, v24
	v_and_b32_e32 v23, 0xffff0000, v24
	v_pk_fma_f32 v[14:15], v[112:113], v[22:23], v[14:15] op_sel_hi:[0, 1, 1]
	v_lshlrev_b32_e32 v22, 16, v28
	v_and_b32_e32 v23, 0xffff0000, v28
	v_pk_fma_f32 v[14:15], v[110:111], v[22:23], v[14:15] op_sel_hi:[0, 1, 1]
	v_lshlrev_b32_e32 v22, 16, v32
	v_and_b32_e32 v23, 0xffff0000, v32
	v_pk_fma_f32 v[14:15], v[108:109], v[22:23], v[14:15] op_sel_hi:[0, 1, 1]
	v_lshlrev_b32_e32 v22, 16, v36
	v_and_b32_e32 v23, 0xffff0000, v36
	v_pk_fma_f32 v[14:15], v[106:107], v[22:23], v[14:15] op_sel_hi:[0, 1, 1]
	v_lshlrev_b32_e32 v22, 16, v40
	v_and_b32_e32 v23, 0xffff0000, v40
	v_pk_fma_f32 v[22:23], v[104:105], v[22:23], v[14:15] op_sel_hi:[0, 1, 1]
	v_lshlrev_b32_e32 v14, 16, v17
	v_and_b32_e32 v15, 0xffff0000, v17
	v_pk_fma_f32 v[14:15], v[84:85], v[14:15], 0 op_sel_hi:[0, 1, 0]
	v_lshlrev_b32_e32 v16, 16, v21
	v_and_b32_e32 v17, 0xffff0000, v21
	v_pk_fma_f32 v[14:15], v[114:115], v[16:17], v[14:15] op_sel_hi:[0, 1, 1]
	v_lshlrev_b32_e32 v16, 16, v25
	v_and_b32_e32 v17, 0xffff0000, v25
	v_pk_fma_f32 v[116:117], v[112:113], v[118:119], v[116:117] op_sel_hi:[0, 1, 1]
	v_lshlrev_b32_e32 v118, 16, v26
	v_and_b32_e32 v119, 0xffff0000, v26
	v_pk_fma_f32 v[14:15], v[112:113], v[16:17], v[14:15] op_sel_hi:[0, 1, 1]
	v_lshlrev_b32_e32 v16, 16, v29
	v_and_b32_e32 v17, 0xffff0000, v29
	v_pk_fma_f32 v[116:117], v[110:111], v[118:119], v[116:117] op_sel_hi:[0, 1, 1]
	v_lshlrev_b32_e32 v118, 16, v30
	v_and_b32_e32 v119, 0xffff0000, v30
	v_pk_fma_f32 v[14:15], v[110:111], v[16:17], v[14:15] op_sel_hi:[0, 1, 1]
	v_lshlrev_b32_e32 v16, 16, v33
	v_and_b32_e32 v17, 0xffff0000, v33
	v_pk_fma_f32 v[116:117], v[108:109], v[118:119], v[116:117] op_sel_hi:[0, 1, 1]
	v_lshlrev_b32_e32 v118, 16, v34
	v_and_b32_e32 v119, 0xffff0000, v34
	v_pk_fma_f32 v[14:15], v[108:109], v[16:17], v[14:15] op_sel_hi:[0, 1, 1]
	v_lshlrev_b32_e32 v16, 16, v37
	v_and_b32_e32 v17, 0xffff0000, v37
	v_pk_fma_f32 v[116:117], v[106:107], v[118:119], v[116:117] op_sel_hi:[0, 1, 1]
	v_lshlrev_b32_e32 v118, 16, v38
	v_and_b32_e32 v119, 0xffff0000, v38
	v_pk_fma_f32 v[14:15], v[106:107], v[16:17], v[14:15] op_sel_hi:[0, 1, 1]
	v_lshlrev_b32_e32 v16, 16, v41
	v_and_b32_e32 v17, 0xffff0000, v41
	v_pk_fma_f32 v[116:117], v[104:105], v[118:119], v[116:117] op_sel_hi:[0, 1, 1]
	v_pk_fma_f32 v[20:21], v[104:105], v[16:17], v[14:15] op_sel_hi:[0, 1, 1]
	s_waitcnt vmcnt(8)
	v_lshlrev_b32_e32 v14, 16, v50
	v_and_b32_e32 v15, 0xffff0000, v50
	v_lshlrev_b32_e32 v24, 16, v52
	v_and_b32_e32 v25, 0xffff0000, v52
	v_lshlrev_b32_e32 v26, 16, v53
	v_and_b32_e32 v27, 0xffff0000, v53
	v_pk_fma_f32 v[14:15], v[86:87], v[14:15], v[116:117] op_sel_hi:[0, 1, 1]
	s_waitcnt vmcnt(7)
	v_lshlrev_b32_e32 v52, 16, v42
	v_and_b32_e32 v53, 0xffff0000, v42
	s_waitcnt vmcnt(6)
	v_lshlrev_b32_e32 v28, 16, v62
	v_and_b32_e32 v29, 0xffff0000, v62
	v_pk_fma_f32 v[14:15], v[88:89], v[52:53], v[14:15] op_sel_hi:[0, 1, 1]
	s_waitcnt vmcnt(5)
	v_lshlrev_b32_e32 v36, 16, v74
	v_and_b32_e32 v37, 0xffff0000, v74
	v_pk_fma_f32 v[14:15], v[90:91], v[28:29], v[14:15] op_sel_hi:[0, 1, 1]
	v_pk_fma_f32 v[14:15], v[94:95], v[36:37], v[14:15] op_sel_hi:[0, 1, 1]
	s_waitcnt vmcnt(4)
	v_lshlrev_b32_e32 v28, 16, v46
	v_and_b32_e32 v29, 0xffff0000, v46
	v_lshlrev_b32_e32 v16, 16, v51
	v_and_b32_e32 v17, 0xffff0000, v51
	v_pk_fma_f32 v[14:15], v[102:103], v[28:29], v[14:15] op_sel_hi:[0, 1, 1]
	s_waitcnt vmcnt(3)
	v_lshlrev_b32_e32 v28, 16, v54
	v_and_b32_e32 v29, 0xffff0000, v54
	v_pk_fma_f32 v[14:15], v[100:101], v[28:29], v[14:15] op_sel_hi:[0, 1, 1]
	s_waitcnt vmcnt(2)
	v_lshlrev_b32_e32 v28, 16, v58
	v_and_b32_e32 v29, 0xffff0000, v58
	v_pk_fma_f32 v[16:17], v[86:87], v[16:17], v[18:19] op_sel_hi:[0, 1, 1]
	v_lshlrev_b32_e32 v18, 16, v43
	v_and_b32_e32 v19, 0xffff0000, v43
	v_lshlrev_b32_e32 v30, 16, v63
	v_and_b32_e32 v31, 0xffff0000, v63
	v_pk_fma_f32 v[14:15], v[98:99], v[28:29], v[14:15] op_sel_hi:[0, 1, 1]
	s_waitcnt vmcnt(1)
	v_lshlrev_b32_e32 v28, 16, v66
	v_and_b32_e32 v29, 0xffff0000, v66
	v_pk_fma_f32 v[16:17], v[88:89], v[18:19], v[16:17] op_sel_hi:[0, 1, 1]
	v_lshlrev_b32_e32 v38, 16, v75
	v_and_b32_e32 v39, 0xffff0000, v75
	v_pk_fma_f32 v[14:15], v[96:97], v[28:29], v[14:15] op_sel_hi:[0, 1, 1]
	s_waitcnt vmcnt(0)
	v_lshlrev_b32_e32 v28, 16, v70
	v_and_b32_e32 v29, 0xffff0000, v70
	v_pk_fma_f32 v[16:17], v[90:91], v[30:31], v[16:17] op_sel_hi:[0, 1, 1]
	v_pk_fma_f32 v[14:15], v[92:93], v[28:29], v[14:15] op_sel_hi:[0, 1, 1]
	v_pk_fma_f32 v[16:17], v[94:95], v[38:39], v[16:17] op_sel_hi:[0, 1, 1]
	v_lshlrev_b32_e32 v28, 16, v47
	v_and_b32_e32 v29, 0xffff0000, v47
	v_pk_fma_f32 v[16:17], v[102:103], v[28:29], v[16:17] op_sel_hi:[0, 1, 1]
	v_lshlrev_b32_e32 v28, 16, v55
	v_and_b32_e32 v29, 0xffff0000, v55
	v_pk_fma_f32 v[16:17], v[100:101], v[28:29], v[16:17] op_sel_hi:[0, 1, 1]
	v_lshlrev_b32_e32 v28, 16, v59
	v_and_b32_e32 v29, 0xffff0000, v59
	v_pk_fma_f32 v[16:17], v[98:99], v[28:29], v[16:17] op_sel_hi:[0, 1, 1]
	v_lshlrev_b32_e32 v28, 16, v67
	v_and_b32_e32 v29, 0xffff0000, v67
	v_pk_fma_f32 v[16:17], v[96:97], v[28:29], v[16:17] op_sel_hi:[0, 1, 1]
	v_lshlrev_b32_e32 v28, 16, v71
	v_and_b32_e32 v29, 0xffff0000, v71
	v_pk_fma_f32 v[16:17], v[92:93], v[28:29], v[16:17] op_sel_hi:[0, 1, 1]
	v_pk_fma_f32 v[14:15], v[82:83], v[14:15], v[52:53] op_sel_hi:[0, 1, 1] neg_lo:[0, 0, 1] neg_hi:[0, 0, 1]
	v_pk_fma_f32 v[16:17], v[82:83], v[16:17], v[18:19] op_sel_hi:[0, 1, 1] neg_lo:[0, 0, 1] neg_hi:[0, 0, 1]
	v_cvt_pk_bf16_f32 v14, v14, v15
	v_cvt_pk_bf16_f32 v15, v16, v17
	v_pk_fma_f32 v[16:17], v[86:87], v[24:25], v[22:23] op_sel_hi:[0, 1, 1]
	v_lshlrev_b32_e32 v18, 16, v44
	v_and_b32_e32 v19, 0xffff0000, v44
	v_lshlrev_b32_e32 v32, 16, v64
	v_and_b32_e32 v33, 0xffff0000, v64
	v_pk_fma_f32 v[16:17], v[88:89], v[18:19], v[16:17] op_sel_hi:[0, 1, 1]
	v_lshlrev_b32_e32 v40, 16, v76
	v_and_b32_e32 v41, 0xffff0000, v76
	v_pk_fma_f32 v[16:17], v[90:91], v[32:33], v[16:17] op_sel_hi:[0, 1, 1]
	v_pk_fma_f32 v[16:17], v[94:95], v[40:41], v[16:17] op_sel_hi:[0, 1, 1]
	v_lshlrev_b32_e32 v22, 16, v48
	v_and_b32_e32 v23, 0xffff0000, v48
	v_pk_fma_f32 v[16:17], v[102:103], v[22:23], v[16:17] op_sel_hi:[0, 1, 1]
	v_lshlrev_b32_e32 v22, 16, v56
	v_and_b32_e32 v23, 0xffff0000, v56
	v_pk_fma_f32 v[16:17], v[100:101], v[22:23], v[16:17] op_sel_hi:[0, 1, 1]
	v_lshlrev_b32_e32 v22, 16, v60
	v_and_b32_e32 v23, 0xffff0000, v60
	v_pk_fma_f32 v[16:17], v[98:99], v[22:23], v[16:17] op_sel_hi:[0, 1, 1]
	v_lshlrev_b32_e32 v22, 16, v68
	v_and_b32_e32 v23, 0xffff0000, v68
	v_pk_fma_f32 v[16:17], v[96:97], v[22:23], v[16:17] op_sel_hi:[0, 1, 1]
	v_lshlrev_b32_e32 v22, 16, v72
	v_and_b32_e32 v23, 0xffff0000, v72
	v_pk_fma_f32 v[16:17], v[92:93], v[22:23], v[16:17] op_sel_hi:[0, 1, 1]
	v_pk_fma_f32 v[16:17], v[82:83], v[16:17], v[18:19] op_sel_hi:[0, 1, 1] neg_lo:[0, 0, 1] neg_hi:[0, 0, 1]
	v_pk_fma_f32 v[18:19], v[86:87], v[26:27], v[20:21] op_sel_hi:[0, 1, 1]
	v_lshlrev_b32_e32 v20, 16, v45
	v_and_b32_e32 v21, 0xffff0000, v45
	v_lshlrev_b32_e32 v34, 16, v65
	v_and_b32_e32 v35, 0xffff0000, v65
	v_pk_fma_f32 v[18:19], v[88:89], v[20:21], v[18:19] op_sel_hi:[0, 1, 1]
	v_lshlrev_b32_e32 v50, 16, v77
	v_and_b32_e32 v51, 0xffff0000, v77
	v_pk_fma_f32 v[18:19], v[90:91], v[34:35], v[18:19] op_sel_hi:[0, 1, 1]
	v_pk_fma_f32 v[18:19], v[94:95], v[50:51], v[18:19] op_sel_hi:[0, 1, 1]
	v_lshlrev_b32_e32 v22, 16, v49
	v_and_b32_e32 v23, 0xffff0000, v49
	v_pk_fma_f32 v[18:19], v[102:103], v[22:23], v[18:19] op_sel_hi:[0, 1, 1]
	v_lshlrev_b32_e32 v22, 16, v57
	v_and_b32_e32 v23, 0xffff0000, v57
	v_pk_fma_f32 v[18:19], v[100:101], v[22:23], v[18:19] op_sel_hi:[0, 1, 1]
	v_lshlrev_b32_e32 v22, 16, v61
	v_and_b32_e32 v23, 0xffff0000, v61
	v_pk_fma_f32 v[18:19], v[98:99], v[22:23], v[18:19] op_sel_hi:[0, 1, 1]
	v_lshlrev_b32_e32 v22, 16, v69
	v_and_b32_e32 v23, 0xffff0000, v69
	v_pk_fma_f32 v[18:19], v[96:97], v[22:23], v[18:19] op_sel_hi:[0, 1, 1]
	v_lshlrev_b32_e32 v22, 16, v73
	v_and_b32_e32 v23, 0xffff0000, v73
	v_pk_fma_f32 v[18:19], v[92:93], v[22:23], v[18:19] op_sel_hi:[0, 1, 1]
	v_pk_fma_f32 v[18:19], v[82:83], v[18:19], v[20:21] op_sel_hi:[0, 1, 1] neg_lo:[0, 0, 1] neg_hi:[0, 0, 1]
	v_lshlrev_b64 v[20:21], 11, v[80:81]
	v_cvt_pk_bf16_f32 v16, v16, v17
	v_cvt_pk_bf16_f32 v17, v18, v19
	v_lshl_add_u64 v[18:19], s[74:75], 0, v[78:79]
	v_lshl_add_u64 v[30:31], s[84:85], 0, v[20:21]
	v_lshlrev_b32_e32 v20, 8, v85
	v_mov_b32_e32 v21, v1
	v_lshl_add_u64 v[28:29], v[18:19], 0, v[20:21]
	v_add_co_u32_e32 v56, vcc, 0x1000, v28
	s_nop 1
	v_addc_co_u32_e32 v57, vcc, 0, v29, vcc
	v_add_co_u32_e32 v58, vcc, 0x3000, v28
	s_nop 1
	v_addc_co_u32_e32 v59, vcc, 0, v29, vcc
	v_add_co_u32_e32 v60, vcc, 0x5000, v28
	s_nop 1
	v_addc_co_u32_e32 v61, vcc, 0, v29, vcc
	v_add_co_u32_e32 v62, vcc, 0x7000, v28
	s_nop 1
	v_addc_co_u32_e32 v63, vcc, 0, v29, vcc
	global_load_dwordx4 v[84:87], v[56:57], off offset:-4096
	global_load_dwordx4 v[88:91], v[56:57], off offset:-4032
	global_load_dwordx4 v[92:95], v[56:57], off offset:-3968
	global_load_dwordx4 v[96:99], v[56:57], off offset:-3904
	global_load_dwordx4 v[100:103], v78, s[30:31] offset:1536
	global_load_dwordx4 v[104:107], v[56:57], off
	global_load_dwordx4 v[108:111], v[56:57], off offset:64
	global_load_dwordx4 v[112:115], v[56:57], off offset:128
	global_load_dwordx4 v[116:119], v[56:57], off offset:192
	global_load_dwordx4 v[120:123], v78, s[30:31] offset:1600
	global_load_dwordx4 v[124:127], v[58:59], off offset:-4096
	global_load_dwordx4 v[128:131], v[58:59], off offset:-4032
	global_load_dwordx4 v[132:135], v[58:59], off offset:-3968
	global_load_dwordx4 v[136:139], v[58:59], off offset:-3904
	global_load_dwordx4 v[140:143], v78, s[30:31] offset:1664
	global_load_dwordx4 v[144:147], v[58:59], off
	global_load_dwordx4 v[148:151], v[58:59], off offset:64
	global_load_dwordx4 v[152:155], v[58:59], off offset:128
	global_load_dwordx4 v[156:159], v[58:59], off offset:192
	global_load_dwordx4 v[160:163], v78, s[30:31] offset:1728
	global_load_dwordx4 v[164:167], v[60:61], off offset:-4096
	global_load_dwordx4 v[168:171], v[60:61], off offset:-4032
	global_load_dwordx4 v[172:175], v[60:61], off offset:-3968
	global_load_dwordx4 v[176:179], v[60:61], off offset:-3904
	global_load_dwordx4 v[180:183], v78, s[30:31] offset:1792
	global_load_dwordx4 v[184:187], v[60:61], off
	global_load_dwordx4 v[188:191], v[60:61], off offset:64
	global_load_dwordx4 v[192:195], v[60:61], off offset:128
	global_load_dwordx4 v[196:199], v[60:61], off offset:192
	global_load_dwordx4 v[200:203], v78, s[30:31] offset:1856
	global_load_dwordx4 v[204:207], v[62:63], off offset:-4096
	global_load_dwordx4 v[222:225], v[62:63], off offset:-4032
	global_load_dwordx4 v[226:229], v[62:63], off offset:-3968
	global_load_dwordx4 v[230:233], v[62:63], off offset:-3904
	global_load_dwordx4 v[234:237], v78, s[30:31] offset:1920
	global_load_dwordx4 v[238:241], v[62:63], off
	global_load_dwordx4 v[242:245], v[62:63], off offset:64
	global_load_dwordx4 v[246:249], v[62:63], off offset:128
	global_load_dwordx4 v[52:55], v[62:63], off offset:192
	s_nop 0
	s_nop 0
	s_waitcnt vmcnt(38)
	v_mfma_f32_16x16x32_bf16 v[18:21], v[84:87], v[2:5], 0
	v_lshl_add_u64 v[26:27], v[30:31], 0, s[0:1]
	s_movk_i32 s0, 0x1000
	s_waitcnt vmcnt(37)
	v_mfma_f32_16x16x32_bf16 v[18:21], v[88:91], v[6:9], v[18:21]
	s_nop 0
	s_waitcnt vmcnt(36)
	v_mfma_f32_16x16x32_bf16 v[18:21], v[92:95], v[10:13], v[18:21]
	s_nop 0
	s_waitcnt vmcnt(35)
	v_mfma_f32_16x16x32_bf16 v[18:21], v[96:99], v[14:17], v[18:21]
	s_nop 0
	s_waitcnt vmcnt(34)
	s_nop 5
	v_pk_mul_f32 v[20:21], v[20:21], v[102:103]
	v_add_co_u32_e32 v24, vcc, s0, v28
	v_pk_mul_f32 v[18:19], v[18:19], v[100:101]
	s_nop 0
	v_addc_co_u32_e32 v25, vcc, 0, v29, vcc
	s_movk_i32 s0, 0x2000
	v_cvt_pk_bf16_f32 v22, v18, v19
	v_cvt_pk_bf16_f32 v23, v20, v21
	v_lshl_add_u64 v[18:19], v[30:31], 0, v[0:1]
	v_add_co_u32_e32 v34, vcc, s0, v28
	global_store_dwordx2 v[18:19], v[22:23], off offset:1792
	s_nop 0
	v_addc_co_u32_e32 v35, vcc, 0, v29, vcc
	s_nop 0
	s_nop 0
	s_waitcnt vmcnt(34)
	v_mfma_f32_16x16x32_bf16 v[20:23], v[104:107], v[2:5], 0
	s_movk_i32 s0, 0x3000
	v_mov_b32_e32 v0, 0x1f0
	v_lshl_or_b32 v0, v83, 2, v0
	s_waitcnt vmcnt(33)
	v_mfma_f32_16x16x32_bf16 v[20:23], v[108:111], v[6:9], v[20:23]
	s_nop 0
	s_waitcnt vmcnt(32)
	v_mfma_f32_16x16x32_bf16 v[20:23], v[112:115], v[10:13], v[20:23]
	s_nop 0
	v_add_co_u32_e32 v24, vcc, s0, v28
	s_waitcnt vmcnt(31)
	v_mfma_f32_16x16x32_bf16 v[20:23], v[116:119], v[14:17], v[20:23]
	s_nop 0
	v_addc_co_u32_e32 v25, vcc, 0, v29, vcc
	s_movk_i32 s0, 0x4000
	s_waitcnt vmcnt(30)
	s_nop 3
	v_pk_mul_f32 v[22:23], v[22:23], v[122:123]
	v_pk_mul_f32 v[20:21], v[20:21], v[120:121]
	s_nop 0
	v_cvt_pk_bf16_f32 v20, v20, v21
	v_cvt_pk_bf16_f32 v21, v22, v23
	global_store_dwordx2 v[18:19], v[20:21], off offset:1824
	s_nop 0
	s_nop 0
	s_nop 0
	s_waitcnt vmcnt(30)
	v_mfma_f32_16x16x32_bf16 v[20:23], v[124:127], v[2:5], 0
	s_waitcnt vmcnt(29)
	v_mfma_f32_16x16x32_bf16 v[20:23], v[128:131], v[6:9], v[20:23]
	s_nop 0
	s_waitcnt vmcnt(28)
	v_mfma_f32_16x16x32_bf16 v[20:23], v[132:135], v[10:13], v[20:23]
	s_nop 0
	v_add_co_u32_e32 v34, vcc, s0, v28
	s_waitcnt vmcnt(27)
	v_mfma_f32_16x16x32_bf16 v[20:23], v[136:139], v[14:17], v[20:23]
	s_nop 0
	v_addc_co_u32_e32 v35, vcc, 0, v29, vcc
	s_movk_i32 s0, 0x5000
	s_waitcnt vmcnt(26)
	s_nop 3
	v_pk_mul_f32 v[22:23], v[22:23], v[142:143]
	v_pk_mul_f32 v[20:21], v[20:21], v[140:141]
	s_nop 0
	v_cvt_pk_bf16_f32 v20, v20, v21
	v_cvt_pk_bf16_f32 v21, v22, v23
	global_store_dwordx2 v[18:19], v[20:21], off offset:1856
	s_nop 0
	s_nop 0
	s_nop 0
	s_waitcnt vmcnt(26)
	v_mfma_f32_16x16x32_bf16 v[20:23], v[144:147], v[2:5], 0
	s_waitcnt vmcnt(25)
	v_mfma_f32_16x16x32_bf16 v[20:23], v[148:151], v[6:9], v[20:23]
	s_nop 0
	s_waitcnt vmcnt(24)
	v_mfma_f32_16x16x32_bf16 v[20:23], v[152:155], v[10:13], v[20:23]
	s_nop 0
	v_add_co_u32_e32 v24, vcc, s0, v28
	s_waitcnt vmcnt(23)
	v_mfma_f32_16x16x32_bf16 v[20:23], v[156:159], v[14:17], v[20:23]
	s_nop 0
	v_addc_co_u32_e32 v25, vcc, 0, v29, vcc
	s_movk_i32 s0, 0x6000
	s_waitcnt vmcnt(22)
	s_nop 3
	v_pk_mul_f32 v[22:23], v[22:23], v[162:163]
	v_pk_mul_f32 v[20:21], v[20:21], v[160:161]
	s_nop 0
	v_cvt_pk_bf16_f32 v20, v20, v21
	v_cvt_pk_bf16_f32 v21, v22, v23
	global_store_dwordx2 v[18:19], v[20:21], off offset:1888
	s_nop 0
	s_nop 0
	s_nop 0
	s_waitcnt vmcnt(22)
	v_mfma_f32_16x16x32_bf16 v[20:23], v[164:167], v[2:5], 0
	s_waitcnt vmcnt(21)
	v_mfma_f32_16x16x32_bf16 v[20:23], v[168:171], v[6:9], v[20:23]
	s_nop 0
	s_waitcnt vmcnt(20)
	v_mfma_f32_16x16x32_bf16 v[20:23], v[172:175], v[10:13], v[20:23]
	s_nop 0
	v_add_co_u32_e32 v34, vcc, s0, v28
	s_waitcnt vmcnt(19)
	v_mfma_f32_16x16x32_bf16 v[20:23], v[176:179], v[14:17], v[20:23]
	s_nop 0
	v_addc_co_u32_e32 v35, vcc, 0, v29, vcc
	s_waitcnt vmcnt(18)
	s_nop 4
	v_pk_mul_f32 v[22:23], v[22:23], v[182:183]
	v_pk_mul_f32 v[20:21], v[20:21], v[180:181]
	s_nop 0
	v_cvt_pk_bf16_f32 v20, v20, v21
	v_cvt_pk_bf16_f32 v21, v22, v23
	global_store_dwordx2 v[18:19], v[20:21], off offset:1920
	s_nop 0
	s_nop 0
	s_nop 0
	s_waitcnt vmcnt(18)
	v_mfma_f32_16x16x32_bf16 v[20:23], v[184:187], v[2:5], 0
	s_waitcnt vmcnt(17)
	v_mfma_f32_16x16x32_bf16 v[20:23], v[188:191], v[6:9], v[20:23]
	s_nop 0
	s_waitcnt vmcnt(16)
	v_mfma_f32_16x16x32_bf16 v[20:23], v[192:195], v[10:13], v[20:23]
	s_nop 0
	s_waitcnt vmcnt(15)
	v_mfma_f32_16x16x32_bf16 v[20:23], v[196:199], v[14:17], v[20:23]
	s_nop 0
	s_waitcnt vmcnt(14)
	s_nop 5
	v_pk_mul_f32 v[22:23], v[22:23], v[202:203]
	v_pk_mul_f32 v[20:21], v[20:21], v[200:201]
	s_nop 0
	v_cvt_pk_bf16_f32 v20, v20, v21
	v_cvt_pk_bf16_f32 v21, v22, v23
	global_store_dwordx2 v[18:19], v[20:21], off offset:1952
	s_nop 0
	s_nop 0
	s_nop 0
	s_waitcnt vmcnt(14)
	v_mfma_f32_16x16x32_bf16 v[20:23], v[204:207], v[2:5], 0
	s_waitcnt vmcnt(13)
	v_mfma_f32_16x16x32_bf16 v[20:23], v[222:225], v[6:9], v[20:23]
	s_nop 0
	s_waitcnt vmcnt(12)
	v_mfma_f32_16x16x32_bf16 v[20:23], v[226:229], v[10:13], v[20:23]
	s_nop 0
	s_waitcnt vmcnt(11)
	v_mfma_f32_16x16x32_bf16 v[20:23], v[230:233], v[14:17], v[20:23]
	s_nop 0
	s_waitcnt vmcnt(10)
	s_nop 5
	v_pk_mul_f32 v[22:23], v[22:23], v[236:237]
	v_pk_mul_f32 v[20:21], v[20:21], v[234:235]
	s_nop 0
	v_cvt_pk_bf16_f32 v20, v20, v21
	v_cvt_pk_bf16_f32 v21, v22, v23
	v_add_co_u32_e32 v22, vcc, 0x7000, v28
	global_store_dwordx2 v[18:19], v[20:21], off offset:1984
	s_nop 0
	v_addc_co_u32_e32 v23, vcc, 0, v29, vcc
	s_nop 0
	s_waitcnt vmcnt(10)
	v_mfma_f32_16x16x32_bf16 v[2:5], v[238:241], v[2:5], 0
	s_nop 0
	s_waitcnt vmcnt(9)
	v_mfma_f32_16x16x32_bf16 v[2:5], v[242:245], v[6:9], v[2:5]
	s_nop 0
	s_waitcnt vmcnt(8)
	v_mfma_f32_16x16x32_bf16 v[2:5], v[246:249], v[10:13], v[2:5]
	s_nop 0
	s_waitcnt vmcnt(7)
	v_mfma_f32_16x16x32_bf16 v[2:5], v[52:55], v[14:17], v[2:5]
	s_cbranch_execnz .LBB0_579
.LBB0_593:
	v_mov_b32_e32 v0, v209
	v_mov_b32_e32 v29, v1
	v_readfirstlane_b32 s0, v0
	s_ashr_i32 s0, s0, 2
	v_and_b32_e32 v23, 15, v0
	s_nop 1
	v_bfi_b32 v2, -16, s0, v0
	v_add_u32_e32 v20, s59, v2
	s_mov_b32 s0, 0x38e38e39
	v_bfe_u32 v34, v0, 4, 2
	v_mul_hi_i32 v0, v20, s0
	v_lshrrev_b32_e32 v3, 31, v0
	v_ashrrev_i32_e32 v0, 13, v0
	v_add_u32_e32 v0, v0, v3
	v_mul_i32_i24_e32 v0, 0x9000, v0
	v_sub_u32_e32 v0, v20, v0
	s_mov_b32 s0, 0x8000
	v_cmp_gt_i32_e32 vcc, s0, v0
	v_lshlrev_b32_e32 v28, 4, v34
	v_ashrrev_i32_e32 v21, 31, v20
	v_cndmask_b32_e32 v3, v220, v221, vcc
	v_and_b32_e32 v11, v3, v0
	v_cndmask_b32_e32 v10, v217, v210, vcc
	v_add_u32_e32 v3, -1, v11
	v_add_u32_e32 v4, 1, v11
	v_max_i32_e32 v0, 0, v3
	v_min_u32_e32 v4, v4, v10
	v_sub_u32_e32 v0, v4, v0
	v_cvt_f32_i32_e32 v0, v0
	v_div_scale_f32 v4, s[0:1], v0, v0, 1.0
	v_rcp_f32_e32 v5, v4
	v_readlane_b32 s0, v253, 62
	v_readlane_b32 s1, v253, 63
	v_fma_f32 v6, -v4, v5, 1.0
	v_fmac_f32_e32 v5, v6, v5
	v_div_scale_f32 v6, vcc, 1.0, v0, 1.0
	v_mul_f32_e32 v7, v6, v5
	v_fma_f32 v8, -v4, v7, v6
	v_fmac_f32_e32 v7, v8, v5
	v_fma_f32 v4, -v4, v7, v6
	v_div_fmas_f32 v4, v4, v5, v7
	v_cmp_lt_u32_e32 vcc, v3, v10
	v_lshl_add_u64 v[8:9], s[0:1], 0, v[28:29]
	v_lshlrev_b64 v[6:7], 10, v[20:21]
	v_cndmask_b32_e32 v3, v11, v3, vcc
	v_add_u32_e32 v2, v2, v3
	v_sub_u32_e32 v2, v2, v11
	v_add_u32_e32 v2, s59, v2
	v_ashrrev_i32_e32 v3, 31, v2
	v_lshlrev_b64 v[2:3], 10, v[2:3]
	v_lshl_add_u64 v[14:15], v[8:9], 0, v[2:3]
	v_div_fixup_f32 v18, v4, v0, 1.0
	global_load_dwordx4 v[2:5], v[14:15], off
	v_lshl_add_u64 v[16:17], v[8:9], 0, v[6:7]
	global_load_dwordx4 v[6:9], v[16:17], off
	global_load_dwordx4 v[92:95], v[14:15], off offset:64
	global_load_dwordx4 v[96:99], v[16:17], off offset:64
	global_load_dwordx4 v[100:103], v[14:15], off offset:128
	global_load_dwordx4 v[104:107], v[16:17], off offset:128
	global_load_dwordx4 v[108:111], v[14:15], off offset:192
	global_load_dwordx4 v[112:115], v[16:17], off offset:192
	v_cndmask_b32_e64 v22, 0, 1.0, vcc
	v_cmp_lt_u32_e32 vcc, v11, v10
	v_lshlrev_b64 v[20:21], 11, v[20:21]
	s_mov_b64 s[0:1], 0x400
	v_cndmask_b32_e64 v24, 0, 1.0, vcc
	v_lshlrev_b32_e32 v0, 3, v34
	s_waitcnt vmcnt(7)
	v_lshlrev_b32_e32 v10, 16, v2
	v_and_b32_e32 v11, 0xffff0000, v2
	v_pk_fma_f32 v[10:11], v[22:23], v[10:11], 0 op_sel_hi:[0, 1, 0]
	s_waitcnt vmcnt(6)
	v_lshlrev_b32_e32 v12, 16, v6
	v_and_b32_e32 v13, 0xffff0000, v6
	v_pk_fma_f32 v[10:11], v[24:25], v[12:13], v[10:11] op_sel_hi:[0, 1, 1]
	v_pk_fma_f32 v[10:11], v[18:19], v[10:11], v[12:13] op_sel_hi:[0, 1, 1] neg_lo:[0, 0, 1] neg_hi:[0, 0, 1]
	v_cvt_pk_bf16_f32 v2, v10, v11
	v_lshlrev_b32_e32 v10, 16, v3
	v_and_b32_e32 v11, 0xffff0000, v3
	v_pk_fma_f32 v[10:11], v[22:23], v[10:11], 0 op_sel_hi:[0, 1, 0]
	v_lshlrev_b32_e32 v6, 16, v7
	v_and_b32_e32 v7, 0xffff0000, v7
	v_pk_fma_f32 v[10:11], v[24:25], v[6:7], v[10:11] op_sel_hi:[0, 1, 1]
	v_pk_fma_f32 v[6:7], v[18:19], v[10:11], v[6:7] op_sel_hi:[0, 1, 1] neg_lo:[0, 0, 1] neg_hi:[0, 0, 1]
	v_cvt_pk_bf16_f32 v3, v6, v7
	v_lshlrev_b32_e32 v6, 16, v4
	v_and_b32_e32 v7, 0xffff0000, v4
	v_pk_fma_f32 v[6:7], v[22:23], v[6:7], 0 op_sel_hi:[0, 1, 0]
	v_lshlrev_b32_e32 v10, 16, v8
	v_and_b32_e32 v11, 0xffff0000, v8
	v_pk_fma_f32 v[6:7], v[24:25], v[10:11], v[6:7] op_sel_hi:[0, 1, 1]
	v_pk_fma_f32 v[6:7], v[18:19], v[6:7], v[10:11] op_sel_hi:[0, 1, 1] neg_lo:[0, 0, 1] neg_hi:[0, 0, 1]
	v_cvt_pk_bf16_f32 v4, v6, v7
	v_lshlrev_b32_e32 v6, 16, v5
	v_and_b32_e32 v7, 0xffff0000, v5
	v_pk_fma_f32 v[6:7], v[22:23], v[6:7], 0 op_sel_hi:[0, 1, 0]
	v_lshlrev_b32_e32 v8, 16, v9
	v_and_b32_e32 v9, 0xffff0000, v9
	v_pk_fma_f32 v[6:7], v[24:25], v[8:9], v[6:7] op_sel_hi:[0, 1, 1]
	v_pk_fma_f32 v[6:7], v[18:19], v[6:7], v[8:9] op_sel_hi:[0, 1, 1] neg_lo:[0, 0, 1] neg_hi:[0, 0, 1]
	v_cvt_pk_bf16_f32 v5, v6, v7
	s_nop 0
	s_nop 0
	s_waitcnt vmcnt(5)
	v_lshlrev_b32_e32 v26, 16, v92
	v_and_b32_e32 v27, 0xffff0000, v92
	v_pk_fma_f32 v[26:27], v[22:23], v[26:27], 0 op_sel_hi:[0, 1, 0]
	s_waitcnt vmcnt(4)
	v_lshlrev_b32_e32 v30, 16, v96
	v_and_b32_e32 v31, 0xffff0000, v96
	v_pk_fma_f32 v[26:27], v[24:25], v[30:31], v[26:27] op_sel_hi:[0, 1, 1]
	v_pk_fma_f32 v[26:27], v[18:19], v[26:27], v[30:31] op_sel_hi:[0, 1, 1] neg_lo:[0, 0, 1] neg_hi:[0, 0, 1]
	v_cvt_pk_bf16_f32 v6, v26, v27
	v_lshlrev_b32_e32 v26, 16, v93
	v_and_b32_e32 v27, 0xffff0000, v93
	v_pk_fma_f32 v[26:27], v[22:23], v[26:27], 0 op_sel_hi:[0, 1, 0]
	v_lshlrev_b32_e32 v10, 16, v97
	v_and_b32_e32 v11, 0xffff0000, v97
	v_pk_fma_f32 v[26:27], v[24:25], v[10:11], v[26:27] op_sel_hi:[0, 1, 1]
	v_pk_fma_f32 v[10:11], v[18:19], v[26:27], v[10:11] op_sel_hi:[0, 1, 1] neg_lo:[0, 0, 1] neg_hi:[0, 0, 1]
	v_cvt_pk_bf16_f32 v7, v10, v11
	v_lshlrev_b32_e32 v10, 16, v94
	v_and_b32_e32 v11, 0xffff0000, v94
	v_pk_fma_f32 v[10:11], v[22:23], v[10:11], 0 op_sel_hi:[0, 1, 0]
	v_lshlrev_b32_e32 v26, 16, v98
	v_and_b32_e32 v27, 0xffff0000, v98
	v_pk_fma_f32 v[10:11], v[24:25], v[26:27], v[10:11] op_sel_hi:[0, 1, 1]
	v_pk_fma_f32 v[10:11], v[18:19], v[10:11], v[26:27] op_sel_hi:[0, 1, 1] neg_lo:[0, 0, 1] neg_hi:[0, 0, 1]
	v_cvt_pk_bf16_f32 v8, v10, v11
	v_lshlrev_b32_e32 v10, 16, v95
	v_and_b32_e32 v11, 0xffff0000, v95
	v_pk_fma_f32 v[10:11], v[22:23], v[10:11], 0 op_sel_hi:[0, 1, 0]
	v_lshlrev_b32_e32 v12, 16, v99
	v_and_b32_e32 v13, 0xffff0000, v99
	v_pk_fma_f32 v[10:11], v[24:25], v[12:13], v[10:11] op_sel_hi:[0, 1, 1]
	v_pk_fma_f32 v[10:11], v[18:19], v[10:11], v[12:13] op_sel_hi:[0, 1, 1] neg_lo:[0, 0, 1] neg_hi:[0, 0, 1]
	v_cvt_pk_bf16_f32 v9, v10, v11
	s_nop 0
	s_nop 0
	s_waitcnt vmcnt(3)
	v_lshlrev_b32_e32 v26, 16, v100
	v_and_b32_e32 v27, 0xffff0000, v100
	v_pk_fma_f32 v[26:27], v[22:23], v[26:27], 0 op_sel_hi:[0, 1, 0]
	s_waitcnt vmcnt(2)
	v_lshlrev_b32_e32 v36, 16, v104
	v_and_b32_e32 v37, 0xffff0000, v104
	v_pk_fma_f32 v[26:27], v[24:25], v[36:37], v[26:27] op_sel_hi:[0, 1, 1]
	v_pk_fma_f32 v[26:27], v[18:19], v[26:27], v[36:37] op_sel_hi:[0, 1, 1] neg_lo:[0, 0, 1] neg_hi:[0, 0, 1]
	v_cvt_pk_bf16_f32 v10, v26, v27
	v_lshlrev_b32_e32 v26, 16, v101
	v_and_b32_e32 v27, 0xffff0000, v101
	v_pk_fma_f32 v[26:27], v[22:23], v[26:27], 0 op_sel_hi:[0, 1, 0]
	v_lshlrev_b32_e32 v30, 16, v105
	v_and_b32_e32 v31, 0xffff0000, v105
	v_pk_fma_f32 v[26:27], v[24:25], v[30:31], v[26:27] op_sel_hi:[0, 1, 1]
	v_pk_fma_f32 v[26:27], v[18:19], v[26:27], v[30:31] op_sel_hi:[0, 1, 1] neg_lo:[0, 0, 1] neg_hi:[0, 0, 1]
	v_cvt_pk_bf16_f32 v11, v26, v27
	v_lshlrev_b32_e32 v26, 16, v102
	v_and_b32_e32 v27, 0xffff0000, v102
	v_pk_fma_f32 v[26:27], v[22:23], v[26:27], 0 op_sel_hi:[0, 1, 0]
	v_lshlrev_b32_e32 v30, 16, v106
	v_and_b32_e32 v31, 0xffff0000, v106
	v_pk_fma_f32 v[26:27], v[24:25], v[30:31], v[26:27] op_sel_hi:[0, 1, 1]
	v_pk_fma_f32 v[26:27], v[18:19], v[26:27], v[30:31] op_sel_hi:[0, 1, 1] neg_lo:[0, 0, 1] neg_hi:[0, 0, 1]
	v_cvt_pk_bf16_f32 v12, v26, v27
	v_lshlrev_b32_e32 v26, 16, v103
	v_and_b32_e32 v27, 0xffff0000, v103
	v_pk_fma_f32 v[26:27], v[22:23], v[26:27], 0 op_sel_hi:[0, 1, 0]
	v_lshlrev_b32_e32 v30, 16, v107
	v_and_b32_e32 v31, 0xffff0000, v107
	v_pk_fma_f32 v[26:27], v[24:25], v[30:31], v[26:27] op_sel_hi:[0, 1, 1]
	v_pk_fma_f32 v[26:27], v[18:19], v[26:27], v[30:31] op_sel_hi:[0, 1, 1] neg_lo:[0, 0, 1] neg_hi:[0, 0, 1]
	s_nop 0
	s_nop 0
	s_nop 0
	v_cvt_pk_bf16_f32 v13, v26, v27
	s_waitcnt vmcnt(1)
	v_lshlrev_b32_e32 v26, 16, v108
	v_and_b32_e32 v27, 0xffff0000, v108
	v_pk_fma_f32 v[26:27], v[22:23], v[26:27], 0 op_sel_hi:[0, 1, 0]
	s_waitcnt vmcnt(0)
	v_lshlrev_b32_e32 v36, 16, v112
	v_and_b32_e32 v37, 0xffff0000, v112
	v_pk_fma_f32 v[26:27], v[24:25], v[36:37], v[26:27] op_sel_hi:[0, 1, 1]
	v_pk_fma_f32 v[26:27], v[18:19], v[26:27], v[36:37] op_sel_hi:[0, 1, 1] neg_lo:[0, 0, 1] neg_hi:[0, 0, 1]
	v_cvt_pk_bf16_f32 v14, v26, v27
	v_lshlrev_b32_e32 v26, 16, v109
	v_and_b32_e32 v27, 0xffff0000, v109
	v_pk_fma_f32 v[26:27], v[22:23], v[26:27], 0 op_sel_hi:[0, 1, 0]
	v_lshlrev_b32_e32 v30, 16, v113
	v_and_b32_e32 v31, 0xffff0000, v113
	v_pk_fma_f32 v[26:27], v[24:25], v[30:31], v[26:27] op_sel_hi:[0, 1, 1]
	v_pk_fma_f32 v[26:27], v[18:19], v[26:27], v[30:31] op_sel_hi:[0, 1, 1] neg_lo:[0, 0, 1] neg_hi:[0, 0, 1]
	v_cvt_pk_bf16_f32 v15, v26, v27
	v_lshlrev_b32_e32 v26, 16, v110
	v_and_b32_e32 v27, 0xffff0000, v110
	v_pk_fma_f32 v[26:27], v[22:23], v[26:27], 0 op_sel_hi:[0, 1, 0]
	v_lshlrev_b32_e32 v30, 16, v114
	v_and_b32_e32 v31, 0xffff0000, v114
	v_pk_fma_f32 v[26:27], v[24:25], v[30:31], v[26:27] op_sel_hi:[0, 1, 1]
	v_pk_fma_f32 v[26:27], v[18:19], v[26:27], v[30:31] op_sel_hi:[0, 1, 1] neg_lo:[0, 0, 1] neg_hi:[0, 0, 1]
	v_cvt_pk_bf16_f32 v16, v26, v27
	v_lshlrev_b32_e32 v26, 16, v111
	v_and_b32_e32 v27, 0xffff0000, v111
	v_pk_fma_f32 v[26:27], v[22:23], v[26:27], 0 op_sel_hi:[0, 1, 0]
	v_lshlrev_b32_e32 v30, 16, v115
	v_and_b32_e32 v31, 0xffff0000, v115
	v_pk_fma_f32 v[24:25], v[24:25], v[30:31], v[26:27] op_sel_hi:[0, 1, 1]
	v_pk_fma_f32 v[18:19], v[18:19], v[24:25], v[30:31] op_sel_hi:[0, 1, 1] neg_lo:[0, 0, 1] neg_hi:[0, 0, 1]
	v_cvt_pk_bf16_f32 v17, v18, v19
	v_lshl_add_u64 v[18:19], s[38:39], 0, v[28:29]
	v_lshl_add_u64 v[30:31], s[84:85], 0, v[20:21]
	v_lshlrev_b32_e32 v20, 8, v23
	v_mov_b32_e32 v21, v1
	v_lshl_add_u64 v[32:33], v[18:19], 0, v[20:21]
	v_add_co_u32_e32 v56, vcc, 0x1000, v32
	s_nop 1
	v_addc_co_u32_e32 v57, vcc, 0, v33, vcc
	v_add_co_u32_e32 v58, vcc, 0x3000, v32
	s_nop 1
	v_addc_co_u32_e32 v59, vcc, 0, v33, vcc
	v_add_co_u32_e32 v60, vcc, 0x5000, v32
	s_nop 1
	v_addc_co_u32_e32 v61, vcc, 0, v33, vcc
	v_add_co_u32_e32 v62, vcc, 0x7000, v32
	s_nop 1
	v_addc_co_u32_e32 v63, vcc, 0, v33, vcc
	global_load_dwordx4 v[84:87], v[56:57], off offset:-4096
	global_load_dwordx4 v[88:91], v[56:57], off offset:-4032
	global_load_dwordx4 v[92:95], v[56:57], off offset:-3968
	global_load_dwordx4 v[96:99], v[56:57], off offset:-3904
	global_load_dwordx4 v[100:103], v28, s[30:31]
	global_load_dwordx4 v[104:107], v[56:57], off
	global_load_dwordx4 v[108:111], v[56:57], off offset:64
	global_load_dwordx4 v[112:115], v[56:57], off offset:128
	global_load_dwordx4 v[116:119], v[56:57], off offset:192
	global_load_dwordx4 v[120:123], v28, s[30:31] offset:64
	global_load_dwordx4 v[124:127], v[58:59], off offset:-4096
	global_load_dwordx4 v[128:131], v[58:59], off offset:-4032
	global_load_dwordx4 v[132:135], v[58:59], off offset:-3968
	global_load_dwordx4 v[136:139], v[58:59], off offset:-3904
	global_load_dwordx4 v[140:143], v28, s[30:31] offset:128
	global_load_dwordx4 v[144:147], v[58:59], off
	global_load_dwordx4 v[148:151], v[58:59], off offset:64
	global_load_dwordx4 v[152:155], v[58:59], off offset:128
	global_load_dwordx4 v[156:159], v[58:59], off offset:192
	global_load_dwordx4 v[160:163], v28, s[30:31] offset:192
	global_load_dwordx4 v[164:167], v[60:61], off offset:-4096
	global_load_dwordx4 v[168:171], v[60:61], off offset:-4032
	global_load_dwordx4 v[172:175], v[60:61], off offset:-3968
	global_load_dwordx4 v[176:179], v[60:61], off offset:-3904
	global_load_dwordx4 v[180:183], v28, s[30:31] offset:256
	global_load_dwordx4 v[184:187], v[60:61], off
	global_load_dwordx4 v[188:191], v[60:61], off offset:64
	global_load_dwordx4 v[192:195], v[60:61], off offset:128
	global_load_dwordx4 v[196:199], v[60:61], off offset:192
	global_load_dwordx4 v[200:203], v28, s[30:31] offset:320
	global_load_dwordx4 v[204:207], v[62:63], off offset:-4096
	global_load_dwordx4 v[222:225], v[62:63], off offset:-4032
	global_load_dwordx4 v[226:229], v[62:63], off offset:-3968
	global_load_dwordx4 v[230:233], v[62:63], off offset:-3904
	global_load_dwordx4 v[234:237], v28, s[30:31] offset:384
	global_load_dwordx4 v[238:241], v[62:63], off
	global_load_dwordx4 v[242:245], v[62:63], off offset:64
	global_load_dwordx4 v[246:249], v[62:63], off offset:128
	global_load_dwordx4 v[52:55], v[62:63], off offset:192
	s_nop 0
	s_nop 0
	s_waitcnt vmcnt(38)
	v_mfma_f32_16x16x32_bf16 v[18:21], v[84:87], v[2:5], 0
	v_lshl_add_u64 v[26:27], v[30:31], 0, s[0:1]
	s_movk_i32 s0, 0x1000
	s_waitcnt vmcnt(37)
	v_mfma_f32_16x16x32_bf16 v[18:21], v[88:91], v[6:9], v[18:21]
	s_nop 0
	s_waitcnt vmcnt(36)
	v_mfma_f32_16x16x32_bf16 v[18:21], v[92:95], v[10:13], v[18:21]
	s_nop 0
	s_waitcnt vmcnt(35)
	v_mfma_f32_16x16x32_bf16 v[18:21], v[96:99], v[14:17], v[18:21]
	s_nop 0
	s_waitcnt vmcnt(34)
	s_nop 5
	v_pk_mul_f32 v[20:21], v[20:21], v[102:103]
	v_add_co_u32_e32 v24, vcc, s0, v32
	v_pk_mul_f32 v[18:19], v[18:19], v[100:101]
	s_nop 0
	v_addc_co_u32_e32 v25, vcc, 0, v33, vcc
	s_movk_i32 s0, 0x2000
	v_cvt_pk_bf16_f32 v22, v18, v19
	v_cvt_pk_bf16_f32 v23, v20, v21
	v_lshl_add_u64 v[18:19], v[30:31], 0, v[0:1]
	v_add_co_u32_e32 v30, vcc, s0, v32
	global_store_dwordx2 v[18:19], v[22:23], off offset:1024
	s_nop 0
	v_addc_co_u32_e32 v31, vcc, 0, v33, vcc
	s_nop 0
	s_nop 0
	s_waitcnt vmcnt(34)
	v_mfma_f32_16x16x32_bf16 v[20:23], v[104:107], v[2:5], 0
	s_movk_i32 s0, 0x3000
	v_mov_b32_e32 v0, 0x70
	v_lshl_or_b32 v0, v34, 2, v0
	s_waitcnt vmcnt(33)
	v_mfma_f32_16x16x32_bf16 v[20:23], v[108:111], v[6:9], v[20:23]
	s_nop 0
	s_waitcnt vmcnt(32)
	v_mfma_f32_16x16x32_bf16 v[20:23], v[112:115], v[10:13], v[20:23]
	s_nop 0
	v_add_co_u32_e32 v24, vcc, s0, v32
	s_waitcnt vmcnt(31)
	v_mfma_f32_16x16x32_bf16 v[20:23], v[116:119], v[14:17], v[20:23]
	s_nop 0
	v_addc_co_u32_e32 v25, vcc, 0, v33, vcc
	s_movk_i32 s0, 0x4000
	s_waitcnt vmcnt(30)
	s_nop 3
	v_pk_mul_f32 v[22:23], v[22:23], v[122:123]
	v_pk_mul_f32 v[20:21], v[20:21], v[120:121]
	s_nop 0
	v_cvt_pk_bf16_f32 v20, v20, v21
	v_cvt_pk_bf16_f32 v21, v22, v23
	global_store_dwordx2 v[18:19], v[20:21], off offset:1056
	s_nop 0
	s_nop 0
	s_nop 0
	s_waitcnt vmcnt(30)
	v_mfma_f32_16x16x32_bf16 v[20:23], v[124:127], v[2:5], 0
	s_waitcnt vmcnt(29)
	v_mfma_f32_16x16x32_bf16 v[20:23], v[128:131], v[6:9], v[20:23]
	s_nop 0
	s_waitcnt vmcnt(28)
	v_mfma_f32_16x16x32_bf16 v[20:23], v[132:135], v[10:13], v[20:23]
	s_nop 0
	v_add_co_u32_e32 v30, vcc, s0, v32
	s_waitcnt vmcnt(27)
	v_mfma_f32_16x16x32_bf16 v[20:23], v[136:139], v[14:17], v[20:23]
	s_nop 0
	v_addc_co_u32_e32 v31, vcc, 0, v33, vcc
	s_movk_i32 s0, 0x5000
	s_waitcnt vmcnt(26)
	s_nop 3
	v_pk_mul_f32 v[22:23], v[22:23], v[142:143]
	v_pk_mul_f32 v[20:21], v[20:21], v[140:141]
	s_nop 0
	v_cvt_pk_bf16_f32 v20, v20, v21
	v_cvt_pk_bf16_f32 v21, v22, v23
	global_store_dwordx2 v[18:19], v[20:21], off offset:1088
	s_nop 0
	s_nop 0
	s_nop 0
	s_waitcnt vmcnt(26)
	v_mfma_f32_16x16x32_bf16 v[20:23], v[144:147], v[2:5], 0
	s_waitcnt vmcnt(25)
	v_mfma_f32_16x16x32_bf16 v[20:23], v[148:151], v[6:9], v[20:23]
	s_nop 0
	s_waitcnt vmcnt(24)
	v_mfma_f32_16x16x32_bf16 v[20:23], v[152:155], v[10:13], v[20:23]
	s_nop 0
	v_add_co_u32_e32 v24, vcc, s0, v32
	s_waitcnt vmcnt(23)
	v_mfma_f32_16x16x32_bf16 v[20:23], v[156:159], v[14:17], v[20:23]
	s_nop 0
	v_addc_co_u32_e32 v25, vcc, 0, v33, vcc
	s_movk_i32 s0, 0x6000
	s_waitcnt vmcnt(22)
	s_nop 3
	v_pk_mul_f32 v[22:23], v[22:23], v[162:163]
	v_pk_mul_f32 v[20:21], v[20:21], v[160:161]
	s_nop 0
	v_cvt_pk_bf16_f32 v20, v20, v21
	v_cvt_pk_bf16_f32 v21, v22, v23
	global_store_dwordx2 v[18:19], v[20:21], off offset:1120
	s_nop 0
	s_nop 0
	s_nop 0
	s_waitcnt vmcnt(22)
	v_mfma_f32_16x16x32_bf16 v[20:23], v[164:167], v[2:5], 0
	s_waitcnt vmcnt(21)
	v_mfma_f32_16x16x32_bf16 v[20:23], v[168:171], v[6:9], v[20:23]
	s_nop 0
	s_waitcnt vmcnt(20)
	v_mfma_f32_16x16x32_bf16 v[20:23], v[172:175], v[10:13], v[20:23]
	s_nop 0
	v_add_co_u32_e32 v30, vcc, s0, v32
	s_waitcnt vmcnt(19)
	v_mfma_f32_16x16x32_bf16 v[20:23], v[176:179], v[14:17], v[20:23]
	s_nop 0
	v_addc_co_u32_e32 v31, vcc, 0, v33, vcc
	s_waitcnt vmcnt(18)
	s_nop 4
	v_pk_mul_f32 v[22:23], v[22:23], v[182:183]
	v_pk_mul_f32 v[20:21], v[20:21], v[180:181]
	s_nop 0
	v_cvt_pk_bf16_f32 v20, v20, v21
	v_cvt_pk_bf16_f32 v21, v22, v23
	global_store_dwordx2 v[18:19], v[20:21], off offset:1152
	s_nop 0
	s_nop 0
	s_nop 0
	s_waitcnt vmcnt(18)
	v_mfma_f32_16x16x32_bf16 v[20:23], v[184:187], v[2:5], 0
	s_waitcnt vmcnt(17)
	v_mfma_f32_16x16x32_bf16 v[20:23], v[188:191], v[6:9], v[20:23]
	s_nop 0
	s_waitcnt vmcnt(16)
	v_mfma_f32_16x16x32_bf16 v[20:23], v[192:195], v[10:13], v[20:23]
	s_nop 0
	s_waitcnt vmcnt(15)
	v_mfma_f32_16x16x32_bf16 v[20:23], v[196:199], v[14:17], v[20:23]
	s_nop 0
	s_waitcnt vmcnt(14)
	s_nop 5
	v_pk_mul_f32 v[22:23], v[22:23], v[202:203]
	v_pk_mul_f32 v[20:21], v[20:21], v[200:201]
	s_nop 0
	v_cvt_pk_bf16_f32 v20, v20, v21
	v_cvt_pk_bf16_f32 v21, v22, v23
	global_store_dwordx2 v[18:19], v[20:21], off offset:1184
	s_nop 0
	s_nop 0
	s_nop 0
	s_waitcnt vmcnt(14)
	v_mfma_f32_16x16x32_bf16 v[20:23], v[204:207], v[2:5], 0
	s_waitcnt vmcnt(13)
	v_mfma_f32_16x16x32_bf16 v[20:23], v[222:225], v[6:9], v[20:23]
	s_nop 0
	s_waitcnt vmcnt(12)
	v_mfma_f32_16x16x32_bf16 v[20:23], v[226:229], v[10:13], v[20:23]
	s_nop 0
	s_nop 0
	s_nop 0
	s_waitcnt vmcnt(11)
	v_mfma_f32_16x16x32_bf16 v[20:23], v[230:233], v[14:17], v[20:23]
	s_waitcnt vmcnt(10)
	s_nop 6
	v_pk_mul_f32 v[22:23], v[22:23], v[236:237]
	v_pk_mul_f32 v[20:21], v[20:21], v[234:235]
	s_nop 0
	v_cvt_pk_bf16_f32 v20, v20, v21
	v_cvt_pk_bf16_f32 v21, v22, v23
	v_add_co_u32_e32 v22, vcc, 0x7000, v32
	global_store_dwordx2 v[18:19], v[20:21], off offset:1216
	s_nop 0
	v_addc_co_u32_e32 v23, vcc, 0, v33, vcc
	s_nop 0
	s_waitcnt vmcnt(10)
	v_mfma_f32_16x16x32_bf16 v[2:5], v[238:241], v[2:5], 0
	s_nop 0
	s_waitcnt vmcnt(9)
	v_mfma_f32_16x16x32_bf16 v[2:5], v[242:245], v[6:9], v[2:5]
	s_nop 0
	s_waitcnt vmcnt(8)
	v_mfma_f32_16x16x32_bf16 v[2:5], v[246:249], v[10:13], v[2:5]
	s_nop 0
	s_waitcnt vmcnt(7)
	v_mfma_f32_16x16x32_bf16 v[2:5], v[52:55], v[14:17], v[2:5]
	s_branch .LBB0_579
